# K-loops: next segment's scalar setup and the loop counter update moved to the tail of the preceding load segment so every load segment opens with its ds_reads
# baseline (speedup 1.0000x reference)
; #define PG8_STAGE(bufoff, gbase, voff) do { _Pragma("unroll") for (int _i = 0; _i < 2; ++_i) \
;         __builtin_amdgcn_global_load_lds((const unsigned*)((const char*)(gbase) + (voff)[_i]), (PG8_LAS unsigned*)(lds + (bufoff) + ldsw + _i * 8192), 16, 0, 0); } while (0)
; #define PG8_LDA(dst, b, h) do { _Pragma("unroll") for (int m = 0; m < 4; ++m) _Pragma("unroll") for (int k = 0; k < 2; ++k) dst[m][k] = *(const PG8_LAS bf16x8*)(lds + PG8_SA(b, h) + aoff + m * 2048 + k * 1024); } while (0)
; #define PG8_LDB(dst, b, h) do { _Pragma("unroll") for (int n = 0; n < 2; ++n) _Pragma("unroll") for (int k = 0; k < 2; ++k) dst[n][k] = *(const PG8_LAS bf16x8*)(lds + PG8_SB(b, h) + boff + n * 2048 + k * 1024); } while (0)
; #define PG8_MMA(ai, bj, At, Bt) do { __builtin_amdgcn_s_setprio(1); _Pragma("unroll") for (int m = 0; m < 4; ++m) _Pragma("unroll") for (int n = 0; n < 2; ++n) _Pragma("unroll") for (int k = 0; k < 2; ++k) \
;         acc[ai][bj][m][n] = __builtin_amdgcn_mfma_f32_16x16x32_bf16(Bt[n][k], At[m][k], acc[ai][bj][m][n], 0, 0, 0); __builtin_amdgcn_s_setprio(0); } while (0)
; #define PG8_WAIT_V(n) asm volatile("s_waitcnt vmcnt(" #n ")" ::: "memory")
; #define PG8_WAIT_L(n) asm volatile("s_waitcnt lgkmcnt(" #n ")" ::: "memory")
; template <class Epi, class Sched, bool ALIGN_EPI = false, bool SP2 = false>
; __device__ __forceinline__ void gemm_phase(PG8_LAS unsigned char* lds, const Gemm g, const Sched& S, const Epi& E) {
;     ...
;             const bool last = (t == nt - 2);
;             const char* a1 = cA + (size_t)(t + 1) * kstep;
;             const char* a2 = last ? nA : cA + (size_t)(t + 2) * kstep; const char* b2 = last ? nB : cB + (size_t)(t + 2) * kstep;
;             const char* a3 = a2 + kstep; const char* b3 = b2 + kstep;
;             if (last && has_next) S.a_ready(nxt);
;             if constexpr (SP2) {
;             PG8_LDB(B0, 0, 0); PG8_LDB(B1, 0, 1); PG8_SCHED; PG8_LDA(At, 0, 0); PG8_STAGE(PG8_SA(1, 1), a1 + hstep, voffA);
;             PG8_WAIT_V(8); PG8_WAIT_L(0); PG8_BAR; PG8_MMA(0, 0, At, B0); PG8_MMA(0, 1, At, B1); PG8_BAR; PG8_SCHED;
;             PG8_LDA(At, 0, 1); PG8_STAGE(PG8_SB(0, 0), b2, voffB); PG8_STAGE(PG8_SB(0, 1), b2 + hstep, voffB); PG8_STAGE(PG8_SA(0, 0), a2, voffA);
;             PG8_WAIT_V(8); PG8_WAIT_L(0); PG8_BAR; PG8_MMA(1, 0, At, B0); PG8_MMA(1, 1, At, B1); PG8_BAR; PG8_SCHED;
.LBB0_67:
	ds_read_b128 v[128:131], v159
	ds_read_b128 v[152:155], v159 offset:1024
	ds_read_b128 v[162:165], v159 offset:2048
	ds_read_b128 v[166:169], v159 offset:3072
	ds_read_b128 v[170:173], v160
	ds_read_b128 v[174:177], v160 offset:1024
	ds_read_b128 v[178:181], v160 offset:2048
	ds_read_b128 v[182:185], v160 offset:3072
	s_add_i32 m0, s1, 0xc000
	ds_read_b128 v[186:189], v161
	ds_read_b128 v[190:193], v161 offset:1024
	ds_read_b128 v[194:197], v161 offset:2048
	ds_read_b128 v[200:203], v161 offset:3072
	ds_read_b128 v[204:207], v161 offset:4096
	ds_read_b128 v[208:211], v161 offset:5120
	ds_read_b128 v[212:215], v161 offset:6144
	ds_read_b128 v[216:219], v161 offset:7168
	global_load_lds_dwordx4 v144, s[74:75]
	s_add_i32 m0, s1, 0xe000
	s_nop 0
	global_load_lds_dwordx4 v146, s[74:75]
	s_add_u32 s76, s74, 0xfff80080
	s_addc_u32 s77, s75, -1
	s_cmp_eq_u32 s88, 28
	s_cselect_b32 s79, s5, s77
	s_cselect_b32 s78, s14, s76
	s_cselect_b32 s77, s24, s69
	s_cselect_b32 s76, s25, s67
	s_add_i32 s89, s85, s0
	s_mov_b32 m0, s89
	s_waitcnt vmcnt(8)
	s_waitcnt lgkmcnt(0)
	s_barrier
	s_setprio 1
	s_waitcnt lgkmcnt(0)
	v_mfma_f32_16x16x32_bf16 v[124:127], v[128:131], v[186:189], v[124:127]
	v_mfma_f32_16x16x32_bf16 v[120:123], v[162:165], v[186:189], v[120:123]
	v_mfma_f32_16x16x32_bf16 v[108:111], v[128:131], v[194:197], v[108:111]
	v_mfma_f32_16x16x32_bf16 v[104:107], v[162:165], v[194:197], v[104:107]
	v_mfma_f32_16x16x32_bf16 v[92:95], v[128:131], v[204:207], v[92:95]
	v_mfma_f32_16x16x32_bf16 v[88:91], v[162:165], v[204:207], v[88:91]
	v_mfma_f32_16x16x32_bf16 v[76:79], v[128:131], v[212:215], v[76:79]
	v_mfma_f32_16x16x32_bf16 v[72:75], v[162:165], v[212:215], v[72:75]
	v_mfma_f32_16x16x32_bf16 v[124:127], v[152:155], v[190:193], v[124:127]
	v_mfma_f32_16x16x32_bf16 v[120:123], v[166:169], v[190:193], v[120:123]
	v_mfma_f32_16x16x32_bf16 v[108:111], v[152:155], v[200:203], v[108:111]
	v_mfma_f32_16x16x32_bf16 v[104:107], v[166:169], v[200:203], v[104:107]
	v_mfma_f32_16x16x32_bf16 v[92:95], v[152:155], v[208:211], v[92:95]
	v_mfma_f32_16x16x32_bf16 v[88:91], v[166:169], v[208:211], v[88:91]
	v_mfma_f32_16x16x32_bf16 v[76:79], v[152:155], v[216:219], v[76:79]
	v_mfma_f32_16x16x32_bf16 v[72:75], v[166:169], v[216:219], v[72:75]
	s_setprio 0
	s_setprio 1
	v_mfma_f32_16x16x32_bf16 v[116:119], v[170:173], v[186:189], v[116:119]
	v_mfma_f32_16x16x32_bf16 v[112:115], v[178:181], v[186:189], v[112:115]
	v_mfma_f32_16x16x32_bf16 v[100:103], v[170:173], v[194:197], v[100:103]
	v_mfma_f32_16x16x32_bf16 v[96:99], v[178:181], v[194:197], v[96:99]
	v_mfma_f32_16x16x32_bf16 v[84:87], v[170:173], v[204:207], v[84:87]
	v_mfma_f32_16x16x32_bf16 v[80:83], v[178:181], v[204:207], v[80:83]
	v_mfma_f32_16x16x32_bf16 v[68:71], v[170:173], v[212:215], v[68:71]
	v_mfma_f32_16x16x32_bf16 v[64:67], v[178:181], v[212:215], v[64:67]
	v_mfma_f32_16x16x32_bf16 v[116:119], v[174:177], v[190:193], v[116:119]
	v_mfma_f32_16x16x32_bf16 v[112:115], v[182:185], v[190:193], v[112:115]
	v_mfma_f32_16x16x32_bf16 v[100:103], v[174:177], v[200:203], v[100:103]
	v_mfma_f32_16x16x32_bf16 v[96:99], v[182:185], v[200:203], v[96:99]
	v_mfma_f32_16x16x32_bf16 v[84:87], v[174:177], v[208:211], v[84:87]
	v_mfma_f32_16x16x32_bf16 v[80:83], v[182:185], v[208:211], v[80:83]
	v_mfma_f32_16x16x32_bf16 v[68:71], v[174:177], v[216:219], v[68:71]
	v_mfma_f32_16x16x32_bf16 v[64:67], v[182:185], v[216:219], v[64:67]
	s_setprio 0
	s_barrier
	ds_read_b128 v[186:189], v161 offset:16384
	ds_read_b128 v[190:193], v161 offset:17408
	ds_read_b128 v[194:197], v161 offset:18432
	ds_read_b128 v[200:203], v161 offset:19456
	ds_read_b128 v[204:207], v161 offset:20480
	ds_read_b128 v[208:211], v161 offset:21504
	ds_read_b128 v[212:215], v161 offset:22528
	ds_read_b128 v[216:219], v161 offset:23552
	global_load_lds_dwordx4 v134, s[76:77]
	s_add_i32 m0, s89, 0x2000
	s_add_u32 s96, s76, 0x80000
	s_addc_u32 s97, s77, 0
	s_add_i32 s89, s86, s0
	global_load_lds_dwordx4 v138, s[76:77]
	s_mov_b32 m0, s89
	s_nop 0
	global_load_lds_dwordx4 v134, s[96:97]
	s_add_i32 m0, s89, 0x2000
	s_nop 0
	global_load_lds_dwordx4 v138, s[96:97]
	s_mov_b32 m0, s1
	s_nop 0
	global_load_lds_dwordx4 v132, s[78:79]
	s_mov_b32 m0, s11
	s_nop 0
	global_load_lds_dwordx4 v136, s[78:79]
	s_waitcnt vmcnt(8)
	s_waitcnt lgkmcnt(0)
	s_barrier
	s_setprio 1
	s_waitcnt lgkmcnt(0)
	v_mfma_f32_16x16x32_bf16 v[60:63], v[128:131], v[186:189], v[60:63]
	v_mfma_f32_16x16x32_bf16 v[56:59], v[162:165], v[186:189], v[56:59]
	v_mfma_f32_16x16x32_bf16 v[44:47], v[128:131], v[194:197], v[44:47]
	v_mfma_f32_16x16x32_bf16 v[40:43], v[162:165], v[194:197], v[40:43]
	v_mfma_f32_16x16x32_bf16 v[28:31], v[128:131], v[204:207], v[28:31]
	v_mfma_f32_16x16x32_bf16 v[24:27], v[162:165], v[204:207], v[24:27]
	v_mfma_f32_16x16x32_bf16 v[12:15], v[128:131], v[212:215], v[12:15]
	v_mfma_f32_16x16x32_bf16 v[8:11], v[162:165], v[212:215], v[8:11]
	v_mfma_f32_16x16x32_bf16 v[60:63], v[152:155], v[190:193], v[60:63]
	v_mfma_f32_16x16x32_bf16 v[56:59], v[166:169], v[190:193], v[56:59]
	v_mfma_f32_16x16x32_bf16 v[44:47], v[152:155], v[200:203], v[44:47]
	v_mfma_f32_16x16x32_bf16 v[40:43], v[166:169], v[200:203], v[40:43]
	v_mfma_f32_16x16x32_bf16 v[28:31], v[152:155], v[208:211], v[28:31]
	v_mfma_f32_16x16x32_bf16 v[24:27], v[166:169], v[208:211], v[24:27]
	v_mfma_f32_16x16x32_bf16 v[12:15], v[152:155], v[216:219], v[12:15]
	v_mfma_f32_16x16x32_bf16 v[8:11], v[166:169], v[216:219], v[8:11]
	s_setprio 0
	s_setprio 1
	v_mfma_f32_16x16x32_bf16 v[52:55], v[170:173], v[186:189], v[52:55]
	v_mfma_f32_16x16x32_bf16 v[48:51], v[178:181], v[186:189], v[48:51]
	v_mfma_f32_16x16x32_bf16 v[36:39], v[170:173], v[194:197], v[36:39]
	v_mfma_f32_16x16x32_bf16 v[32:35], v[178:181], v[194:197], v[32:35]
	v_mfma_f32_16x16x32_bf16 v[20:23], v[170:173], v[204:207], v[20:23]
	v_mfma_f32_16x16x32_bf16 v[16:19], v[178:181], v[204:207], v[16:19]
	v_mfma_f32_16x16x32_bf16 v[4:7], v[170:173], v[212:215], v[4:7]
	v_mfma_f32_16x16x32_bf16 v[0:3], v[178:181], v[212:215], v[0:3]
	v_mfma_f32_16x16x32_bf16 v[52:55], v[174:177], v[190:193], v[52:55]
	v_mfma_f32_16x16x32_bf16 v[48:51], v[182:185], v[190:193], v[48:51]
	v_mfma_f32_16x16x32_bf16 v[36:39], v[174:177], v[200:203], v[36:39]
	v_mfma_f32_16x16x32_bf16 v[32:35], v[182:185], v[200:203], v[32:35]
	v_mfma_f32_16x16x32_bf16 v[20:23], v[174:177], v[208:211], v[20:23]
	v_mfma_f32_16x16x32_bf16 v[16:19], v[182:185], v[208:211], v[16:19]
	v_mfma_f32_16x16x32_bf16 v[4:7], v[174:177], v[216:219], v[4:7]
	v_mfma_f32_16x16x32_bf16 v[0:3], v[182:185], v[216:219], v[0:3]
	s_setprio 0
	s_barrier
; #define PG8_STAGE(bufoff, gbase, voff) do { _Pragma("unroll") for (int _i = 0; _i < 2; ++_i) \
;         __builtin_amdgcn_global_load_lds((const unsigned*)((const char*)(gbase) + (voff)[_i]), (PG8_LAS unsigned*)(lds + (bufoff) + ldsw + _i * 8192), 16, 0, 0); } while (0)
; #define PG8_LDA(dst, b, h) do { _Pragma("unroll") for (int m = 0; m < 4; ++m) _Pragma("unroll") for (int k = 0; k < 2; ++k) dst[m][k] = *(const PG8_LAS bf16x8*)(lds + PG8_SA(b, h) + aoff + m * 2048 + k * 1024); } while (0)
; #define PG8_LDB(dst, b, h) do { _Pragma("unroll") for (int n = 0; n < 2; ++n) _Pragma("unroll") for (int k = 0; k < 2; ++k) dst[n][k] = *(const PG8_LAS bf16x8*)(lds + PG8_SB(b, h) + boff + n * 2048 + k * 1024); } while (0)
; #define PG8_MMA(ai, bj, At, Bt) do { __builtin_amdgcn_s_setprio(1); _Pragma("unroll") for (int m = 0; m < 4; ++m) _Pragma("unroll") for (int n = 0; n < 2; ++n) _Pragma("unroll") for (int k = 0; k < 2; ++k) \
;         acc[ai][bj][m][n] = __builtin_amdgcn_mfma_f32_16x16x32_bf16(Bt[n][k], At[m][k], acc[ai][bj][m][n], 0, 0, 0); __builtin_amdgcn_s_setprio(0); } while (0)
; #define PG8_WAIT_V(n) asm volatile("s_waitcnt vmcnt(" #n ")" ::: "memory")
; #define PG8_WAIT_L(n) asm volatile("s_waitcnt lgkmcnt(" #n ")" ::: "memory")
; #define PG8_BAR __builtin_amdgcn_s_barrier()
; #define PG8_SCHED __builtin_amdgcn_sched_barrier(0)
; template <class Epi, class Sched, bool ALIGN_EPI = false, bool SP2 = false>
; __device__ __forceinline__ void gemm_phase(PG8_LAS unsigned char* lds, const Gemm g, const Sched& S, const Epi& E) {
;     ...
;         for (int t = 0; t < nt; t += 2) {
;     ...
;             PG8_LDB(B0, 1, 0); PG8_LDB(B1, 1, 1); PG8_SCHED; PG8_LDA(At, 1, 0); PG8_STAGE(PG8_SA(0, 1), a2 + hstep, voffA);
;             PG8_WAIT_V(8); PG8_WAIT_L(0); PG8_BAR; PG8_MMA(0, 0, At, B0); PG8_MMA(0, 1, At, B1); PG8_BAR; PG8_SCHED;
;             PG8_LDA(At, 1, 1); PG8_STAGE(PG8_SB(1, 0), b3, voffB); PG8_STAGE(PG8_SB(1, 1), b3 + hstep, voffB); PG8_STAGE(PG8_SA(1, 0), a3, voffA);
;             PG8_WAIT_V(8); PG8_WAIT_L(0); PG8_BAR; PG8_MMA(1, 0, At, B0); PG8_MMA(1, 1, At, B1); PG8_BAR; PG8_SCHED;
	ds_read_b128 v[128:131], v198
	ds_read_b128 v[152:155], v198 offset:1024
	ds_read_b128 v[162:165], v198 offset:2048
	ds_read_b128 v[166:169], v198 offset:3072
	ds_read_b128 v[170:173], v199
	ds_read_b128 v[174:177], v199 offset:1024
	ds_read_b128 v[178:181], v199 offset:2048
	ds_read_b128 v[182:185], v199 offset:3072
	ds_read_b128 v[186:189], v161 offset:32768
	ds_read_b128 v[190:193], v161 offset:33792
	ds_read_b128 v[194:197], v161 offset:34816
	ds_read_b128 v[200:203], v161 offset:35840
	ds_read_b128 v[204:207], v161 offset:36864
	ds_read_b128 v[208:211], v161 offset:37888
	ds_read_b128 v[212:215], v161 offset:38912
	ds_read_b128 v[216:219], v161 offset:39936
	s_add_u32 s98, s78, 0x80000
	s_addc_u32 s99, s79, 0
	s_mov_b32 m0, s33
	s_add_u32 s100, s78, 0x80
	s_addc_u32 s101, s79, 0
	global_load_lds_dwordx4 v132, s[98:99]
	s_mov_b32 m0, s35
	s_nop 0
	global_load_lds_dwordx4 v136, s[98:99]
	s_add_i32 s89, 0, 0x18000
	s_add_i32 s94, 0, 0x1c000
	s_add_u32 s98, s76, 0x80
	s_addc_u32 s99, s77, 0
	s_add_i32 s78, s89, s0
	s_mov_b32 m0, s78
	s_waitcnt vmcnt(8)
	s_waitcnt lgkmcnt(0)
	s_barrier
	s_setprio 1
	s_waitcnt lgkmcnt(0)
	v_mfma_f32_16x16x32_bf16 v[124:127], v[128:131], v[186:189], v[124:127]
	v_mfma_f32_16x16x32_bf16 v[120:123], v[162:165], v[186:189], v[120:123]
	v_mfma_f32_16x16x32_bf16 v[108:111], v[128:131], v[194:197], v[108:111]
	v_mfma_f32_16x16x32_bf16 v[104:107], v[162:165], v[194:197], v[104:107]
	v_mfma_f32_16x16x32_bf16 v[92:95], v[128:131], v[204:207], v[92:95]
	v_mfma_f32_16x16x32_bf16 v[88:91], v[162:165], v[204:207], v[88:91]
	v_mfma_f32_16x16x32_bf16 v[76:79], v[128:131], v[212:215], v[76:79]
	v_mfma_f32_16x16x32_bf16 v[72:75], v[162:165], v[212:215], v[72:75]
	v_mfma_f32_16x16x32_bf16 v[124:127], v[152:155], v[190:193], v[124:127]
	v_mfma_f32_16x16x32_bf16 v[120:123], v[166:169], v[190:193], v[120:123]
	v_mfma_f32_16x16x32_bf16 v[108:111], v[152:155], v[200:203], v[108:111]
	v_mfma_f32_16x16x32_bf16 v[104:107], v[166:169], v[200:203], v[104:107]
	v_mfma_f32_16x16x32_bf16 v[92:95], v[152:155], v[208:211], v[92:95]
	v_mfma_f32_16x16x32_bf16 v[88:91], v[166:169], v[208:211], v[88:91]
	v_mfma_f32_16x16x32_bf16 v[76:79], v[152:155], v[216:219], v[76:79]
	v_mfma_f32_16x16x32_bf16 v[72:75], v[166:169], v[216:219], v[72:75]
	s_setprio 0
	s_setprio 1
	v_mfma_f32_16x16x32_bf16 v[116:119], v[170:173], v[186:189], v[116:119]
	v_mfma_f32_16x16x32_bf16 v[112:115], v[178:181], v[186:189], v[112:115]
	v_mfma_f32_16x16x32_bf16 v[100:103], v[170:173], v[194:197], v[100:103]
	v_mfma_f32_16x16x32_bf16 v[96:99], v[178:181], v[194:197], v[96:99]
	v_mfma_f32_16x16x32_bf16 v[84:87], v[170:173], v[204:207], v[84:87]
	v_mfma_f32_16x16x32_bf16 v[80:83], v[178:181], v[204:207], v[80:83]
	v_mfma_f32_16x16x32_bf16 v[68:71], v[170:173], v[212:215], v[68:71]
	v_mfma_f32_16x16x32_bf16 v[64:67], v[178:181], v[212:215], v[64:67]
	v_mfma_f32_16x16x32_bf16 v[116:119], v[174:177], v[190:193], v[116:119]
	v_mfma_f32_16x16x32_bf16 v[112:115], v[182:185], v[190:193], v[112:115]
	v_mfma_f32_16x16x32_bf16 v[100:103], v[174:177], v[200:203], v[100:103]
	v_mfma_f32_16x16x32_bf16 v[96:99], v[182:185], v[200:203], v[96:99]
	v_mfma_f32_16x16x32_bf16 v[84:87], v[174:177], v[208:211], v[84:87]
	v_mfma_f32_16x16x32_bf16 v[80:83], v[182:185], v[208:211], v[80:83]
	v_mfma_f32_16x16x32_bf16 v[68:71], v[174:177], v[216:219], v[68:71]
	v_mfma_f32_16x16x32_bf16 v[64:67], v[182:185], v[216:219], v[64:67]
	s_setprio 0
	s_barrier
	ds_read_b128 v[186:189], v161 offset:49152
	ds_read_b128 v[190:193], v161 offset:50176
	ds_read_b128 v[194:197], v161 offset:51200
	ds_read_b128 v[200:203], v161 offset:52224
	ds_read_b128 v[204:207], v161 offset:53248
	ds_read_b128 v[208:211], v161 offset:54272
	ds_read_b128 v[212:215], v161 offset:55296
	ds_read_b128 v[216:219], v161 offset:56320
	global_load_lds_dwordx4 v134, s[98:99]
	s_add_i32 m0, s78, 0x2000
	s_add_u32 s76, s76, 0x80080
	s_addc_u32 s77, s77, 0
	s_add_i32 s78, s94, s0
	global_load_lds_dwordx4 v138, s[98:99]
	s_mov_b32 m0, s78
	s_nop 0
	global_load_lds_dwordx4 v134, s[76:77]
	s_add_i32 m0, s78, 0x2000
	s_nop 0
	global_load_lds_dwordx4 v138, s[76:77]
	s_mov_b32 m0, s80
	s_nop 0
	global_load_lds_dwordx4 v132, s[100:101]
	s_mov_b32 m0, s81
	s_nop 0
	global_load_lds_dwordx4 v136, s[100:101]
	s_add_i32 s88, s88, 2
	s_add_u32 s74, s74, 0x100
	s_addc_u32 s75, s75, 0
	s_add_u32 s67, s67, 0x100
	s_addc_u32 s69, s69, 0
	s_cmp_gt_u32 s88, 29
	s_waitcnt vmcnt(8)
	s_waitcnt lgkmcnt(0)
	s_barrier
	s_setprio 1
	s_waitcnt lgkmcnt(0)
	v_mfma_f32_16x16x32_bf16 v[60:63], v[128:131], v[186:189], v[60:63]
	v_mfma_f32_16x16x32_bf16 v[56:59], v[162:165], v[186:189], v[56:59]
	v_mfma_f32_16x16x32_bf16 v[44:47], v[128:131], v[194:197], v[44:47]
	v_mfma_f32_16x16x32_bf16 v[40:43], v[162:165], v[194:197], v[40:43]
	v_mfma_f32_16x16x32_bf16 v[28:31], v[128:131], v[204:207], v[28:31]
	v_mfma_f32_16x16x32_bf16 v[24:27], v[162:165], v[204:207], v[24:27]
	v_mfma_f32_16x16x32_bf16 v[12:15], v[128:131], v[212:215], v[12:15]
	v_mfma_f32_16x16x32_bf16 v[8:11], v[162:165], v[212:215], v[8:11]
	v_mfma_f32_16x16x32_bf16 v[60:63], v[152:155], v[190:193], v[60:63]
	v_mfma_f32_16x16x32_bf16 v[56:59], v[166:169], v[190:193], v[56:59]
	v_mfma_f32_16x16x32_bf16 v[44:47], v[152:155], v[200:203], v[44:47]
	v_mfma_f32_16x16x32_bf16 v[40:43], v[166:169], v[200:203], v[40:43]
	v_mfma_f32_16x16x32_bf16 v[28:31], v[152:155], v[208:211], v[28:31]
	v_mfma_f32_16x16x32_bf16 v[24:27], v[166:169], v[208:211], v[24:27]
	v_mfma_f32_16x16x32_bf16 v[12:15], v[152:155], v[216:219], v[12:15]
	v_mfma_f32_16x16x32_bf16 v[8:11], v[166:169], v[216:219], v[8:11]
	s_setprio 0
	s_setprio 1
	v_mfma_f32_16x16x32_bf16 v[52:55], v[170:173], v[186:189], v[52:55]
	v_mfma_f32_16x16x32_bf16 v[48:51], v[178:181], v[186:189], v[48:51]
	v_mfma_f32_16x16x32_bf16 v[36:39], v[170:173], v[194:197], v[36:39]
	v_mfma_f32_16x16x32_bf16 v[32:35], v[178:181], v[194:197], v[32:35]
	v_mfma_f32_16x16x32_bf16 v[20:23], v[170:173], v[204:207], v[20:23]
	v_mfma_f32_16x16x32_bf16 v[16:19], v[178:181], v[204:207], v[16:19]
	v_mfma_f32_16x16x32_bf16 v[4:7], v[170:173], v[212:215], v[4:7]
	v_mfma_f32_16x16x32_bf16 v[0:3], v[178:181], v[212:215], v[0:3]
	v_mfma_f32_16x16x32_bf16 v[52:55], v[174:177], v[190:193], v[52:55]
	v_mfma_f32_16x16x32_bf16 v[48:51], v[182:185], v[190:193], v[48:51]
	v_mfma_f32_16x16x32_bf16 v[36:39], v[174:177], v[200:203], v[36:39]
	v_mfma_f32_16x16x32_bf16 v[32:35], v[182:185], v[200:203], v[32:35]
	v_mfma_f32_16x16x32_bf16 v[20:23], v[174:177], v[208:211], v[20:23]
	v_mfma_f32_16x16x32_bf16 v[16:19], v[182:185], v[208:211], v[16:19]
	v_mfma_f32_16x16x32_bf16 v[4:7], v[174:177], v[216:219], v[4:7]
	v_mfma_f32_16x16x32_bf16 v[0:3], v[182:185], v[216:219], v[0:3]
	s_setprio 0
	s_barrier
	s_cbranch_scc0 .LBB0_67
	s_and_b64 vcc, exec, s[60:61]
	s_cbranch_vccz .LBB0_70
	s_barrier

; #define PG8_STAGE(bufoff, gbase, voff) do { _Pragma("unroll") for (int _i = 0; _i < 2; ++_i) \
;         __builtin_amdgcn_global_load_lds((const unsigned*)((const char*)(gbase) + (voff)[_i]), (PG8_LAS unsigned*)(lds + (bufoff) + ldsw + _i * 8192), 16, 0, 0); } while (0)
; #define PG8_LDA(dst, b, h) do { _Pragma("unroll") for (int m = 0; m < 4; ++m) _Pragma("unroll") for (int k = 0; k < 2; ++k) dst[m][k] = *(const PG8_LAS bf16x8*)(lds + PG8_SA(b, h) + aoff + m * 2048 + k * 1024); } while (0)
; #define PG8_LDB(dst, b, h) do { _Pragma("unroll") for (int n = 0; n < 2; ++n) _Pragma("unroll") for (int k = 0; k < 2; ++k) dst[n][k] = *(const PG8_LAS bf16x8*)(lds + PG8_SB(b, h) + boff + n * 2048 + k * 1024); } while (0)
; #define PG8_MMA(ai, bj, At, Bt) do { __builtin_amdgcn_s_setprio(1); _Pragma("unroll") for (int m = 0; m < 4; ++m) _Pragma("unroll") for (int n = 0; n < 2; ++n) _Pragma("unroll") for (int k = 0; k < 2; ++k) \
;         acc[ai][bj][m][n] = __builtin_amdgcn_mfma_f32_16x16x32_bf16(Bt[n][k], At[m][k], acc[ai][bj][m][n], 0, 0, 0); __builtin_amdgcn_s_setprio(0); } while (0)
; #define PG8_WAIT_V(n) asm volatile("s_waitcnt vmcnt(" #n ")" ::: "memory")
; #define PG8_WAIT_L(n) asm volatile("s_waitcnt lgkmcnt(" #n ")" ::: "memory")
; template <class Epi, class Sched, bool ALIGN_EPI = false, bool SP2 = false>
; __device__ __forceinline__ void gemm_phase(PG8_LAS unsigned char* lds, const Gemm g, const Sched& S, const Epi& E) {
;     ...
;             const bool last = (t == nt - 2);
;             const char* a1 = cA + (size_t)(t + 1) * kstep;
;             const char* a2 = last ? nA : cA + (size_t)(t + 2) * kstep; const char* b2 = last ? nB : cB + (size_t)(t + 2) * kstep;
;             const char* a3 = a2 + kstep; const char* b3 = b2 + kstep;
;             if (last && has_next) S.a_ready(nxt);
;             if constexpr (SP2) {
;             PG8_LDB(B0, 0, 0); PG8_LDB(B1, 0, 1); PG8_SCHED; PG8_LDA(At, 0, 0); PG8_STAGE(PG8_SA(1, 1), a1 + hstep, voffA);
;             PG8_WAIT_V(8); PG8_WAIT_L(0); PG8_BAR; PG8_MMA(0, 0, At, B0); PG8_MMA(0, 1, At, B1); PG8_BAR; PG8_SCHED;
;             PG8_LDA(At, 0, 1); PG8_STAGE(PG8_SB(0, 0), b2, voffB); PG8_STAGE(PG8_SB(0, 1), b2 + hstep, voffB); PG8_STAGE(PG8_SA(0, 0), a2, voffA);
;             PG8_WAIT_V(8); PG8_WAIT_L(0); PG8_BAR; PG8_MMA(1, 0, At, B0); PG8_MMA(1, 1, At, B1); PG8_BAR; PG8_SCHED;
.LBB0_245:
	ds_read_b128 v[144:147], v153
	ds_read_b128 v[156:159], v153 offset:1024
	ds_read_b128 v[160:163], v153 offset:2048
	ds_read_b128 v[164:167], v153 offset:3072
	ds_read_b128 v[168:171], v154
	ds_read_b128 v[172:175], v154 offset:1024
	ds_read_b128 v[176:179], v154 offset:2048
	ds_read_b128 v[180:183], v154 offset:3072
	s_add_i32 m0, s33, 0xc000
	ds_read_b128 v[184:187], v155
	ds_read_b128 v[188:191], v155 offset:1024
	ds_read_b128 v[192:195], v155 offset:2048
	ds_read_b128 v[200:203], v155 offset:3072
	ds_read_b128 v[204:207], v155 offset:4096
	ds_read_b128 v[208:211], v155 offset:5120
	ds_read_b128 v[212:215], v155 offset:6144
	ds_read_b128 v[216:219], v155 offset:7168
	global_load_lds_dwordx4 v136, s[70:71]
	s_add_i32 m0, s33, 0xe000
	s_nop 0
	global_load_lds_dwordx4 v138, s[70:71]
	s_add_u32 s72, s70, 0xfff80080
	s_addc_u32 s73, s71, -1
	s_cmp_eq_u32 s87, 28
	s_cselect_b32 s75, s25, s73
	s_cselect_b32 s74, s63, s72
	s_cselect_b32 s73, s61, s86
	s_cselect_b32 s72, s84, s85
	s_add_i32 s88, s82, s1
	s_mov_b32 m0, s88
	s_waitcnt vmcnt(8)
	s_waitcnt lgkmcnt(0)
	s_barrier
	s_setprio 1
	s_waitcnt lgkmcnt(0)
	v_mfma_f32_16x16x32_bf16 v[124:127], v[144:147], v[184:187], v[124:127]
	v_mfma_f32_16x16x32_bf16 v[120:123], v[160:163], v[184:187], v[120:123]
	v_mfma_f32_16x16x32_bf16 v[108:111], v[144:147], v[192:195], v[108:111]
	v_mfma_f32_16x16x32_bf16 v[104:107], v[160:163], v[192:195], v[104:107]
	v_mfma_f32_16x16x32_bf16 v[92:95], v[144:147], v[204:207], v[92:95]
	v_mfma_f32_16x16x32_bf16 v[88:91], v[160:163], v[204:207], v[88:91]
	v_mfma_f32_16x16x32_bf16 v[76:79], v[144:147], v[212:215], v[76:79]
	v_mfma_f32_16x16x32_bf16 v[72:75], v[160:163], v[212:215], v[72:75]
	v_mfma_f32_16x16x32_bf16 v[124:127], v[156:159], v[188:191], v[124:127]
	v_mfma_f32_16x16x32_bf16 v[120:123], v[164:167], v[188:191], v[120:123]
	v_mfma_f32_16x16x32_bf16 v[108:111], v[156:159], v[200:203], v[108:111]
	v_mfma_f32_16x16x32_bf16 v[104:107], v[164:167], v[200:203], v[104:107]
	v_mfma_f32_16x16x32_bf16 v[92:95], v[156:159], v[208:211], v[92:95]
	v_mfma_f32_16x16x32_bf16 v[88:91], v[164:167], v[208:211], v[88:91]
	v_mfma_f32_16x16x32_bf16 v[76:79], v[156:159], v[216:219], v[76:79]
	v_mfma_f32_16x16x32_bf16 v[72:75], v[164:167], v[216:219], v[72:75]
	s_setprio 0
	s_setprio 1
	v_mfma_f32_16x16x32_bf16 v[116:119], v[168:171], v[184:187], v[116:119]
	v_mfma_f32_16x16x32_bf16 v[112:115], v[176:179], v[184:187], v[112:115]
	v_mfma_f32_16x16x32_bf16 v[100:103], v[168:171], v[192:195], v[100:103]
	v_mfma_f32_16x16x32_bf16 v[96:99], v[176:179], v[192:195], v[96:99]
	v_mfma_f32_16x16x32_bf16 v[84:87], v[168:171], v[204:207], v[84:87]
	v_mfma_f32_16x16x32_bf16 v[80:83], v[176:179], v[204:207], v[80:83]
	v_mfma_f32_16x16x32_bf16 v[68:71], v[168:171], v[212:215], v[68:71]
	v_mfma_f32_16x16x32_bf16 v[64:67], v[176:179], v[212:215], v[64:67]
	v_mfma_f32_16x16x32_bf16 v[116:119], v[172:175], v[188:191], v[116:119]
	v_mfma_f32_16x16x32_bf16 v[112:115], v[180:183], v[188:191], v[112:115]
	v_mfma_f32_16x16x32_bf16 v[100:103], v[172:175], v[200:203], v[100:103]
	v_mfma_f32_16x16x32_bf16 v[96:99], v[180:183], v[200:203], v[96:99]
	v_mfma_f32_16x16x32_bf16 v[84:87], v[172:175], v[208:211], v[84:87]
	v_mfma_f32_16x16x32_bf16 v[80:83], v[180:183], v[208:211], v[80:83]
	v_mfma_f32_16x16x32_bf16 v[68:71], v[172:175], v[216:219], v[68:71]
	v_mfma_f32_16x16x32_bf16 v[64:67], v[180:183], v[216:219], v[64:67]
	s_setprio 0
	s_barrier
	ds_read_b128 v[184:187], v155 offset:16384
	ds_read_b128 v[188:191], v155 offset:17408
	ds_read_b128 v[192:195], v155 offset:18432
	ds_read_b128 v[200:203], v155 offset:19456
	ds_read_b128 v[204:207], v155 offset:20480
	ds_read_b128 v[208:211], v155 offset:21504
	ds_read_b128 v[212:215], v155 offset:22528
	ds_read_b128 v[216:219], v155 offset:23552
	global_load_lds_dwordx4 v130, s[72:73]
	s_add_i32 m0, s88, 0x2000
	s_add_u32 s88, s72, 0x80000
	s_addc_u32 s89, s73, 0
	s_add_i32 s94, s83, s1
	global_load_lds_dwordx4 v134, s[72:73]
	s_mov_b32 m0, s94
	s_nop 0
	global_load_lds_dwordx4 v130, s[88:89]
	s_add_i32 m0, s94, 0x2000
	s_nop 0
	global_load_lds_dwordx4 v134, s[88:89]
	s_mov_b32 m0, s33
	s_nop 0
	global_load_lds_dwordx4 v128, s[74:75]
	s_mov_b32 m0, s35
	s_nop 0
	global_load_lds_dwordx4 v132, s[74:75]
	s_waitcnt vmcnt(8)
	s_waitcnt lgkmcnt(0)
	s_barrier
	s_setprio 1
	s_waitcnt lgkmcnt(0)
	v_mfma_f32_16x16x32_bf16 v[60:63], v[144:147], v[184:187], v[60:63]
	v_mfma_f32_16x16x32_bf16 v[56:59], v[160:163], v[184:187], v[56:59]
	v_mfma_f32_16x16x32_bf16 v[44:47], v[144:147], v[192:195], v[44:47]
	v_mfma_f32_16x16x32_bf16 v[40:43], v[160:163], v[192:195], v[40:43]
	v_mfma_f32_16x16x32_bf16 v[28:31], v[144:147], v[204:207], v[28:31]
	v_mfma_f32_16x16x32_bf16 v[24:27], v[160:163], v[204:207], v[24:27]
	v_mfma_f32_16x16x32_bf16 v[12:15], v[144:147], v[212:215], v[12:15]
	v_mfma_f32_16x16x32_bf16 v[8:11], v[160:163], v[212:215], v[8:11]
	v_mfma_f32_16x16x32_bf16 v[60:63], v[156:159], v[188:191], v[60:63]
	v_mfma_f32_16x16x32_bf16 v[56:59], v[164:167], v[188:191], v[56:59]
	v_mfma_f32_16x16x32_bf16 v[44:47], v[156:159], v[200:203], v[44:47]
	v_mfma_f32_16x16x32_bf16 v[40:43], v[164:167], v[200:203], v[40:43]
	v_mfma_f32_16x16x32_bf16 v[28:31], v[156:159], v[208:211], v[28:31]
	v_mfma_f32_16x16x32_bf16 v[24:27], v[164:167], v[208:211], v[24:27]
	v_mfma_f32_16x16x32_bf16 v[12:15], v[156:159], v[216:219], v[12:15]
	v_mfma_f32_16x16x32_bf16 v[8:11], v[164:167], v[216:219], v[8:11]
	s_setprio 0
	s_setprio 1
	v_mfma_f32_16x16x32_bf16 v[52:55], v[168:171], v[184:187], v[52:55]
	v_mfma_f32_16x16x32_bf16 v[48:51], v[176:179], v[184:187], v[48:51]
	v_mfma_f32_16x16x32_bf16 v[36:39], v[168:171], v[192:195], v[36:39]
	v_mfma_f32_16x16x32_bf16 v[32:35], v[176:179], v[192:195], v[32:35]
	v_mfma_f32_16x16x32_bf16 v[20:23], v[168:171], v[204:207], v[20:23]
	v_mfma_f32_16x16x32_bf16 v[16:19], v[176:179], v[204:207], v[16:19]
	v_mfma_f32_16x16x32_bf16 v[4:7], v[168:171], v[212:215], v[4:7]
	v_mfma_f32_16x16x32_bf16 v[0:3], v[176:179], v[212:215], v[0:3]
	v_mfma_f32_16x16x32_bf16 v[52:55], v[172:175], v[188:191], v[52:55]
	v_mfma_f32_16x16x32_bf16 v[48:51], v[180:183], v[188:191], v[48:51]
	v_mfma_f32_16x16x32_bf16 v[36:39], v[172:175], v[200:203], v[36:39]
	v_mfma_f32_16x16x32_bf16 v[32:35], v[180:183], v[200:203], v[32:35]
	v_mfma_f32_16x16x32_bf16 v[20:23], v[172:175], v[208:211], v[20:23]
	v_mfma_f32_16x16x32_bf16 v[16:19], v[180:183], v[208:211], v[16:19]
	v_mfma_f32_16x16x32_bf16 v[4:7], v[172:175], v[216:219], v[4:7]
	v_mfma_f32_16x16x32_bf16 v[0:3], v[180:183], v[216:219], v[0:3]
	s_setprio 0
	s_barrier
; #define PG8_STAGE(bufoff, gbase, voff) do { _Pragma("unroll") for (int _i = 0; _i < 2; ++_i) \
;         __builtin_amdgcn_global_load_lds((const unsigned*)((const char*)(gbase) + (voff)[_i]), (PG8_LAS unsigned*)(lds + (bufoff) + ldsw + _i * 8192), 16, 0, 0); } while (0)
; #define PG8_LDA(dst, b, h) do { _Pragma("unroll") for (int m = 0; m < 4; ++m) _Pragma("unroll") for (int k = 0; k < 2; ++k) dst[m][k] = *(const PG8_LAS bf16x8*)(lds + PG8_SA(b, h) + aoff + m * 2048 + k * 1024); } while (0)
; #define PG8_LDB(dst, b, h) do { _Pragma("unroll") for (int n = 0; n < 2; ++n) _Pragma("unroll") for (int k = 0; k < 2; ++k) dst[n][k] = *(const PG8_LAS bf16x8*)(lds + PG8_SB(b, h) + boff + n * 2048 + k * 1024); } while (0)
; #define PG8_MMA(ai, bj, At, Bt) do { __builtin_amdgcn_s_setprio(1); _Pragma("unroll") for (int m = 0; m < 4; ++m) _Pragma("unroll") for (int n = 0; n < 2; ++n) _Pragma("unroll") for (int k = 0; k < 2; ++k) \
;         acc[ai][bj][m][n] = __builtin_amdgcn_mfma_f32_16x16x32_bf16(Bt[n][k], At[m][k], acc[ai][bj][m][n], 0, 0, 0); __builtin_amdgcn_s_setprio(0); } while (0)
; #define PG8_WAIT_V(n) asm volatile("s_waitcnt vmcnt(" #n ")" ::: "memory")
; #define PG8_WAIT_L(n) asm volatile("s_waitcnt lgkmcnt(" #n ")" ::: "memory")
; #define PG8_BAR __builtin_amdgcn_s_barrier()
; #define PG8_SCHED __builtin_amdgcn_sched_barrier(0)
; template <class Epi, class Sched, bool ALIGN_EPI = false, bool SP2 = false>
; __device__ __forceinline__ void gemm_phase(PG8_LAS unsigned char* lds, const Gemm g, const Sched& S, const Epi& E) {
;     ...
;         for (int t = 0; t < nt; t += 2) {
;     ...
;             PG8_LDB(B0, 1, 0); PG8_LDB(B1, 1, 1); PG8_SCHED; PG8_LDA(At, 1, 0); PG8_STAGE(PG8_SA(0, 1), a2 + hstep, voffA);
;             PG8_WAIT_V(8); PG8_WAIT_L(0); PG8_BAR; PG8_MMA(0, 0, At, B0); PG8_MMA(0, 1, At, B1); PG8_BAR; PG8_SCHED;
;             PG8_LDA(At, 1, 1); PG8_STAGE(PG8_SB(1, 0), b3, voffB); PG8_STAGE(PG8_SB(1, 1), b3 + hstep, voffB); PG8_STAGE(PG8_SA(1, 0), a3, voffA);
;             PG8_WAIT_V(8); PG8_WAIT_L(0); PG8_BAR; PG8_MMA(1, 0, At, B0); PG8_MMA(1, 1, At, B1); PG8_BAR; PG8_SCHED;
	ds_read_b128 v[144:147], v196
	ds_read_b128 v[156:159], v196 offset:1024
	ds_read_b128 v[160:163], v196 offset:2048
	ds_read_b128 v[164:167], v196 offset:3072
	ds_read_b128 v[168:171], v197
	ds_read_b128 v[172:175], v197 offset:1024
	ds_read_b128 v[176:179], v197 offset:2048
	ds_read_b128 v[180:183], v197 offset:3072
	ds_read_b128 v[184:187], v155 offset:32768
	ds_read_b128 v[188:191], v155 offset:33792
	ds_read_b128 v[192:195], v155 offset:34816
	ds_read_b128 v[200:203], v155 offset:35840
	ds_read_b128 v[204:207], v155 offset:36864
	ds_read_b128 v[208:211], v155 offset:37888
	ds_read_b128 v[212:215], v155 offset:38912
	ds_read_b128 v[216:219], v155 offset:39936
	s_add_u32 s98, s74, 0x80000
	s_addc_u32 s99, s75, 0
	s_mov_b32 m0, s69
	s_add_u32 s100, s74, 0x80
	s_addc_u32 s101, s75, 0
	global_load_lds_dwordx4 v128, s[98:99]
	s_mov_b32 m0, s76
	s_nop 0
	global_load_lds_dwordx4 v132, s[98:99]
	s_add_i32 s88, 0, 0x18000
	s_add_i32 s89, 0, 0x1c000
	s_add_u32 s98, s72, 0x80
	s_addc_u32 s99, s73, 0
	s_add_i32 s74, s88, s1
	s_mov_b32 m0, s74
	s_waitcnt vmcnt(8)
	s_waitcnt lgkmcnt(0)
	s_barrier
	s_setprio 1
	s_waitcnt lgkmcnt(0)
	v_mfma_f32_16x16x32_bf16 v[124:127], v[144:147], v[184:187], v[124:127]
	v_mfma_f32_16x16x32_bf16 v[120:123], v[160:163], v[184:187], v[120:123]
	v_mfma_f32_16x16x32_bf16 v[108:111], v[144:147], v[192:195], v[108:111]
	v_mfma_f32_16x16x32_bf16 v[104:107], v[160:163], v[192:195], v[104:107]
	v_mfma_f32_16x16x32_bf16 v[92:95], v[144:147], v[204:207], v[92:95]
	v_mfma_f32_16x16x32_bf16 v[88:91], v[160:163], v[204:207], v[88:91]
	v_mfma_f32_16x16x32_bf16 v[76:79], v[144:147], v[212:215], v[76:79]
	v_mfma_f32_16x16x32_bf16 v[72:75], v[160:163], v[212:215], v[72:75]
	v_mfma_f32_16x16x32_bf16 v[124:127], v[156:159], v[188:191], v[124:127]
	v_mfma_f32_16x16x32_bf16 v[120:123], v[164:167], v[188:191], v[120:123]
	v_mfma_f32_16x16x32_bf16 v[108:111], v[156:159], v[200:203], v[108:111]
	v_mfma_f32_16x16x32_bf16 v[104:107], v[164:167], v[200:203], v[104:107]
	v_mfma_f32_16x16x32_bf16 v[92:95], v[156:159], v[208:211], v[92:95]
	v_mfma_f32_16x16x32_bf16 v[88:91], v[164:167], v[208:211], v[88:91]
	v_mfma_f32_16x16x32_bf16 v[76:79], v[156:159], v[216:219], v[76:79]
	v_mfma_f32_16x16x32_bf16 v[72:75], v[164:167], v[216:219], v[72:75]
	s_setprio 0
	s_setprio 1
	v_mfma_f32_16x16x32_bf16 v[116:119], v[168:171], v[184:187], v[116:119]
	v_mfma_f32_16x16x32_bf16 v[112:115], v[176:179], v[184:187], v[112:115]
	v_mfma_f32_16x16x32_bf16 v[100:103], v[168:171], v[192:195], v[100:103]
	v_mfma_f32_16x16x32_bf16 v[96:99], v[176:179], v[192:195], v[96:99]
	v_mfma_f32_16x16x32_bf16 v[84:87], v[168:171], v[204:207], v[84:87]
	v_mfma_f32_16x16x32_bf16 v[80:83], v[176:179], v[204:207], v[80:83]
	v_mfma_f32_16x16x32_bf16 v[68:71], v[168:171], v[212:215], v[68:71]
	v_mfma_f32_16x16x32_bf16 v[64:67], v[176:179], v[212:215], v[64:67]
	v_mfma_f32_16x16x32_bf16 v[116:119], v[172:175], v[188:191], v[116:119]
	v_mfma_f32_16x16x32_bf16 v[112:115], v[180:183], v[188:191], v[112:115]
	v_mfma_f32_16x16x32_bf16 v[100:103], v[172:175], v[200:203], v[100:103]
	v_mfma_f32_16x16x32_bf16 v[96:99], v[180:183], v[200:203], v[96:99]
	v_mfma_f32_16x16x32_bf16 v[84:87], v[172:175], v[208:211], v[84:87]
	v_mfma_f32_16x16x32_bf16 v[80:83], v[180:183], v[208:211], v[80:83]
	v_mfma_f32_16x16x32_bf16 v[68:71], v[172:175], v[216:219], v[68:71]
	v_mfma_f32_16x16x32_bf16 v[64:67], v[180:183], v[216:219], v[64:67]
	s_setprio 0
	s_barrier
	ds_read_b128 v[184:187], v155 offset:49152
	ds_read_b128 v[188:191], v155 offset:50176
	ds_read_b128 v[192:195], v155 offset:51200
	ds_read_b128 v[200:203], v155 offset:52224
	ds_read_b128 v[204:207], v155 offset:53248
	ds_read_b128 v[208:211], v155 offset:54272
	ds_read_b128 v[212:215], v155 offset:55296
	ds_read_b128 v[216:219], v155 offset:56320
	global_load_lds_dwordx4 v130, s[98:99]
	s_add_i32 m0, s74, 0x2000
	s_add_u32 s72, s72, 0x80080
	s_addc_u32 s73, s73, 0
	s_add_i32 s74, s89, s1
	global_load_lds_dwordx4 v134, s[98:99]
	s_mov_b32 m0, s74
	s_nop 0
	global_load_lds_dwordx4 v130, s[72:73]
	s_add_i32 m0, s74, 0x2000
	s_nop 0
	global_load_lds_dwordx4 v134, s[72:73]
	s_mov_b32 m0, s78
	s_nop 0
	global_load_lds_dwordx4 v128, s[100:101]
	s_mov_b32 m0, s79
	s_nop 0
	global_load_lds_dwordx4 v132, s[100:101]
	s_add_i32 s87, s87, 2
	s_add_u32 s70, s70, 0x100
	s_addc_u32 s71, s71, 0
	s_add_u32 s85, s85, 0x100
	s_addc_u32 s86, s86, 0
	s_cmp_gt_u32 s87, 29
	s_waitcnt vmcnt(8)
	s_waitcnt lgkmcnt(0)
	s_barrier
	s_setprio 1
	s_waitcnt lgkmcnt(0)
	v_mfma_f32_16x16x32_bf16 v[60:63], v[144:147], v[184:187], v[60:63]
	v_mfma_f32_16x16x32_bf16 v[56:59], v[160:163], v[184:187], v[56:59]
	v_mfma_f32_16x16x32_bf16 v[44:47], v[144:147], v[192:195], v[44:47]
	v_mfma_f32_16x16x32_bf16 v[40:43], v[160:163], v[192:195], v[40:43]
	v_mfma_f32_16x16x32_bf16 v[28:31], v[144:147], v[204:207], v[28:31]
	v_mfma_f32_16x16x32_bf16 v[24:27], v[160:163], v[204:207], v[24:27]
	v_mfma_f32_16x16x32_bf16 v[12:15], v[144:147], v[212:215], v[12:15]
	v_mfma_f32_16x16x32_bf16 v[8:11], v[160:163], v[212:215], v[8:11]
	v_mfma_f32_16x16x32_bf16 v[60:63], v[156:159], v[188:191], v[60:63]
	v_mfma_f32_16x16x32_bf16 v[56:59], v[164:167], v[188:191], v[56:59]
	v_mfma_f32_16x16x32_bf16 v[44:47], v[156:159], v[200:203], v[44:47]
	v_mfma_f32_16x16x32_bf16 v[40:43], v[164:167], v[200:203], v[40:43]
	v_mfma_f32_16x16x32_bf16 v[28:31], v[156:159], v[208:211], v[28:31]
	v_mfma_f32_16x16x32_bf16 v[24:27], v[164:167], v[208:211], v[24:27]
	v_mfma_f32_16x16x32_bf16 v[12:15], v[156:159], v[216:219], v[12:15]
	v_mfma_f32_16x16x32_bf16 v[8:11], v[164:167], v[216:219], v[8:11]
	s_setprio 0
	s_setprio 1
	v_mfma_f32_16x16x32_bf16 v[52:55], v[168:171], v[184:187], v[52:55]
	v_mfma_f32_16x16x32_bf16 v[48:51], v[176:179], v[184:187], v[48:51]
	v_mfma_f32_16x16x32_bf16 v[36:39], v[168:171], v[192:195], v[36:39]
	v_mfma_f32_16x16x32_bf16 v[32:35], v[176:179], v[192:195], v[32:35]
	v_mfma_f32_16x16x32_bf16 v[20:23], v[168:171], v[204:207], v[20:23]
	v_mfma_f32_16x16x32_bf16 v[16:19], v[176:179], v[204:207], v[16:19]
	v_mfma_f32_16x16x32_bf16 v[4:7], v[168:171], v[212:215], v[4:7]
	v_mfma_f32_16x16x32_bf16 v[0:3], v[176:179], v[212:215], v[0:3]
	v_mfma_f32_16x16x32_bf16 v[52:55], v[172:175], v[188:191], v[52:55]
	v_mfma_f32_16x16x32_bf16 v[48:51], v[180:183], v[188:191], v[48:51]
	v_mfma_f32_16x16x32_bf16 v[36:39], v[172:175], v[200:203], v[36:39]
	v_mfma_f32_16x16x32_bf16 v[32:35], v[180:183], v[200:203], v[32:35]
	v_mfma_f32_16x16x32_bf16 v[20:23], v[172:175], v[208:211], v[20:23]
	v_mfma_f32_16x16x32_bf16 v[16:19], v[180:183], v[208:211], v[16:19]
	v_mfma_f32_16x16x32_bf16 v[4:7], v[172:175], v[216:219], v[4:7]
	v_mfma_f32_16x16x32_bf16 v[0:3], v[180:183], v[216:219], v[0:3]
	s_setprio 0
	s_barrier
	s_cbranch_scc0 .LBB0_245
	s_and_b64 vcc, exec, s[14:15]
	s_cbranch_vccz .LBB0_248
	s_barrier

; #define PG8_STAGE(bufoff, gbase, voff) do { _Pragma("unroll") for (int _i = 0; _i < 2; ++_i) \
;         __builtin_amdgcn_global_load_lds((const unsigned*)((const char*)(gbase) + (voff)[_i]), (PG8_LAS unsigned*)(lds + (bufoff) + ldsw + _i * 8192), 16, 0, 0); } while (0)
; #define PG8_LDA(dst, b, h) do { _Pragma("unroll") for (int m = 0; m < 4; ++m) _Pragma("unroll") for (int k = 0; k < 2; ++k) dst[m][k] = *(const PG8_LAS bf16x8*)(lds + PG8_SA(b, h) + aoff + m * 2048 + k * 1024); } while (0)
; #define PG8_LDB(dst, b, h) do { _Pragma("unroll") for (int n = 0; n < 2; ++n) _Pragma("unroll") for (int k = 0; k < 2; ++k) dst[n][k] = *(const PG8_LAS bf16x8*)(lds + PG8_SB(b, h) + boff + n * 2048 + k * 1024); } while (0)
; #define PG8_MMA(ai, bj, At, Bt) do { __builtin_amdgcn_s_setprio(1); _Pragma("unroll") for (int m = 0; m < 4; ++m) _Pragma("unroll") for (int n = 0; n < 2; ++n) _Pragma("unroll") for (int k = 0; k < 2; ++k) \
;         acc[ai][bj][m][n] = __builtin_amdgcn_mfma_f32_16x16x32_bf16(Bt[n][k], At[m][k], acc[ai][bj][m][n], 0, 0, 0); __builtin_amdgcn_s_setprio(0); } while (0)
; #define PG8_WAIT_V(n) asm volatile("s_waitcnt vmcnt(" #n ")" ::: "memory")
; #define PG8_WAIT_L(n) asm volatile("s_waitcnt lgkmcnt(" #n ")" ::: "memory")
; template <class Epi, class Sched, bool ALIGN_EPI = false, bool SP2 = false>
; __device__ __forceinline__ void gemm_phase(PG8_LAS unsigned char* lds, const Gemm g, const Sched& S, const Epi& E) {
;     ...
;             const bool last = (t == nt - 2);
;             const char* a1 = cA + (size_t)(t + 1) * kstep;
;             const char* a2 = last ? nA : cA + (size_t)(t + 2) * kstep; const char* b2 = last ? nB : cB + (size_t)(t + 2) * kstep;
;             const char* a3 = a2 + kstep; const char* b3 = b2 + kstep;
;             if (last && has_next) S.a_ready(nxt);
;             if constexpr (SP2) {
;             PG8_LDB(B0, 0, 0); PG8_LDB(B1, 0, 1); PG8_SCHED; PG8_LDA(At, 0, 0); PG8_STAGE(PG8_SA(1, 1), a1 + hstep, voffA);
;             PG8_WAIT_V(8); PG8_WAIT_L(0); PG8_BAR; PG8_MMA(0, 0, At, B0); PG8_MMA(0, 1, At, B1); PG8_BAR; PG8_SCHED;
;             PG8_LDA(At, 0, 1); PG8_STAGE(PG8_SB(0, 0), b2, voffB); PG8_STAGE(PG8_SB(0, 1), b2 + hstep, voffB); PG8_STAGE(PG8_SA(0, 0), a2, voffA);
;             PG8_WAIT_V(8); PG8_WAIT_L(0); PG8_BAR; PG8_MMA(1, 0, At, B0); PG8_MMA(1, 1, At, B1); PG8_BAR; PG8_SCHED;
.LBB0_376:
	ds_read_b128 v[152:155], v149
	ds_read_b128 v[156:159], v149 offset:1024
	ds_read_b128 v[160:163], v149 offset:2048
	ds_read_b128 v[164:167], v149 offset:3072
	ds_read_b128 v[168:171], v150
	ds_read_b128 v[172:175], v150 offset:1024
	ds_read_b128 v[176:179], v150 offset:2048
	ds_read_b128 v[180:183], v150 offset:3072
	s_add_i32 m0, s33, 0xc000
	ds_read_b128 v[184:187], v151
	ds_read_b128 v[188:191], v151 offset:1024
	ds_read_b128 v[192:195], v151 offset:2048
	ds_read_b128 v[200:203], v151 offset:3072
	ds_read_b128 v[204:207], v151 offset:4096
	ds_read_b128 v[208:211], v151 offset:5120
	ds_read_b128 v[212:215], v151 offset:6144
	ds_read_b128 v[216:219], v151 offset:7168
	global_load_lds_dwordx4 v136, s[68:69]
	s_add_i32 m0, s33, 0xe000
	s_nop 0
	global_load_lds_dwordx4 v138, s[68:69]
	s_add_u32 s70, s68, 0xfff80080
	s_addc_u32 s71, s69, -1
	s_cmp_eq_u32 s88, 28
	s_cselect_b32 s73, s25, s71
	s_cselect_b32 s72, s61, s70
	s_cselect_b32 s71, s49, s87
	s_cselect_b32 s70, s85, s86
	s_add_i32 s89, s80, s1
	s_mov_b32 m0, s89
	s_waitcnt vmcnt(8)
	s_waitcnt lgkmcnt(0)
	s_barrier
	s_setprio 1
	s_waitcnt lgkmcnt(0)
	v_mfma_f32_16x16x32_bf16 v[124:127], v[152:155], v[184:187], v[124:127]
	v_mfma_f32_16x16x32_bf16 v[120:123], v[160:163], v[184:187], v[120:123]
	v_mfma_f32_16x16x32_bf16 v[108:111], v[152:155], v[192:195], v[108:111]
	v_mfma_f32_16x16x32_bf16 v[104:107], v[160:163], v[192:195], v[104:107]
	v_mfma_f32_16x16x32_bf16 v[92:95], v[152:155], v[204:207], v[92:95]
	v_mfma_f32_16x16x32_bf16 v[88:91], v[160:163], v[204:207], v[88:91]
	v_mfma_f32_16x16x32_bf16 v[76:79], v[152:155], v[212:215], v[76:79]
	v_mfma_f32_16x16x32_bf16 v[72:75], v[160:163], v[212:215], v[72:75]
	v_mfma_f32_16x16x32_bf16 v[124:127], v[156:159], v[188:191], v[124:127]
	v_mfma_f32_16x16x32_bf16 v[120:123], v[164:167], v[188:191], v[120:123]
	v_mfma_f32_16x16x32_bf16 v[108:111], v[156:159], v[200:203], v[108:111]
	v_mfma_f32_16x16x32_bf16 v[104:107], v[164:167], v[200:203], v[104:107]
	v_mfma_f32_16x16x32_bf16 v[92:95], v[156:159], v[208:211], v[92:95]
	v_mfma_f32_16x16x32_bf16 v[88:91], v[164:167], v[208:211], v[88:91]
	v_mfma_f32_16x16x32_bf16 v[76:79], v[156:159], v[216:219], v[76:79]
	v_mfma_f32_16x16x32_bf16 v[72:75], v[164:167], v[216:219], v[72:75]
	s_setprio 0
	s_setprio 1
	v_mfma_f32_16x16x32_bf16 v[116:119], v[168:171], v[184:187], v[116:119]
	v_mfma_f32_16x16x32_bf16 v[112:115], v[176:179], v[184:187], v[112:115]
	v_mfma_f32_16x16x32_bf16 v[100:103], v[168:171], v[192:195], v[100:103]
	v_mfma_f32_16x16x32_bf16 v[96:99], v[176:179], v[192:195], v[96:99]
	v_mfma_f32_16x16x32_bf16 v[84:87], v[168:171], v[204:207], v[84:87]
	v_mfma_f32_16x16x32_bf16 v[80:83], v[176:179], v[204:207], v[80:83]
	v_mfma_f32_16x16x32_bf16 v[68:71], v[168:171], v[212:215], v[68:71]
	v_mfma_f32_16x16x32_bf16 v[64:67], v[176:179], v[212:215], v[64:67]
	v_mfma_f32_16x16x32_bf16 v[116:119], v[172:175], v[188:191], v[116:119]
	v_mfma_f32_16x16x32_bf16 v[112:115], v[180:183], v[188:191], v[112:115]
	v_mfma_f32_16x16x32_bf16 v[100:103], v[172:175], v[200:203], v[100:103]
	v_mfma_f32_16x16x32_bf16 v[96:99], v[180:183], v[200:203], v[96:99]
	v_mfma_f32_16x16x32_bf16 v[84:87], v[172:175], v[208:211], v[84:87]
	v_mfma_f32_16x16x32_bf16 v[80:83], v[180:183], v[208:211], v[80:83]
	v_mfma_f32_16x16x32_bf16 v[68:71], v[172:175], v[216:219], v[68:71]
	v_mfma_f32_16x16x32_bf16 v[64:67], v[180:183], v[216:219], v[64:67]
	s_setprio 0
	s_barrier
	ds_read_b128 v[184:187], v151 offset:16384
	ds_read_b128 v[188:191], v151 offset:17408
	ds_read_b128 v[192:195], v151 offset:18432
	ds_read_b128 v[200:203], v151 offset:19456
	ds_read_b128 v[204:207], v151 offset:20480
	ds_read_b128 v[208:211], v151 offset:21504
	ds_read_b128 v[212:215], v151 offset:22528
	ds_read_b128 v[216:219], v151 offset:23552
	global_load_lds_dwordx4 v130, s[70:71]
	s_add_i32 m0, s89, 0x2000
	s_add_u32 s96, s70, 0x80000
	s_addc_u32 s97, s71, 0
	s_add_i32 s89, s81, s1
	global_load_lds_dwordx4 v134, s[70:71]
	s_mov_b32 m0, s89
	s_nop 0
	global_load_lds_dwordx4 v130, s[96:97]
	s_add_i32 m0, s89, 0x2000
	s_nop 0
	global_load_lds_dwordx4 v134, s[96:97]
	s_mov_b32 m0, s33
	s_nop 0
	global_load_lds_dwordx4 v128, s[72:73]
	s_mov_b32 m0, s35
	s_nop 0
	global_load_lds_dwordx4 v132, s[72:73]
	s_waitcnt vmcnt(8)
	s_waitcnt lgkmcnt(0)
	s_barrier
	s_setprio 1
	s_waitcnt lgkmcnt(0)
	v_mfma_f32_16x16x32_bf16 v[60:63], v[152:155], v[184:187], v[60:63]
	v_mfma_f32_16x16x32_bf16 v[56:59], v[160:163], v[184:187], v[56:59]
	v_mfma_f32_16x16x32_bf16 v[44:47], v[152:155], v[192:195], v[44:47]
	v_mfma_f32_16x16x32_bf16 v[40:43], v[160:163], v[192:195], v[40:43]
	v_mfma_f32_16x16x32_bf16 v[28:31], v[152:155], v[204:207], v[28:31]
	v_mfma_f32_16x16x32_bf16 v[24:27], v[160:163], v[204:207], v[24:27]
	v_mfma_f32_16x16x32_bf16 v[12:15], v[152:155], v[212:215], v[12:15]
	v_mfma_f32_16x16x32_bf16 v[8:11], v[160:163], v[212:215], v[8:11]
	v_mfma_f32_16x16x32_bf16 v[60:63], v[156:159], v[188:191], v[60:63]
	v_mfma_f32_16x16x32_bf16 v[56:59], v[164:167], v[188:191], v[56:59]
	v_mfma_f32_16x16x32_bf16 v[44:47], v[156:159], v[200:203], v[44:47]
	v_mfma_f32_16x16x32_bf16 v[40:43], v[164:167], v[200:203], v[40:43]
	v_mfma_f32_16x16x32_bf16 v[28:31], v[156:159], v[208:211], v[28:31]
	v_mfma_f32_16x16x32_bf16 v[24:27], v[164:167], v[208:211], v[24:27]
	v_mfma_f32_16x16x32_bf16 v[12:15], v[156:159], v[216:219], v[12:15]
	v_mfma_f32_16x16x32_bf16 v[8:11], v[164:167], v[216:219], v[8:11]
	s_setprio 0
	s_setprio 1
	v_mfma_f32_16x16x32_bf16 v[52:55], v[168:171], v[184:187], v[52:55]
	v_mfma_f32_16x16x32_bf16 v[48:51], v[176:179], v[184:187], v[48:51]
	v_mfma_f32_16x16x32_bf16 v[36:39], v[168:171], v[192:195], v[36:39]
	v_mfma_f32_16x16x32_bf16 v[32:35], v[176:179], v[192:195], v[32:35]
	v_mfma_f32_16x16x32_bf16 v[20:23], v[168:171], v[204:207], v[20:23]
	v_mfma_f32_16x16x32_bf16 v[16:19], v[176:179], v[204:207], v[16:19]
	v_mfma_f32_16x16x32_bf16 v[4:7], v[168:171], v[212:215], v[4:7]
	v_mfma_f32_16x16x32_bf16 v[0:3], v[176:179], v[212:215], v[0:3]
	v_mfma_f32_16x16x32_bf16 v[52:55], v[172:175], v[188:191], v[52:55]
	v_mfma_f32_16x16x32_bf16 v[48:51], v[180:183], v[188:191], v[48:51]
	v_mfma_f32_16x16x32_bf16 v[36:39], v[172:175], v[200:203], v[36:39]
	v_mfma_f32_16x16x32_bf16 v[32:35], v[180:183], v[200:203], v[32:35]
	v_mfma_f32_16x16x32_bf16 v[20:23], v[172:175], v[208:211], v[20:23]
	v_mfma_f32_16x16x32_bf16 v[16:19], v[180:183], v[208:211], v[16:19]
	v_mfma_f32_16x16x32_bf16 v[4:7], v[172:175], v[216:219], v[4:7]
	v_mfma_f32_16x16x32_bf16 v[0:3], v[180:183], v[216:219], v[0:3]
	s_setprio 0
	s_barrier
; #define PG8_STAGE(bufoff, gbase, voff) do { _Pragma("unroll") for (int _i = 0; _i < 2; ++_i) \
;         __builtin_amdgcn_global_load_lds((const unsigned*)((const char*)(gbase) + (voff)[_i]), (PG8_LAS unsigned*)(lds + (bufoff) + ldsw + _i * 8192), 16, 0, 0); } while (0)
; #define PG8_LDA(dst, b, h) do { _Pragma("unroll") for (int m = 0; m < 4; ++m) _Pragma("unroll") for (int k = 0; k < 2; ++k) dst[m][k] = *(const PG8_LAS bf16x8*)(lds + PG8_SA(b, h) + aoff + m * 2048 + k * 1024); } while (0)
; #define PG8_LDB(dst, b, h) do { _Pragma("unroll") for (int n = 0; n < 2; ++n) _Pragma("unroll") for (int k = 0; k < 2; ++k) dst[n][k] = *(const PG8_LAS bf16x8*)(lds + PG8_SB(b, h) + boff + n * 2048 + k * 1024); } while (0)
; #define PG8_MMA(ai, bj, At, Bt) do { __builtin_amdgcn_s_setprio(1); _Pragma("unroll") for (int m = 0; m < 4; ++m) _Pragma("unroll") for (int n = 0; n < 2; ++n) _Pragma("unroll") for (int k = 0; k < 2; ++k) \
;         acc[ai][bj][m][n] = __builtin_amdgcn_mfma_f32_16x16x32_bf16(Bt[n][k], At[m][k], acc[ai][bj][m][n], 0, 0, 0); __builtin_amdgcn_s_setprio(0); } while (0)
; #define PG8_WAIT_V(n) asm volatile("s_waitcnt vmcnt(" #n ")" ::: "memory")
; #define PG8_WAIT_L(n) asm volatile("s_waitcnt lgkmcnt(" #n ")" ::: "memory")
; #define PG8_BAR __builtin_amdgcn_s_barrier()
; #define PG8_SCHED __builtin_amdgcn_sched_barrier(0)
; template <class Epi, class Sched, bool ALIGN_EPI = false, bool SP2 = false>
; __device__ __forceinline__ void gemm_phase(PG8_LAS unsigned char* lds, const Gemm g, const Sched& S, const Epi& E) {
;     ...
;         for (int t = 0; t < nt; t += 2) {
;     ...
;             PG8_LDB(B0, 1, 0); PG8_LDB(B1, 1, 1); PG8_SCHED; PG8_LDA(At, 1, 0); PG8_STAGE(PG8_SA(0, 1), a2 + hstep, voffA);
;             PG8_WAIT_V(8); PG8_WAIT_L(0); PG8_BAR; PG8_MMA(0, 0, At, B0); PG8_MMA(0, 1, At, B1); PG8_BAR; PG8_SCHED;
;             PG8_LDA(At, 1, 1); PG8_STAGE(PG8_SB(1, 0), b3, voffB); PG8_STAGE(PG8_SB(1, 1), b3 + hstep, voffB); PG8_STAGE(PG8_SA(1, 0), a3, voffA);
;             PG8_WAIT_V(8); PG8_WAIT_L(0); PG8_BAR; PG8_MMA(1, 0, At, B0); PG8_MMA(1, 1, At, B1); PG8_BAR; PG8_SCHED;
	ds_read_b128 v[152:155], v196
	ds_read_b128 v[156:159], v196 offset:1024
	ds_read_b128 v[160:163], v196 offset:2048
	ds_read_b128 v[164:167], v196 offset:3072
	ds_read_b128 v[168:171], v197
	ds_read_b128 v[172:175], v197 offset:1024
	ds_read_b128 v[176:179], v197 offset:2048
	ds_read_b128 v[180:183], v197 offset:3072
	ds_read_b128 v[184:187], v151 offset:32768
	ds_read_b128 v[188:191], v151 offset:33792
	ds_read_b128 v[192:195], v151 offset:34816
	ds_read_b128 v[200:203], v151 offset:35840
	ds_read_b128 v[204:207], v151 offset:36864
	ds_read_b128 v[208:211], v151 offset:37888
	ds_read_b128 v[212:215], v151 offset:38912
	ds_read_b128 v[216:219], v151 offset:39936
	s_add_u32 s98, s72, 0x80000
	s_addc_u32 s99, s73, 0
	s_mov_b32 m0, s67
	s_add_u32 s100, s72, 0x80
	s_addc_u32 s101, s73, 0
	global_load_lds_dwordx4 v128, s[98:99]
	s_mov_b32 m0, s74
	s_nop 0
	global_load_lds_dwordx4 v132, s[98:99]
	s_add_i32 s89, 0, 0x18000
	s_add_i32 s94, 0, 0x1c000
	s_add_u32 s98, s70, 0x80
	s_addc_u32 s99, s71, 0
	s_add_i32 s72, s89, s1
	s_mov_b32 m0, s72
	s_waitcnt vmcnt(8)
	s_waitcnt lgkmcnt(0)
	s_barrier
	s_setprio 1
	s_waitcnt lgkmcnt(0)
	v_mfma_f32_16x16x32_bf16 v[124:127], v[152:155], v[184:187], v[124:127]
	v_mfma_f32_16x16x32_bf16 v[120:123], v[160:163], v[184:187], v[120:123]
	v_mfma_f32_16x16x32_bf16 v[108:111], v[152:155], v[192:195], v[108:111]
	v_mfma_f32_16x16x32_bf16 v[104:107], v[160:163], v[192:195], v[104:107]
	v_mfma_f32_16x16x32_bf16 v[92:95], v[152:155], v[204:207], v[92:95]
	v_mfma_f32_16x16x32_bf16 v[88:91], v[160:163], v[204:207], v[88:91]
	v_mfma_f32_16x16x32_bf16 v[76:79], v[152:155], v[212:215], v[76:79]
	v_mfma_f32_16x16x32_bf16 v[72:75], v[160:163], v[212:215], v[72:75]
	v_mfma_f32_16x16x32_bf16 v[124:127], v[156:159], v[188:191], v[124:127]
	v_mfma_f32_16x16x32_bf16 v[120:123], v[164:167], v[188:191], v[120:123]
	v_mfma_f32_16x16x32_bf16 v[108:111], v[156:159], v[200:203], v[108:111]
	v_mfma_f32_16x16x32_bf16 v[104:107], v[164:167], v[200:203], v[104:107]
	v_mfma_f32_16x16x32_bf16 v[92:95], v[156:159], v[208:211], v[92:95]
	v_mfma_f32_16x16x32_bf16 v[88:91], v[164:167], v[208:211], v[88:91]
	v_mfma_f32_16x16x32_bf16 v[76:79], v[156:159], v[216:219], v[76:79]
	v_mfma_f32_16x16x32_bf16 v[72:75], v[164:167], v[216:219], v[72:75]
	s_setprio 0
	s_setprio 1
	v_mfma_f32_16x16x32_bf16 v[116:119], v[168:171], v[184:187], v[116:119]
	v_mfma_f32_16x16x32_bf16 v[112:115], v[176:179], v[184:187], v[112:115]
	v_mfma_f32_16x16x32_bf16 v[100:103], v[168:171], v[192:195], v[100:103]
	v_mfma_f32_16x16x32_bf16 v[96:99], v[176:179], v[192:195], v[96:99]
	v_mfma_f32_16x16x32_bf16 v[84:87], v[168:171], v[204:207], v[84:87]
	v_mfma_f32_16x16x32_bf16 v[80:83], v[176:179], v[204:207], v[80:83]
	v_mfma_f32_16x16x32_bf16 v[68:71], v[168:171], v[212:215], v[68:71]
	v_mfma_f32_16x16x32_bf16 v[64:67], v[176:179], v[212:215], v[64:67]
	v_mfma_f32_16x16x32_bf16 v[116:119], v[172:175], v[188:191], v[116:119]
	v_mfma_f32_16x16x32_bf16 v[112:115], v[180:183], v[188:191], v[112:115]
	v_mfma_f32_16x16x32_bf16 v[100:103], v[172:175], v[200:203], v[100:103]
	v_mfma_f32_16x16x32_bf16 v[96:99], v[180:183], v[200:203], v[96:99]
	v_mfma_f32_16x16x32_bf16 v[84:87], v[172:175], v[208:211], v[84:87]
	v_mfma_f32_16x16x32_bf16 v[80:83], v[180:183], v[208:211], v[80:83]
	v_mfma_f32_16x16x32_bf16 v[68:71], v[172:175], v[216:219], v[68:71]
	v_mfma_f32_16x16x32_bf16 v[64:67], v[180:183], v[216:219], v[64:67]
	s_setprio 0
	s_barrier
	ds_read_b128 v[184:187], v151 offset:49152
	ds_read_b128 v[188:191], v151 offset:50176
	ds_read_b128 v[192:195], v151 offset:51200
	ds_read_b128 v[200:203], v151 offset:52224
	ds_read_b128 v[204:207], v151 offset:53248
	ds_read_b128 v[208:211], v151 offset:54272
	ds_read_b128 v[212:215], v151 offset:55296
	ds_read_b128 v[216:219], v151 offset:56320
	global_load_lds_dwordx4 v130, s[98:99]
	s_add_i32 m0, s72, 0x2000
	s_add_u32 s70, s70, 0x80080
	s_addc_u32 s71, s71, 0
	s_add_i32 s72, s94, s1
	global_load_lds_dwordx4 v134, s[98:99]
	s_mov_b32 m0, s72
	s_nop 0
	global_load_lds_dwordx4 v130, s[70:71]
	s_add_i32 m0, s72, 0x2000
	s_nop 0
	global_load_lds_dwordx4 v134, s[70:71]
	s_mov_b32 m0, s76
	s_nop 0
	global_load_lds_dwordx4 v128, s[100:101]
	s_mov_b32 m0, s77
	s_nop 0
	global_load_lds_dwordx4 v132, s[100:101]
	s_add_i32 s88, s88, 2
	s_add_u32 s68, s68, 0x100
	s_addc_u32 s69, s69, 0
	s_add_u32 s86, s86, 0x100
	s_addc_u32 s87, s87, 0
	s_cmp_gt_u32 s88, 29
	s_waitcnt vmcnt(8)
	s_waitcnt lgkmcnt(0)
	s_barrier
	s_setprio 1
	s_waitcnt lgkmcnt(0)
	v_mfma_f32_16x16x32_bf16 v[60:63], v[152:155], v[184:187], v[60:63]
	v_mfma_f32_16x16x32_bf16 v[56:59], v[160:163], v[184:187], v[56:59]
	v_mfma_f32_16x16x32_bf16 v[44:47], v[152:155], v[192:195], v[44:47]
	v_mfma_f32_16x16x32_bf16 v[40:43], v[160:163], v[192:195], v[40:43]
	v_mfma_f32_16x16x32_bf16 v[28:31], v[152:155], v[204:207], v[28:31]
	v_mfma_f32_16x16x32_bf16 v[24:27], v[160:163], v[204:207], v[24:27]
	v_mfma_f32_16x16x32_bf16 v[12:15], v[152:155], v[212:215], v[12:15]
	v_mfma_f32_16x16x32_bf16 v[8:11], v[160:163], v[212:215], v[8:11]
	v_mfma_f32_16x16x32_bf16 v[60:63], v[156:159], v[188:191], v[60:63]
	v_mfma_f32_16x16x32_bf16 v[56:59], v[164:167], v[188:191], v[56:59]
	v_mfma_f32_16x16x32_bf16 v[44:47], v[156:159], v[200:203], v[44:47]
	v_mfma_f32_16x16x32_bf16 v[40:43], v[164:167], v[200:203], v[40:43]
	v_mfma_f32_16x16x32_bf16 v[28:31], v[156:159], v[208:211], v[28:31]
	v_mfma_f32_16x16x32_bf16 v[24:27], v[164:167], v[208:211], v[24:27]
	v_mfma_f32_16x16x32_bf16 v[12:15], v[156:159], v[216:219], v[12:15]
	v_mfma_f32_16x16x32_bf16 v[8:11], v[164:167], v[216:219], v[8:11]
	s_setprio 0
	s_setprio 1
	v_mfma_f32_16x16x32_bf16 v[52:55], v[168:171], v[184:187], v[52:55]
	v_mfma_f32_16x16x32_bf16 v[48:51], v[176:179], v[184:187], v[48:51]
	v_mfma_f32_16x16x32_bf16 v[36:39], v[168:171], v[192:195], v[36:39]
	v_mfma_f32_16x16x32_bf16 v[32:35], v[176:179], v[192:195], v[32:35]
	v_mfma_f32_16x16x32_bf16 v[20:23], v[168:171], v[204:207], v[20:23]
	v_mfma_f32_16x16x32_bf16 v[16:19], v[176:179], v[204:207], v[16:19]
	v_mfma_f32_16x16x32_bf16 v[4:7], v[168:171], v[212:215], v[4:7]
	v_mfma_f32_16x16x32_bf16 v[0:3], v[176:179], v[212:215], v[0:3]
	v_mfma_f32_16x16x32_bf16 v[52:55], v[172:175], v[188:191], v[52:55]
	v_mfma_f32_16x16x32_bf16 v[48:51], v[180:183], v[188:191], v[48:51]
	v_mfma_f32_16x16x32_bf16 v[36:39], v[172:175], v[200:203], v[36:39]
	v_mfma_f32_16x16x32_bf16 v[32:35], v[180:183], v[200:203], v[32:35]
	v_mfma_f32_16x16x32_bf16 v[20:23], v[172:175], v[208:211], v[20:23]
	v_mfma_f32_16x16x32_bf16 v[16:19], v[180:183], v[208:211], v[16:19]
	v_mfma_f32_16x16x32_bf16 v[4:7], v[172:175], v[216:219], v[4:7]
	v_mfma_f32_16x16x32_bf16 v[0:3], v[180:183], v[216:219], v[0:3]
	s_setprio 0
	s_barrier
	s_cbranch_scc0 .LBB0_376
	s_and_b64 vcc, exec, s[14:15]
	s_cbranch_vccz .LBB0_379
	s_barrier

; #define PG8_STAGE(bufoff, gbase, voff) do { _Pragma("unroll") for (int _i = 0; _i < 2; ++_i) \
;         __builtin_amdgcn_global_load_lds((const unsigned*)((const char*)(gbase) + (voff)[_i]), (PG8_LAS unsigned*)(lds + (bufoff) + ldsw + _i * 8192), 16, 0, 0); } while (0)
; #define PG8_LDA(dst, b, h) do { _Pragma("unroll") for (int m = 0; m < 4; ++m) _Pragma("unroll") for (int k = 0; k < 2; ++k) dst[m][k] = *(const PG8_LAS bf16x8*)(lds + PG8_SA(b, h) + aoff + m * 2048 + k * 1024); } while (0)
; #define PG8_LDB(dst, b, h) do { _Pragma("unroll") for (int n = 0; n < 2; ++n) _Pragma("unroll") for (int k = 0; k < 2; ++k) dst[n][k] = *(const PG8_LAS bf16x8*)(lds + PG8_SB(b, h) + boff + n * 2048 + k * 1024); } while (0)
; #define PG8_MMA(ai, bj, At, Bt) do { __builtin_amdgcn_s_setprio(1); _Pragma("unroll") for (int m = 0; m < 4; ++m) _Pragma("unroll") for (int n = 0; n < 2; ++n) _Pragma("unroll") for (int k = 0; k < 2; ++k) \
;         acc[ai][bj][m][n] = __builtin_amdgcn_mfma_f32_16x16x32_bf16(Bt[n][k], At[m][k], acc[ai][bj][m][n], 0, 0, 0); __builtin_amdgcn_s_setprio(0); } while (0)
; #define PG8_WAIT_V(n) asm volatile("s_waitcnt vmcnt(" #n ")" ::: "memory")
; #define PG8_WAIT_L(n) asm volatile("s_waitcnt lgkmcnt(" #n ")" ::: "memory")
; template <class Epi, class Sched, bool ALIGN_EPI = false, bool SP2 = false>
; __device__ __forceinline__ void gemm_phase(PG8_LAS unsigned char* lds, const Gemm g, const Sched& S, const Epi& E) {
;     ...
;             const bool last = (t == nt - 2);
;             const char* a1 = cA + (size_t)(t + 1) * kstep;
;             const char* a2 = last ? nA : cA + (size_t)(t + 2) * kstep; const char* b2 = last ? nB : cB + (size_t)(t + 2) * kstep;
;             const char* a3 = a2 + kstep; const char* b3 = b2 + kstep;
;             if (last && has_next) S.a_ready(nxt);
;             if constexpr (SP2) {
;             PG8_LDB(B0, 0, 0); PG8_LDB(B1, 0, 1); PG8_SCHED; PG8_LDA(At, 0, 0); PG8_STAGE(PG8_SA(1, 1), a1 + hstep, voffA);
;             PG8_WAIT_V(8); PG8_WAIT_L(0); PG8_BAR; PG8_MMA(0, 0, At, B0); PG8_MMA(0, 1, At, B1); PG8_BAR; PG8_SCHED;
;             PG8_LDA(At, 0, 1); PG8_STAGE(PG8_SB(0, 0), b2, voffB); PG8_STAGE(PG8_SB(0, 1), b2 + hstep, voffB); PG8_STAGE(PG8_SA(0, 0), a2, voffA);
;             PG8_WAIT_V(8); PG8_WAIT_L(0); PG8_BAR; PG8_MMA(1, 0, At, B0); PG8_MMA(1, 1, At, B1); PG8_BAR; PG8_SCHED;
.LBB0_452:
	ds_read_b128 v[128:131], v202
	ds_read_b128 v[132:135], v202 offset:1024
	ds_read_b128 v[136:139], v202 offset:2048
	ds_read_b128 v[140:143], v202 offset:3072
	ds_read_b128 v[144:147], v203
	ds_read_b128 v[148:151], v203 offset:1024
	ds_read_b128 v[152:155], v203 offset:2048
	ds_read_b128 v[156:159], v203 offset:3072
	s_add_i32 m0, s33, 0xc000
	ds_read_b128 v[160:163], v204
	ds_read_b128 v[164:167], v204 offset:1024
	ds_read_b128 v[184:187], v204 offset:2048
	ds_read_b128 v[188:191], v204 offset:3072
	ds_read_b128 v[192:195], v204 offset:4096
	ds_read_b128 v[206:209], v204 offset:5120
	ds_read_b128 v[210:213], v204 offset:6144
	ds_read_b128 v[214:217], v204 offset:7168
	global_load_lds_dwordx4 v176, s[70:71]
	s_add_i32 m0, s33, 0xe000
	s_nop 0
	global_load_lds_dwordx4 v178, s[70:71]
	s_add_u32 s72, s70, 0xffe00080
	s_addc_u32 s73, s71, -1
	s_cmpk_eq_i32 s87, 0x7c
	s_cselect_b32 s75, s25, s73
	s_cselect_b32 s74, s63, s72
	s_cselect_b32 s73, s61, s86
	s_cselect_b32 s72, s84, s85
	s_add_i32 s88, s82, s1
	s_mov_b32 m0, s88
	s_waitcnt vmcnt(8)
	s_waitcnt lgkmcnt(0)
	s_barrier
	s_setprio 1
	s_waitcnt lgkmcnt(0)
	v_mfma_f32_16x16x32_bf16 v[124:127], v[128:131], v[160:163], v[124:127]
	v_mfma_f32_16x16x32_bf16 v[120:123], v[136:139], v[160:163], v[120:123]
	v_mfma_f32_16x16x32_bf16 v[116:119], v[128:131], v[184:187], v[116:119]
	v_mfma_f32_16x16x32_bf16 v[108:111], v[136:139], v[184:187], v[108:111]
	v_mfma_f32_16x16x32_bf16 v[92:95], v[128:131], v[192:195], v[92:95]
	v_mfma_f32_16x16x32_bf16 v[88:91], v[136:139], v[192:195], v[88:91]
	v_mfma_f32_16x16x32_bf16 v[76:79], v[128:131], v[210:213], v[76:79]
	v_mfma_f32_16x16x32_bf16 v[72:75], v[136:139], v[210:213], v[72:75]
	v_mfma_f32_16x16x32_bf16 v[124:127], v[132:135], v[164:167], v[124:127]
	v_mfma_f32_16x16x32_bf16 v[120:123], v[140:143], v[164:167], v[120:123]
	v_mfma_f32_16x16x32_bf16 v[116:119], v[132:135], v[188:191], v[116:119]
	v_mfma_f32_16x16x32_bf16 v[108:111], v[140:143], v[188:191], v[108:111]
	v_mfma_f32_16x16x32_bf16 v[92:95], v[132:135], v[206:209], v[92:95]
	v_mfma_f32_16x16x32_bf16 v[88:91], v[140:143], v[206:209], v[88:91]
	v_mfma_f32_16x16x32_bf16 v[76:79], v[132:135], v[214:217], v[76:79]
	v_mfma_f32_16x16x32_bf16 v[72:75], v[140:143], v[214:217], v[72:75]
	s_setprio 0
	s_setprio 1
	v_mfma_f32_16x16x32_bf16 v[112:115], v[144:147], v[160:163], v[112:115]
	v_mfma_f32_16x16x32_bf16 v[104:107], v[152:155], v[160:163], v[104:107]
	v_mfma_f32_16x16x32_bf16 v[100:103], v[144:147], v[184:187], v[100:103]
	v_mfma_f32_16x16x32_bf16 v[96:99], v[152:155], v[184:187], v[96:99]
	v_mfma_f32_16x16x32_bf16 v[84:87], v[144:147], v[192:195], v[84:87]
	v_mfma_f32_16x16x32_bf16 v[80:83], v[152:155], v[192:195], v[80:83]
	v_mfma_f32_16x16x32_bf16 v[68:71], v[144:147], v[210:213], v[68:71]
	v_mfma_f32_16x16x32_bf16 v[64:67], v[152:155], v[210:213], v[64:67]
	v_mfma_f32_16x16x32_bf16 v[112:115], v[148:151], v[164:167], v[112:115]
	v_mfma_f32_16x16x32_bf16 v[104:107], v[156:159], v[164:167], v[104:107]
	v_mfma_f32_16x16x32_bf16 v[100:103], v[148:151], v[188:191], v[100:103]
	v_mfma_f32_16x16x32_bf16 v[96:99], v[156:159], v[188:191], v[96:99]
	v_mfma_f32_16x16x32_bf16 v[84:87], v[148:151], v[206:209], v[84:87]
	v_mfma_f32_16x16x32_bf16 v[80:83], v[156:159], v[206:209], v[80:83]
	v_mfma_f32_16x16x32_bf16 v[68:71], v[148:151], v[214:217], v[68:71]
	v_mfma_f32_16x16x32_bf16 v[64:67], v[156:159], v[214:217], v[64:67]
	s_setprio 0
	s_barrier
	ds_read_b128 v[160:163], v204 offset:16384
	ds_read_b128 v[164:167], v204 offset:17408
	ds_read_b128 v[184:187], v204 offset:18432
	ds_read_b128 v[188:191], v204 offset:19456
	ds_read_b128 v[192:195], v204 offset:20480
	ds_read_b128 v[206:209], v204 offset:21504
	ds_read_b128 v[210:213], v204 offset:22528
	ds_read_b128 v[214:217], v204 offset:23552
	global_load_lds_dwordx4 v170, s[72:73]
	s_add_i32 m0, s88, 0x2000
	s_add_u32 s88, s72, 0x200000
	s_addc_u32 s89, s73, 0
	s_add_i32 s94, s83, s1
	global_load_lds_dwordx4 v174, s[72:73]
	s_mov_b32 m0, s94
	s_nop 0
	global_load_lds_dwordx4 v170, s[88:89]
	s_add_i32 m0, s94, 0x2000
	s_nop 0
	global_load_lds_dwordx4 v174, s[88:89]
	s_mov_b32 m0, s33
	s_nop 0
	global_load_lds_dwordx4 v168, s[74:75]
	s_mov_b32 m0, s35
	s_nop 0
	global_load_lds_dwordx4 v172, s[74:75]
	s_waitcnt vmcnt(8)
	s_waitcnt lgkmcnt(0)
	s_barrier
	s_setprio 1
	s_waitcnt lgkmcnt(0)
	v_mfma_f32_16x16x32_bf16 v[60:63], v[128:131], v[160:163], v[60:63]
	v_mfma_f32_16x16x32_bf16 v[56:59], v[136:139], v[160:163], v[56:59]
	v_mfma_f32_16x16x32_bf16 v[44:47], v[128:131], v[184:187], v[44:47]
	v_mfma_f32_16x16x32_bf16 v[40:43], v[136:139], v[184:187], v[40:43]
	v_mfma_f32_16x16x32_bf16 v[28:31], v[128:131], v[192:195], v[28:31]
	v_mfma_f32_16x16x32_bf16 v[24:27], v[136:139], v[192:195], v[24:27]
	v_mfma_f32_16x16x32_bf16 v[12:15], v[128:131], v[210:213], v[12:15]
	v_mfma_f32_16x16x32_bf16 v[8:11], v[136:139], v[210:213], v[8:11]
	v_mfma_f32_16x16x32_bf16 v[60:63], v[132:135], v[164:167], v[60:63]
	v_mfma_f32_16x16x32_bf16 v[56:59], v[140:143], v[164:167], v[56:59]
	v_mfma_f32_16x16x32_bf16 v[44:47], v[132:135], v[188:191], v[44:47]
	v_mfma_f32_16x16x32_bf16 v[40:43], v[140:143], v[188:191], v[40:43]
	v_mfma_f32_16x16x32_bf16 v[28:31], v[132:135], v[206:209], v[28:31]
	v_mfma_f32_16x16x32_bf16 v[24:27], v[140:143], v[206:209], v[24:27]
	v_mfma_f32_16x16x32_bf16 v[12:15], v[132:135], v[214:217], v[12:15]
	v_mfma_f32_16x16x32_bf16 v[8:11], v[140:143], v[214:217], v[8:11]
	s_setprio 0
	s_setprio 1
	v_mfma_f32_16x16x32_bf16 v[52:55], v[144:147], v[160:163], v[52:55]
	v_mfma_f32_16x16x32_bf16 v[48:51], v[152:155], v[160:163], v[48:51]
	v_mfma_f32_16x16x32_bf16 v[36:39], v[144:147], v[184:187], v[36:39]
	v_mfma_f32_16x16x32_bf16 v[32:35], v[152:155], v[184:187], v[32:35]
	v_mfma_f32_16x16x32_bf16 v[20:23], v[144:147], v[192:195], v[20:23]
	v_mfma_f32_16x16x32_bf16 v[16:19], v[152:155], v[192:195], v[16:19]
	v_mfma_f32_16x16x32_bf16 v[4:7], v[144:147], v[210:213], v[4:7]
	v_mfma_f32_16x16x32_bf16 v[0:3], v[152:155], v[210:213], v[0:3]
	v_mfma_f32_16x16x32_bf16 v[52:55], v[148:151], v[164:167], v[52:55]
	v_mfma_f32_16x16x32_bf16 v[48:51], v[156:159], v[164:167], v[48:51]
	v_mfma_f32_16x16x32_bf16 v[36:39], v[148:151], v[188:191], v[36:39]
	v_mfma_f32_16x16x32_bf16 v[32:35], v[156:159], v[188:191], v[32:35]
	v_mfma_f32_16x16x32_bf16 v[20:23], v[148:151], v[206:209], v[20:23]
	v_mfma_f32_16x16x32_bf16 v[16:19], v[156:159], v[206:209], v[16:19]
	v_mfma_f32_16x16x32_bf16 v[4:7], v[148:151], v[214:217], v[4:7]
	v_mfma_f32_16x16x32_bf16 v[0:3], v[156:159], v[214:217], v[0:3]
	s_setprio 0
	s_barrier
; #define PG8_STAGE(bufoff, gbase, voff) do { _Pragma("unroll") for (int _i = 0; _i < 2; ++_i) \
;         __builtin_amdgcn_global_load_lds((const unsigned*)((const char*)(gbase) + (voff)[_i]), (PG8_LAS unsigned*)(lds + (bufoff) + ldsw + _i * 8192), 16, 0, 0); } while (0)
; #define PG8_LDA(dst, b, h) do { _Pragma("unroll") for (int m = 0; m < 4; ++m) _Pragma("unroll") for (int k = 0; k < 2; ++k) dst[m][k] = *(const PG8_LAS bf16x8*)(lds + PG8_SA(b, h) + aoff + m * 2048 + k * 1024); } while (0)
; #define PG8_LDB(dst, b, h) do { _Pragma("unroll") for (int n = 0; n < 2; ++n) _Pragma("unroll") for (int k = 0; k < 2; ++k) dst[n][k] = *(const PG8_LAS bf16x8*)(lds + PG8_SB(b, h) + boff + n * 2048 + k * 1024); } while (0)
; #define PG8_MMA(ai, bj, At, Bt) do { __builtin_amdgcn_s_setprio(1); _Pragma("unroll") for (int m = 0; m < 4; ++m) _Pragma("unroll") for (int n = 0; n < 2; ++n) _Pragma("unroll") for (int k = 0; k < 2; ++k) \
;         acc[ai][bj][m][n] = __builtin_amdgcn_mfma_f32_16x16x32_bf16(Bt[n][k], At[m][k], acc[ai][bj][m][n], 0, 0, 0); __builtin_amdgcn_s_setprio(0); } while (0)
; #define PG8_WAIT_V(n) asm volatile("s_waitcnt vmcnt(" #n ")" ::: "memory")
; #define PG8_WAIT_L(n) asm volatile("s_waitcnt lgkmcnt(" #n ")" ::: "memory")
; #define PG8_BAR __builtin_amdgcn_s_barrier()
; #define PG8_SCHED __builtin_amdgcn_sched_barrier(0)
; template <class Epi, class Sched, bool ALIGN_EPI = false, bool SP2 = false>
; __device__ __forceinline__ void gemm_phase(PG8_LAS unsigned char* lds, const Gemm g, const Sched& S, const Epi& E) {
;     ...
;         for (int t = 0; t < nt; t += 2) {
;     ...
;             PG8_LDB(B0, 1, 0); PG8_LDB(B1, 1, 1); PG8_SCHED; PG8_LDA(At, 1, 0); PG8_STAGE(PG8_SA(0, 1), a2 + hstep, voffA);
;             PG8_WAIT_V(8); PG8_WAIT_L(0); PG8_BAR; PG8_MMA(0, 0, At, B0); PG8_MMA(0, 1, At, B1); PG8_BAR; PG8_SCHED;
;             PG8_LDA(At, 1, 1); PG8_STAGE(PG8_SB(1, 0), b3, voffB); PG8_STAGE(PG8_SB(1, 1), b3 + hstep, voffB); PG8_STAGE(PG8_SA(1, 0), a3, voffA);
;             PG8_WAIT_V(8); PG8_WAIT_L(0); PG8_BAR; PG8_MMA(1, 0, At, B0); PG8_MMA(1, 1, At, B1); PG8_BAR; PG8_SCHED;
	ds_read_b128 v[128:131], v218
	ds_read_b128 v[132:135], v218 offset:1024
	ds_read_b128 v[136:139], v218 offset:2048
	ds_read_b128 v[140:143], v218 offset:3072
	ds_read_b128 v[144:147], v219
	ds_read_b128 v[148:151], v219 offset:1024
	ds_read_b128 v[152:155], v219 offset:2048
	ds_read_b128 v[156:159], v219 offset:3072
	ds_read_b128 v[160:163], v204 offset:32768
	ds_read_b128 v[164:167], v204 offset:33792
	ds_read_b128 v[184:187], v204 offset:34816
	ds_read_b128 v[188:191], v204 offset:35840
	ds_read_b128 v[192:195], v204 offset:36864
	ds_read_b128 v[206:209], v204 offset:37888
	ds_read_b128 v[210:213], v204 offset:38912
	ds_read_b128 v[214:217], v204 offset:39936
	s_add_u32 s98, s74, 0x200000
	s_addc_u32 s99, s75, 0
	s_mov_b32 m0, s69
	s_add_u32 s100, s74, 0x80
	s_addc_u32 s101, s75, 0
	global_load_lds_dwordx4 v168, s[98:99]
	s_mov_b32 m0, s76
	s_nop 0
	global_load_lds_dwordx4 v172, s[98:99]
	s_add_i32 s88, 0, 0x18000
	s_add_i32 s89, 0, 0x1c000
	s_add_u32 s98, s72, 0x80
	s_addc_u32 s99, s73, 0
	s_add_i32 s74, s88, s1
	s_mov_b32 m0, s74
	s_waitcnt vmcnt(8)
	s_waitcnt lgkmcnt(0)
	s_barrier
	s_setprio 1
	s_waitcnt lgkmcnt(0)
	v_mfma_f32_16x16x32_bf16 v[124:127], v[128:131], v[160:163], v[124:127]
	v_mfma_f32_16x16x32_bf16 v[120:123], v[136:139], v[160:163], v[120:123]
	v_mfma_f32_16x16x32_bf16 v[116:119], v[128:131], v[184:187], v[116:119]
	v_mfma_f32_16x16x32_bf16 v[108:111], v[136:139], v[184:187], v[108:111]
	v_mfma_f32_16x16x32_bf16 v[92:95], v[128:131], v[192:195], v[92:95]
	v_mfma_f32_16x16x32_bf16 v[88:91], v[136:139], v[192:195], v[88:91]
	v_mfma_f32_16x16x32_bf16 v[76:79], v[128:131], v[210:213], v[76:79]
	v_mfma_f32_16x16x32_bf16 v[72:75], v[136:139], v[210:213], v[72:75]
	v_mfma_f32_16x16x32_bf16 v[124:127], v[132:135], v[164:167], v[124:127]
	v_mfma_f32_16x16x32_bf16 v[120:123], v[140:143], v[164:167], v[120:123]
	v_mfma_f32_16x16x32_bf16 v[116:119], v[132:135], v[188:191], v[116:119]
	v_mfma_f32_16x16x32_bf16 v[108:111], v[140:143], v[188:191], v[108:111]
	v_mfma_f32_16x16x32_bf16 v[92:95], v[132:135], v[206:209], v[92:95]
	v_mfma_f32_16x16x32_bf16 v[88:91], v[140:143], v[206:209], v[88:91]
	v_mfma_f32_16x16x32_bf16 v[76:79], v[132:135], v[214:217], v[76:79]
	v_mfma_f32_16x16x32_bf16 v[72:75], v[140:143], v[214:217], v[72:75]
	s_setprio 0
	s_setprio 1
	v_mfma_f32_16x16x32_bf16 v[112:115], v[144:147], v[160:163], v[112:115]
	v_mfma_f32_16x16x32_bf16 v[104:107], v[152:155], v[160:163], v[104:107]
	v_mfma_f32_16x16x32_bf16 v[100:103], v[144:147], v[184:187], v[100:103]
	v_mfma_f32_16x16x32_bf16 v[96:99], v[152:155], v[184:187], v[96:99]
	v_mfma_f32_16x16x32_bf16 v[84:87], v[144:147], v[192:195], v[84:87]
	v_mfma_f32_16x16x32_bf16 v[80:83], v[152:155], v[192:195], v[80:83]
	v_mfma_f32_16x16x32_bf16 v[68:71], v[144:147], v[210:213], v[68:71]
	v_mfma_f32_16x16x32_bf16 v[64:67], v[152:155], v[210:213], v[64:67]
	v_mfma_f32_16x16x32_bf16 v[112:115], v[148:151], v[164:167], v[112:115]
	v_mfma_f32_16x16x32_bf16 v[104:107], v[156:159], v[164:167], v[104:107]
	v_mfma_f32_16x16x32_bf16 v[100:103], v[148:151], v[188:191], v[100:103]
	v_mfma_f32_16x16x32_bf16 v[96:99], v[156:159], v[188:191], v[96:99]
	v_mfma_f32_16x16x32_bf16 v[84:87], v[148:151], v[206:209], v[84:87]
	v_mfma_f32_16x16x32_bf16 v[80:83], v[156:159], v[206:209], v[80:83]
	v_mfma_f32_16x16x32_bf16 v[68:71], v[148:151], v[214:217], v[68:71]
	v_mfma_f32_16x16x32_bf16 v[64:67], v[156:159], v[214:217], v[64:67]
	s_setprio 0
	s_barrier
	ds_read_b128 v[160:163], v204 offset:49152
	ds_read_b128 v[164:167], v204 offset:50176
	ds_read_b128 v[184:187], v204 offset:51200
	ds_read_b128 v[188:191], v204 offset:52224
	ds_read_b128 v[192:195], v204 offset:53248
	ds_read_b128 v[206:209], v204 offset:54272
	ds_read_b128 v[210:213], v204 offset:55296
	ds_read_b128 v[214:217], v204 offset:56320
	global_load_lds_dwordx4 v170, s[98:99]
	s_add_i32 m0, s74, 0x2000
	s_add_u32 s72, s72, 0x200080
	s_addc_u32 s73, s73, 0
	s_add_i32 s74, s89, s1
	global_load_lds_dwordx4 v174, s[98:99]
	s_mov_b32 m0, s74
	s_nop 0
	global_load_lds_dwordx4 v170, s[72:73]
	s_add_i32 m0, s74, 0x2000
	s_nop 0
	global_load_lds_dwordx4 v174, s[72:73]
	s_mov_b32 m0, s78
	s_nop 0
	global_load_lds_dwordx4 v168, s[100:101]
	s_mov_b32 m0, s79
	s_nop 0
	global_load_lds_dwordx4 v172, s[100:101]
	s_add_i32 s87, s87, 2
	s_add_u32 s70, s70, 0x100
	s_addc_u32 s71, s71, 0
	s_add_u32 s85, s85, 0x100
	s_addc_u32 s86, s86, 0
	s_cmpk_gt_u32 s87, 0x7d
	s_waitcnt vmcnt(8)
	s_waitcnt lgkmcnt(0)
	s_barrier
	s_setprio 1
	s_waitcnt lgkmcnt(0)
	v_mfma_f32_16x16x32_bf16 v[60:63], v[128:131], v[160:163], v[60:63]
	v_mfma_f32_16x16x32_bf16 v[56:59], v[136:139], v[160:163], v[56:59]
	v_mfma_f32_16x16x32_bf16 v[44:47], v[128:131], v[184:187], v[44:47]
	v_mfma_f32_16x16x32_bf16 v[40:43], v[136:139], v[184:187], v[40:43]
	v_mfma_f32_16x16x32_bf16 v[28:31], v[128:131], v[192:195], v[28:31]
	v_mfma_f32_16x16x32_bf16 v[24:27], v[136:139], v[192:195], v[24:27]
	v_mfma_f32_16x16x32_bf16 v[12:15], v[128:131], v[210:213], v[12:15]
	v_mfma_f32_16x16x32_bf16 v[8:11], v[136:139], v[210:213], v[8:11]
	v_mfma_f32_16x16x32_bf16 v[60:63], v[132:135], v[164:167], v[60:63]
	v_mfma_f32_16x16x32_bf16 v[56:59], v[140:143], v[164:167], v[56:59]
	v_mfma_f32_16x16x32_bf16 v[44:47], v[132:135], v[188:191], v[44:47]
	v_mfma_f32_16x16x32_bf16 v[40:43], v[140:143], v[188:191], v[40:43]
	v_mfma_f32_16x16x32_bf16 v[28:31], v[132:135], v[206:209], v[28:31]
	v_mfma_f32_16x16x32_bf16 v[24:27], v[140:143], v[206:209], v[24:27]
	v_mfma_f32_16x16x32_bf16 v[12:15], v[132:135], v[214:217], v[12:15]
	v_mfma_f32_16x16x32_bf16 v[8:11], v[140:143], v[214:217], v[8:11]
	s_setprio 0
	s_setprio 1
	v_mfma_f32_16x16x32_bf16 v[52:55], v[144:147], v[160:163], v[52:55]
	v_mfma_f32_16x16x32_bf16 v[48:51], v[152:155], v[160:163], v[48:51]
	v_mfma_f32_16x16x32_bf16 v[36:39], v[144:147], v[184:187], v[36:39]
	v_mfma_f32_16x16x32_bf16 v[32:35], v[152:155], v[184:187], v[32:35]
	v_mfma_f32_16x16x32_bf16 v[20:23], v[144:147], v[192:195], v[20:23]
	v_mfma_f32_16x16x32_bf16 v[16:19], v[152:155], v[192:195], v[16:19]
	v_mfma_f32_16x16x32_bf16 v[4:7], v[144:147], v[210:213], v[4:7]
	v_mfma_f32_16x16x32_bf16 v[0:3], v[152:155], v[210:213], v[0:3]
	v_mfma_f32_16x16x32_bf16 v[52:55], v[148:151], v[164:167], v[52:55]
	v_mfma_f32_16x16x32_bf16 v[48:51], v[156:159], v[164:167], v[48:51]
	v_mfma_f32_16x16x32_bf16 v[36:39], v[148:151], v[188:191], v[36:39]
	v_mfma_f32_16x16x32_bf16 v[32:35], v[156:159], v[188:191], v[32:35]
	v_mfma_f32_16x16x32_bf16 v[20:23], v[148:151], v[206:209], v[20:23]
	v_mfma_f32_16x16x32_bf16 v[16:19], v[156:159], v[206:209], v[16:19]
	v_mfma_f32_16x16x32_bf16 v[4:7], v[148:151], v[214:217], v[4:7]
	v_mfma_f32_16x16x32_bf16 v[0:3], v[156:159], v[214:217], v[0:3]
	s_setprio 0
	s_barrier
	s_cbranch_scc0 .LBB0_452
	s_and_b64 vcc, exec, s[36:37]
	s_cbranch_vccz .LBB0_455
	s_barrier

; #define PG8_STAGE(bufoff, gbase, voff) do { _Pragma("unroll") for (int _i = 0; _i < 2; ++_i) \
;         __builtin_amdgcn_global_load_lds((const unsigned*)((const char*)(gbase) + (voff)[_i]), (PG8_LAS unsigned*)(lds + (bufoff) + ldsw + _i * 8192), 16, 0, 0); } while (0)
; #define PG8_LDA(dst, b, h) do { _Pragma("unroll") for (int m = 0; m < 4; ++m) _Pragma("unroll") for (int k = 0; k < 2; ++k) dst[m][k] = *(const PG8_LAS bf16x8*)(lds + PG8_SA(b, h) + aoff + m * 2048 + k * 1024); } while (0)
; #define PG8_LDB(dst, b, h) do { _Pragma("unroll") for (int n = 0; n < 2; ++n) _Pragma("unroll") for (int k = 0; k < 2; ++k) dst[n][k] = *(const PG8_LAS bf16x8*)(lds + PG8_SB(b, h) + boff + n * 2048 + k * 1024); } while (0)
; #define PG8_MMA(ai, bj, At, Bt) do { __builtin_amdgcn_s_setprio(1); _Pragma("unroll") for (int m = 0; m < 4; ++m) _Pragma("unroll") for (int n = 0; n < 2; ++n) _Pragma("unroll") for (int k = 0; k < 2; ++k) \
;         acc[ai][bj][m][n] = __builtin_amdgcn_mfma_f32_16x16x32_bf16(Bt[n][k], At[m][k], acc[ai][bj][m][n], 0, 0, 0); __builtin_amdgcn_s_setprio(0); } while (0)
; #define PG8_WAIT_V(n) asm volatile("s_waitcnt vmcnt(" #n ")" ::: "memory")
; #define PG8_WAIT_L(n) asm volatile("s_waitcnt lgkmcnt(" #n ")" ::: "memory")
; template <class Epi, class Sched, bool ALIGN_EPI = false, bool SP2 = false>
; __device__ __forceinline__ void gemm_phase(PG8_LAS unsigned char* lds, const Gemm g, const Sched& S, const Epi& E) {
;     ...
;             const bool last = (t == nt - 2);
;             const char* a1 = cA + (size_t)(t + 1) * kstep;
;             const char* a2 = last ? nA : cA + (size_t)(t + 2) * kstep; const char* b2 = last ? nB : cB + (size_t)(t + 2) * kstep;
;             const char* a3 = a2 + kstep; const char* b3 = b2 + kstep;
;             if (last && has_next) S.a_ready(nxt);
;             if constexpr (SP2) {
;             PG8_LDB(B0, 0, 0); PG8_LDB(B1, 0, 1); PG8_SCHED; PG8_LDA(At, 0, 0); PG8_STAGE(PG8_SA(1, 1), a1 + hstep, voffA);
;             PG8_WAIT_V(8); PG8_WAIT_L(0); PG8_BAR; PG8_MMA(0, 0, At, B0); PG8_MMA(0, 1, At, B1); PG8_BAR; PG8_SCHED;
;             PG8_LDA(At, 0, 1); PG8_STAGE(PG8_SB(0, 0), b2, voffB); PG8_STAGE(PG8_SB(0, 1), b2 + hstep, voffB); PG8_STAGE(PG8_SA(0, 0), a2, voffA);
;             PG8_WAIT_V(8); PG8_WAIT_L(0); PG8_BAR; PG8_MMA(1, 0, At, B0); PG8_MMA(1, 1, At, B1); PG8_BAR; PG8_SCHED;
.LBB0_528:
	ds_read_b128 v[152:155], v149
	ds_read_b128 v[156:159], v149 offset:1024
	ds_read_b128 v[160:163], v149 offset:2048
	ds_read_b128 v[164:167], v149 offset:3072
	ds_read_b128 v[168:171], v150
	ds_read_b128 v[172:175], v150 offset:1024
	ds_read_b128 v[176:179], v150 offset:2048
	ds_read_b128 v[180:183], v150 offset:3072
	s_add_i32 m0, s14, 0xc000
	ds_read_b128 v[184:187], v151
	ds_read_b128 v[188:191], v151 offset:1024
	ds_read_b128 v[192:195], v151 offset:2048
	ds_read_b128 v[200:203], v151 offset:3072
	ds_read_b128 v[204:207], v151 offset:4096
	ds_read_b128 v[208:211], v151 offset:5120
	ds_read_b128 v[212:215], v151 offset:6144
	ds_read_b128 v[216:219], v151 offset:7168
	global_load_lds_dwordx4 v136, s[70:71]
	s_add_i32 m0, s14, 0xe000
	s_nop 0
	global_load_lds_dwordx4 v138, s[70:71]
	s_add_u32 s72, s70, 0xfff80080
	s_addc_u32 s73, s71, -1
	s_cmp_eq_u32 s86, 28
	s_cselect_b32 s75, s25, s73
	s_cselect_b32 s74, s63, s72
	s_cselect_b32 s73, s61, s85
	s_cselect_b32 s72, s83, s84
	s_add_i32 s87, s80, s1
	s_mov_b32 m0, s87
	s_waitcnt vmcnt(8)
	s_waitcnt lgkmcnt(0)
	s_barrier
	s_setprio 1
	s_waitcnt lgkmcnt(0)
	v_mfma_f32_16x16x32_bf16 v[124:127], v[152:155], v[184:187], v[124:127]
	v_mfma_f32_16x16x32_bf16 v[120:123], v[160:163], v[184:187], v[120:123]
	v_mfma_f32_16x16x32_bf16 v[108:111], v[152:155], v[192:195], v[108:111]
	v_mfma_f32_16x16x32_bf16 v[104:107], v[160:163], v[192:195], v[104:107]
	v_mfma_f32_16x16x32_bf16 v[92:95], v[152:155], v[204:207], v[92:95]
	v_mfma_f32_16x16x32_bf16 v[88:91], v[160:163], v[204:207], v[88:91]
	v_mfma_f32_16x16x32_bf16 v[76:79], v[152:155], v[212:215], v[76:79]
	v_mfma_f32_16x16x32_bf16 v[72:75], v[160:163], v[212:215], v[72:75]
	v_mfma_f32_16x16x32_bf16 v[124:127], v[156:159], v[188:191], v[124:127]
	v_mfma_f32_16x16x32_bf16 v[120:123], v[164:167], v[188:191], v[120:123]
	v_mfma_f32_16x16x32_bf16 v[108:111], v[156:159], v[200:203], v[108:111]
	v_mfma_f32_16x16x32_bf16 v[104:107], v[164:167], v[200:203], v[104:107]
	v_mfma_f32_16x16x32_bf16 v[92:95], v[156:159], v[208:211], v[92:95]
	v_mfma_f32_16x16x32_bf16 v[88:91], v[164:167], v[208:211], v[88:91]
	v_mfma_f32_16x16x32_bf16 v[76:79], v[156:159], v[216:219], v[76:79]
	v_mfma_f32_16x16x32_bf16 v[72:75], v[164:167], v[216:219], v[72:75]
	s_setprio 0
	s_setprio 1
	v_mfma_f32_16x16x32_bf16 v[116:119], v[168:171], v[184:187], v[116:119]
	v_mfma_f32_16x16x32_bf16 v[112:115], v[176:179], v[184:187], v[112:115]
	v_mfma_f32_16x16x32_bf16 v[100:103], v[168:171], v[192:195], v[100:103]
	v_mfma_f32_16x16x32_bf16 v[96:99], v[176:179], v[192:195], v[96:99]
	v_mfma_f32_16x16x32_bf16 v[84:87], v[168:171], v[204:207], v[84:87]
	v_mfma_f32_16x16x32_bf16 v[80:83], v[176:179], v[204:207], v[80:83]
	v_mfma_f32_16x16x32_bf16 v[68:71], v[168:171], v[212:215], v[68:71]
	v_mfma_f32_16x16x32_bf16 v[64:67], v[176:179], v[212:215], v[64:67]
	v_mfma_f32_16x16x32_bf16 v[116:119], v[172:175], v[188:191], v[116:119]
	v_mfma_f32_16x16x32_bf16 v[112:115], v[180:183], v[188:191], v[112:115]
	v_mfma_f32_16x16x32_bf16 v[100:103], v[172:175], v[200:203], v[100:103]
	v_mfma_f32_16x16x32_bf16 v[96:99], v[180:183], v[200:203], v[96:99]
	v_mfma_f32_16x16x32_bf16 v[84:87], v[172:175], v[208:211], v[84:87]
	v_mfma_f32_16x16x32_bf16 v[80:83], v[180:183], v[208:211], v[80:83]
	v_mfma_f32_16x16x32_bf16 v[68:71], v[172:175], v[216:219], v[68:71]
	v_mfma_f32_16x16x32_bf16 v[64:67], v[180:183], v[216:219], v[64:67]
	s_setprio 0
	s_barrier
	ds_read_b128 v[184:187], v151 offset:16384
	ds_read_b128 v[188:191], v151 offset:17408
	ds_read_b128 v[192:195], v151 offset:18432
	ds_read_b128 v[200:203], v151 offset:19456
	ds_read_b128 v[204:207], v151 offset:20480
	ds_read_b128 v[208:211], v151 offset:21504
	ds_read_b128 v[212:215], v151 offset:22528
	ds_read_b128 v[216:219], v151 offset:23552
	global_load_lds_dwordx4 v130, s[72:73]
	s_add_i32 m0, s87, 0x2000
	s_add_u32 s88, s72, 0x80000
	s_addc_u32 s89, s73, 0
	s_add_i32 s87, s81, s1
	global_load_lds_dwordx4 v134, s[72:73]
	s_mov_b32 m0, s87
	s_nop 0
	global_load_lds_dwordx4 v130, s[88:89]
	s_add_i32 m0, s87, 0x2000
	s_nop 0
	global_load_lds_dwordx4 v134, s[88:89]
	s_mov_b32 m0, s14
	s_nop 0
	global_load_lds_dwordx4 v128, s[74:75]
	s_mov_b32 m0, s15
	s_nop 0
	global_load_lds_dwordx4 v132, s[74:75]
	s_waitcnt vmcnt(8)
	s_waitcnt lgkmcnt(0)
	s_barrier
	s_setprio 1
	s_waitcnt lgkmcnt(0)
	v_mfma_f32_16x16x32_bf16 v[60:63], v[152:155], v[184:187], v[60:63]
	v_mfma_f32_16x16x32_bf16 v[56:59], v[160:163], v[184:187], v[56:59]
	v_mfma_f32_16x16x32_bf16 v[44:47], v[152:155], v[192:195], v[44:47]
	v_mfma_f32_16x16x32_bf16 v[40:43], v[160:163], v[192:195], v[40:43]
	v_mfma_f32_16x16x32_bf16 v[28:31], v[152:155], v[204:207], v[28:31]
	v_mfma_f32_16x16x32_bf16 v[24:27], v[160:163], v[204:207], v[24:27]
	v_mfma_f32_16x16x32_bf16 v[12:15], v[152:155], v[212:215], v[12:15]
	v_mfma_f32_16x16x32_bf16 v[8:11], v[160:163], v[212:215], v[8:11]
	v_mfma_f32_16x16x32_bf16 v[60:63], v[156:159], v[188:191], v[60:63]
	v_mfma_f32_16x16x32_bf16 v[56:59], v[164:167], v[188:191], v[56:59]
	v_mfma_f32_16x16x32_bf16 v[44:47], v[156:159], v[200:203], v[44:47]
	v_mfma_f32_16x16x32_bf16 v[40:43], v[164:167], v[200:203], v[40:43]
	v_mfma_f32_16x16x32_bf16 v[28:31], v[156:159], v[208:211], v[28:31]
	v_mfma_f32_16x16x32_bf16 v[24:27], v[164:167], v[208:211], v[24:27]
	v_mfma_f32_16x16x32_bf16 v[12:15], v[156:159], v[216:219], v[12:15]
	v_mfma_f32_16x16x32_bf16 v[8:11], v[164:167], v[216:219], v[8:11]
	s_setprio 0
	s_setprio 1
	v_mfma_f32_16x16x32_bf16 v[52:55], v[168:171], v[184:187], v[52:55]
	v_mfma_f32_16x16x32_bf16 v[48:51], v[176:179], v[184:187], v[48:51]
	v_mfma_f32_16x16x32_bf16 v[36:39], v[168:171], v[192:195], v[36:39]
	v_mfma_f32_16x16x32_bf16 v[32:35], v[176:179], v[192:195], v[32:35]
	v_mfma_f32_16x16x32_bf16 v[20:23], v[168:171], v[204:207], v[20:23]
	v_mfma_f32_16x16x32_bf16 v[16:19], v[176:179], v[204:207], v[16:19]
	v_mfma_f32_16x16x32_bf16 v[4:7], v[168:171], v[212:215], v[4:7]
	v_mfma_f32_16x16x32_bf16 v[0:3], v[176:179], v[212:215], v[0:3]
	v_mfma_f32_16x16x32_bf16 v[52:55], v[172:175], v[188:191], v[52:55]
	v_mfma_f32_16x16x32_bf16 v[48:51], v[180:183], v[188:191], v[48:51]
	v_mfma_f32_16x16x32_bf16 v[36:39], v[172:175], v[200:203], v[36:39]
	v_mfma_f32_16x16x32_bf16 v[32:35], v[180:183], v[200:203], v[32:35]
	v_mfma_f32_16x16x32_bf16 v[20:23], v[172:175], v[208:211], v[20:23]
	v_mfma_f32_16x16x32_bf16 v[16:19], v[180:183], v[208:211], v[16:19]
	v_mfma_f32_16x16x32_bf16 v[4:7], v[172:175], v[216:219], v[4:7]
	v_mfma_f32_16x16x32_bf16 v[0:3], v[180:183], v[216:219], v[0:3]
	s_setprio 0
	s_barrier
; #define PG8_STAGE(bufoff, gbase, voff) do { _Pragma("unroll") for (int _i = 0; _i < 2; ++_i) \
;         __builtin_amdgcn_global_load_lds((const unsigned*)((const char*)(gbase) + (voff)[_i]), (PG8_LAS unsigned*)(lds + (bufoff) + ldsw + _i * 8192), 16, 0, 0); } while (0)
; #define PG8_LDA(dst, b, h) do { _Pragma("unroll") for (int m = 0; m < 4; ++m) _Pragma("unroll") for (int k = 0; k < 2; ++k) dst[m][k] = *(const PG8_LAS bf16x8*)(lds + PG8_SA(b, h) + aoff + m * 2048 + k * 1024); } while (0)
; #define PG8_LDB(dst, b, h) do { _Pragma("unroll") for (int n = 0; n < 2; ++n) _Pragma("unroll") for (int k = 0; k < 2; ++k) dst[n][k] = *(const PG8_LAS bf16x8*)(lds + PG8_SB(b, h) + boff + n * 2048 + k * 1024); } while (0)
; #define PG8_MMA(ai, bj, At, Bt) do { __builtin_amdgcn_s_setprio(1); _Pragma("unroll") for (int m = 0; m < 4; ++m) _Pragma("unroll") for (int n = 0; n < 2; ++n) _Pragma("unroll") for (int k = 0; k < 2; ++k) \
;         acc[ai][bj][m][n] = __builtin_amdgcn_mfma_f32_16x16x32_bf16(Bt[n][k], At[m][k], acc[ai][bj][m][n], 0, 0, 0); __builtin_amdgcn_s_setprio(0); } while (0)
; #define PG8_WAIT_V(n) asm volatile("s_waitcnt vmcnt(" #n ")" ::: "memory")
; #define PG8_WAIT_L(n) asm volatile("s_waitcnt lgkmcnt(" #n ")" ::: "memory")
; #define PG8_BAR __builtin_amdgcn_s_barrier()
; #define PG8_SCHED __builtin_amdgcn_sched_barrier(0)
; template <class Epi, class Sched, bool ALIGN_EPI = false, bool SP2 = false>
; __device__ __forceinline__ void gemm_phase(PG8_LAS unsigned char* lds, const Gemm g, const Sched& S, const Epi& E) {
;     ...
;         for (int t = 0; t < nt; t += 2) {
;     ...
;             PG8_LDB(B0, 1, 0); PG8_LDB(B1, 1, 1); PG8_SCHED; PG8_LDA(At, 1, 0); PG8_STAGE(PG8_SA(0, 1), a2 + hstep, voffA);
;             PG8_WAIT_V(8); PG8_WAIT_L(0); PG8_BAR; PG8_MMA(0, 0, At, B0); PG8_MMA(0, 1, At, B1); PG8_BAR; PG8_SCHED;
;             PG8_LDA(At, 1, 1); PG8_STAGE(PG8_SB(1, 0), b3, voffB); PG8_STAGE(PG8_SB(1, 1), b3 + hstep, voffB); PG8_STAGE(PG8_SA(1, 0), a3, voffA);
;             PG8_WAIT_V(8); PG8_WAIT_L(0); PG8_BAR; PG8_MMA(1, 0, At, B0); PG8_MMA(1, 1, At, B1); PG8_BAR; PG8_SCHED;
	ds_read_b128 v[152:155], v196
	ds_read_b128 v[156:159], v196 offset:1024
	ds_read_b128 v[160:163], v196 offset:2048
	ds_read_b128 v[164:167], v196 offset:3072
	ds_read_b128 v[168:171], v197
	ds_read_b128 v[172:175], v197 offset:1024
	ds_read_b128 v[176:179], v197 offset:2048
	ds_read_b128 v[180:183], v197 offset:3072
	ds_read_b128 v[184:187], v151 offset:32768
	ds_read_b128 v[188:191], v151 offset:33792
	ds_read_b128 v[192:195], v151 offset:34816
	ds_read_b128 v[200:203], v151 offset:35840
	ds_read_b128 v[204:207], v151 offset:36864
	ds_read_b128 v[208:211], v151 offset:37888
	ds_read_b128 v[212:215], v151 offset:38912
	ds_read_b128 v[216:219], v151 offset:39936
	s_add_u32 s98, s74, 0x80000
	s_addc_u32 s99, s75, 0
	s_mov_b32 m0, s33
	s_add_u32 s100, s74, 0x80
	s_addc_u32 s101, s75, 0
	global_load_lds_dwordx4 v128, s[98:99]
	s_mov_b32 m0, s35
	s_nop 0
	global_load_lds_dwordx4 v132, s[98:99]
	s_add_i32 s87, 0, 0x18000
	s_add_i32 s88, 0, 0x1c000
	s_add_u32 s98, s72, 0x80
	s_addc_u32 s99, s73, 0
	s_add_i32 s74, s87, s1
	s_mov_b32 m0, s74
	s_waitcnt vmcnt(8)
	s_waitcnt lgkmcnt(0)
	s_barrier
	s_setprio 1
	s_waitcnt lgkmcnt(0)
	v_mfma_f32_16x16x32_bf16 v[124:127], v[152:155], v[184:187], v[124:127]
	v_mfma_f32_16x16x32_bf16 v[120:123], v[160:163], v[184:187], v[120:123]
	v_mfma_f32_16x16x32_bf16 v[108:111], v[152:155], v[192:195], v[108:111]
	v_mfma_f32_16x16x32_bf16 v[104:107], v[160:163], v[192:195], v[104:107]
	v_mfma_f32_16x16x32_bf16 v[92:95], v[152:155], v[204:207], v[92:95]
	v_mfma_f32_16x16x32_bf16 v[88:91], v[160:163], v[204:207], v[88:91]
	v_mfma_f32_16x16x32_bf16 v[76:79], v[152:155], v[212:215], v[76:79]
	v_mfma_f32_16x16x32_bf16 v[72:75], v[160:163], v[212:215], v[72:75]
	v_mfma_f32_16x16x32_bf16 v[124:127], v[156:159], v[188:191], v[124:127]
	v_mfma_f32_16x16x32_bf16 v[120:123], v[164:167], v[188:191], v[120:123]
	v_mfma_f32_16x16x32_bf16 v[108:111], v[156:159], v[200:203], v[108:111]
	v_mfma_f32_16x16x32_bf16 v[104:107], v[164:167], v[200:203], v[104:107]
	v_mfma_f32_16x16x32_bf16 v[92:95], v[156:159], v[208:211], v[92:95]
	v_mfma_f32_16x16x32_bf16 v[88:91], v[164:167], v[208:211], v[88:91]
	v_mfma_f32_16x16x32_bf16 v[76:79], v[156:159], v[216:219], v[76:79]
	v_mfma_f32_16x16x32_bf16 v[72:75], v[164:167], v[216:219], v[72:75]
	s_setprio 0
	s_setprio 1
	v_mfma_f32_16x16x32_bf16 v[116:119], v[168:171], v[184:187], v[116:119]
	v_mfma_f32_16x16x32_bf16 v[112:115], v[176:179], v[184:187], v[112:115]
	v_mfma_f32_16x16x32_bf16 v[100:103], v[168:171], v[192:195], v[100:103]
	v_mfma_f32_16x16x32_bf16 v[96:99], v[176:179], v[192:195], v[96:99]
	v_mfma_f32_16x16x32_bf16 v[84:87], v[168:171], v[204:207], v[84:87]
	v_mfma_f32_16x16x32_bf16 v[80:83], v[176:179], v[204:207], v[80:83]
	v_mfma_f32_16x16x32_bf16 v[68:71], v[168:171], v[212:215], v[68:71]
	v_mfma_f32_16x16x32_bf16 v[64:67], v[176:179], v[212:215], v[64:67]
	v_mfma_f32_16x16x32_bf16 v[116:119], v[172:175], v[188:191], v[116:119]
	v_mfma_f32_16x16x32_bf16 v[112:115], v[180:183], v[188:191], v[112:115]
	v_mfma_f32_16x16x32_bf16 v[100:103], v[172:175], v[200:203], v[100:103]
	v_mfma_f32_16x16x32_bf16 v[96:99], v[180:183], v[200:203], v[96:99]
	v_mfma_f32_16x16x32_bf16 v[84:87], v[172:175], v[208:211], v[84:87]
	v_mfma_f32_16x16x32_bf16 v[80:83], v[180:183], v[208:211], v[80:83]
	v_mfma_f32_16x16x32_bf16 v[68:71], v[172:175], v[216:219], v[68:71]
	v_mfma_f32_16x16x32_bf16 v[64:67], v[180:183], v[216:219], v[64:67]
	s_setprio 0
	s_barrier
	ds_read_b128 v[184:187], v151 offset:49152
	ds_read_b128 v[188:191], v151 offset:50176
	ds_read_b128 v[192:195], v151 offset:51200
	ds_read_b128 v[200:203], v151 offset:52224
	ds_read_b128 v[204:207], v151 offset:53248
	ds_read_b128 v[208:211], v151 offset:54272
	ds_read_b128 v[212:215], v151 offset:55296
	ds_read_b128 v[216:219], v151 offset:56320
	global_load_lds_dwordx4 v130, s[98:99]
	s_add_i32 m0, s74, 0x2000
	s_add_u32 s72, s72, 0x80080
	s_addc_u32 s73, s73, 0
	s_add_i32 s74, s88, s1
	global_load_lds_dwordx4 v134, s[98:99]
	s_mov_b32 m0, s74
	s_nop 0
	global_load_lds_dwordx4 v130, s[72:73]
	s_add_i32 m0, s74, 0x2000
	s_nop 0
	global_load_lds_dwordx4 v134, s[72:73]
	s_mov_b32 m0, s76
	s_nop 0
	global_load_lds_dwordx4 v128, s[100:101]
	s_mov_b32 m0, s77
	s_nop 0
	global_load_lds_dwordx4 v132, s[100:101]
	s_add_i32 s86, s86, 2
	s_add_u32 s70, s70, 0x100
	s_addc_u32 s71, s71, 0
	s_add_u32 s84, s84, 0x100
	s_addc_u32 s85, s85, 0
	s_cmp_gt_u32 s86, 29
	s_waitcnt vmcnt(8)
	s_waitcnt lgkmcnt(0)
	s_barrier
	s_setprio 1
	s_waitcnt lgkmcnt(0)
	v_mfma_f32_16x16x32_bf16 v[60:63], v[152:155], v[184:187], v[60:63]
	v_mfma_f32_16x16x32_bf16 v[56:59], v[160:163], v[184:187], v[56:59]
	v_mfma_f32_16x16x32_bf16 v[44:47], v[152:155], v[192:195], v[44:47]
	v_mfma_f32_16x16x32_bf16 v[40:43], v[160:163], v[192:195], v[40:43]
	v_mfma_f32_16x16x32_bf16 v[28:31], v[152:155], v[204:207], v[28:31]
	v_mfma_f32_16x16x32_bf16 v[24:27], v[160:163], v[204:207], v[24:27]
	v_mfma_f32_16x16x32_bf16 v[12:15], v[152:155], v[212:215], v[12:15]
	v_mfma_f32_16x16x32_bf16 v[8:11], v[160:163], v[212:215], v[8:11]
	v_mfma_f32_16x16x32_bf16 v[60:63], v[156:159], v[188:191], v[60:63]
	v_mfma_f32_16x16x32_bf16 v[56:59], v[164:167], v[188:191], v[56:59]
	v_mfma_f32_16x16x32_bf16 v[44:47], v[156:159], v[200:203], v[44:47]
	v_mfma_f32_16x16x32_bf16 v[40:43], v[164:167], v[200:203], v[40:43]
	v_mfma_f32_16x16x32_bf16 v[28:31], v[156:159], v[208:211], v[28:31]
	v_mfma_f32_16x16x32_bf16 v[24:27], v[164:167], v[208:211], v[24:27]
	v_mfma_f32_16x16x32_bf16 v[12:15], v[156:159], v[216:219], v[12:15]
	v_mfma_f32_16x16x32_bf16 v[8:11], v[164:167], v[216:219], v[8:11]
	s_setprio 0
	s_setprio 1
	v_mfma_f32_16x16x32_bf16 v[52:55], v[168:171], v[184:187], v[52:55]
	v_mfma_f32_16x16x32_bf16 v[48:51], v[176:179], v[184:187], v[48:51]
	v_mfma_f32_16x16x32_bf16 v[36:39], v[168:171], v[192:195], v[36:39]
	v_mfma_f32_16x16x32_bf16 v[32:35], v[176:179], v[192:195], v[32:35]
	v_mfma_f32_16x16x32_bf16 v[20:23], v[168:171], v[204:207], v[20:23]
	v_mfma_f32_16x16x32_bf16 v[16:19], v[176:179], v[204:207], v[16:19]
	v_mfma_f32_16x16x32_bf16 v[4:7], v[168:171], v[212:215], v[4:7]
	v_mfma_f32_16x16x32_bf16 v[0:3], v[176:179], v[212:215], v[0:3]
	v_mfma_f32_16x16x32_bf16 v[52:55], v[172:175], v[188:191], v[52:55]
	v_mfma_f32_16x16x32_bf16 v[48:51], v[180:183], v[188:191], v[48:51]
	v_mfma_f32_16x16x32_bf16 v[36:39], v[172:175], v[200:203], v[36:39]
	v_mfma_f32_16x16x32_bf16 v[32:35], v[180:183], v[200:203], v[32:35]
	v_mfma_f32_16x16x32_bf16 v[20:23], v[172:175], v[208:211], v[20:23]
	v_mfma_f32_16x16x32_bf16 v[16:19], v[180:183], v[208:211], v[16:19]
	v_mfma_f32_16x16x32_bf16 v[4:7], v[172:175], v[216:219], v[4:7]
	v_mfma_f32_16x16x32_bf16 v[0:3], v[180:183], v[216:219], v[0:3]
	s_setprio 0
	s_barrier
	s_cbranch_scc0 .LBB0_528
	s_and_b64 vcc, exec, s[44:45]
	s_cbranch_vccz .LBB0_531
	s_barrier

; #define PG8_STAGE(bufoff, gbase, voff) do { _Pragma("unroll") for (int _i = 0; _i < 2; ++_i) \
;         __builtin_amdgcn_global_load_lds((const unsigned*)((const char*)(gbase) + (voff)[_i]), (PG8_LAS unsigned*)(lds + (bufoff) + ldsw + _i * 8192), 16, 0, 0); } while (0)
; #define PG8_LDA(dst, b, h) do { _Pragma("unroll") for (int m = 0; m < 4; ++m) _Pragma("unroll") for (int k = 0; k < 2; ++k) dst[m][k] = *(const PG8_LAS bf16x8*)(lds + PG8_SA(b, h) + aoff + m * 2048 + k * 1024); } while (0)
; #define PG8_LDB(dst, b, h) do { _Pragma("unroll") for (int n = 0; n < 2; ++n) _Pragma("unroll") for (int k = 0; k < 2; ++k) dst[n][k] = *(const PG8_LAS bf16x8*)(lds + PG8_SB(b, h) + boff + n * 2048 + k * 1024); } while (0)
; #define PG8_MMA(ai, bj, At, Bt) do { __builtin_amdgcn_s_setprio(1); _Pragma("unroll") for (int m = 0; m < 4; ++m) _Pragma("unroll") for (int n = 0; n < 2; ++n) _Pragma("unroll") for (int k = 0; k < 2; ++k) \
;         acc[ai][bj][m][n] = __builtin_amdgcn_mfma_f32_16x16x32_bf16(Bt[n][k], At[m][k], acc[ai][bj][m][n], 0, 0, 0); __builtin_amdgcn_s_setprio(0); } while (0)
; #define PG8_WAIT_V(n) asm volatile("s_waitcnt vmcnt(" #n ")" ::: "memory")
; #define PG8_WAIT_L(n) asm volatile("s_waitcnt lgkmcnt(" #n ")" ::: "memory")
; template <class Epi, class Sched, bool ALIGN_EPI = false, bool SP2 = false>
; __device__ __forceinline__ void gemm_phase(PG8_LAS unsigned char* lds, const Gemm g, const Sched& S, const Epi& E) {
;     ...
;             const bool last = (t == nt - 2);
;             const char* a1 = cA + (size_t)(t + 1) * kstep;
;             const char* a2 = last ? nA : cA + (size_t)(t + 2) * kstep; const char* b2 = last ? nB : cB + (size_t)(t + 2) * kstep;
;             const char* a3 = a2 + kstep; const char* b3 = b2 + kstep;
;             if (last && has_next) S.a_ready(nxt);
;             if constexpr (SP2) {
;             PG8_LDB(B0, 0, 0); PG8_LDB(B1, 0, 1); PG8_SCHED; PG8_LDA(At, 0, 0); PG8_STAGE(PG8_SA(1, 1), a1 + hstep, voffA);
;             PG8_WAIT_V(8); PG8_WAIT_L(0); PG8_BAR; PG8_MMA(0, 0, At, B0); PG8_MMA(0, 1, At, B1); PG8_BAR; PG8_SCHED;
;             PG8_LDA(At, 0, 1); PG8_STAGE(PG8_SB(0, 0), b2, voffB); PG8_STAGE(PG8_SB(0, 1), b2 + hstep, voffB); PG8_STAGE(PG8_SA(0, 0), a2, voffA);
;             PG8_WAIT_V(8); PG8_WAIT_L(0); PG8_BAR; PG8_MMA(1, 0, At, B0); PG8_MMA(1, 1, At, B1); PG8_BAR; PG8_SCHED;
.LBB0_604:
	ds_read_b128 v[128:131], v202
	ds_read_b128 v[132:135], v202 offset:1024
	ds_read_b128 v[136:139], v202 offset:2048
	ds_read_b128 v[140:143], v202 offset:3072
	ds_read_b128 v[144:147], v203
	ds_read_b128 v[148:151], v203 offset:1024
	ds_read_b128 v[152:155], v203 offset:2048
	ds_read_b128 v[156:159], v203 offset:3072
	s_add_i32 m0, s4, 0xc000
	ds_read_b128 v[160:163], v204
	ds_read_b128 v[164:167], v204 offset:1024
	ds_read_b128 v[184:187], v204 offset:2048
	ds_read_b128 v[188:191], v204 offset:3072
	ds_read_b128 v[192:195], v204 offset:4096
	ds_read_b128 v[206:209], v204 offset:5120
	ds_read_b128 v[210:213], v204 offset:6144
	ds_read_b128 v[214:217], v204 offset:7168
	global_load_lds_dwordx4 v176, s[72:73]
	s_add_i32 m0, s4, 0xe000
	s_nop 0
	global_load_lds_dwordx4 v178, s[72:73]
	s_add_u32 s74, s72, 0xffe00080
	s_addc_u32 s75, s73, -1
	s_cmpk_eq_i32 s85, 0x7c
	s_cselect_b32 s77, s25, s75
	s_cselect_b32 s76, s65, s74
	s_cselect_b32 s75, s63, s84
	s_cselect_b32 s74, s82, s83
	s_add_i32 s86, s80, s1
	s_mov_b32 m0, s86
	s_waitcnt vmcnt(8)
	s_waitcnt lgkmcnt(0)
	s_barrier
	s_setprio 1
	s_waitcnt lgkmcnt(0)
	v_mfma_f32_16x16x32_bf16 v[124:127], v[128:131], v[160:163], v[124:127]
	v_mfma_f32_16x16x32_bf16 v[120:123], v[136:139], v[160:163], v[120:123]
	v_mfma_f32_16x16x32_bf16 v[116:119], v[128:131], v[184:187], v[116:119]
	v_mfma_f32_16x16x32_bf16 v[108:111], v[136:139], v[184:187], v[108:111]
	v_mfma_f32_16x16x32_bf16 v[92:95], v[128:131], v[192:195], v[92:95]
	v_mfma_f32_16x16x32_bf16 v[88:91], v[136:139], v[192:195], v[88:91]
	v_mfma_f32_16x16x32_bf16 v[76:79], v[128:131], v[210:213], v[76:79]
	v_mfma_f32_16x16x32_bf16 v[72:75], v[136:139], v[210:213], v[72:75]
	v_mfma_f32_16x16x32_bf16 v[124:127], v[132:135], v[164:167], v[124:127]
	v_mfma_f32_16x16x32_bf16 v[120:123], v[140:143], v[164:167], v[120:123]
	v_mfma_f32_16x16x32_bf16 v[116:119], v[132:135], v[188:191], v[116:119]
	v_mfma_f32_16x16x32_bf16 v[108:111], v[140:143], v[188:191], v[108:111]
	v_mfma_f32_16x16x32_bf16 v[92:95], v[132:135], v[206:209], v[92:95]
	v_mfma_f32_16x16x32_bf16 v[88:91], v[140:143], v[206:209], v[88:91]
	v_mfma_f32_16x16x32_bf16 v[76:79], v[132:135], v[214:217], v[76:79]
	v_mfma_f32_16x16x32_bf16 v[72:75], v[140:143], v[214:217], v[72:75]
	s_setprio 0
	s_setprio 1
	v_mfma_f32_16x16x32_bf16 v[112:115], v[144:147], v[160:163], v[112:115]
	v_mfma_f32_16x16x32_bf16 v[104:107], v[152:155], v[160:163], v[104:107]
	v_mfma_f32_16x16x32_bf16 v[100:103], v[144:147], v[184:187], v[100:103]
	v_mfma_f32_16x16x32_bf16 v[96:99], v[152:155], v[184:187], v[96:99]
	v_mfma_f32_16x16x32_bf16 v[84:87], v[144:147], v[192:195], v[84:87]
	v_mfma_f32_16x16x32_bf16 v[80:83], v[152:155], v[192:195], v[80:83]
	v_mfma_f32_16x16x32_bf16 v[68:71], v[144:147], v[210:213], v[68:71]
	v_mfma_f32_16x16x32_bf16 v[64:67], v[152:155], v[210:213], v[64:67]
	v_mfma_f32_16x16x32_bf16 v[112:115], v[148:151], v[164:167], v[112:115]
	v_mfma_f32_16x16x32_bf16 v[104:107], v[156:159], v[164:167], v[104:107]
	v_mfma_f32_16x16x32_bf16 v[100:103], v[148:151], v[188:191], v[100:103]
	v_mfma_f32_16x16x32_bf16 v[96:99], v[156:159], v[188:191], v[96:99]
	v_mfma_f32_16x16x32_bf16 v[84:87], v[148:151], v[206:209], v[84:87]
	v_mfma_f32_16x16x32_bf16 v[80:83], v[156:159], v[206:209], v[80:83]
	v_mfma_f32_16x16x32_bf16 v[68:71], v[148:151], v[214:217], v[68:71]
	v_mfma_f32_16x16x32_bf16 v[64:67], v[156:159], v[214:217], v[64:67]
	s_setprio 0
	s_barrier
	ds_read_b128 v[160:163], v204 offset:16384
	ds_read_b128 v[164:167], v204 offset:17408
	ds_read_b128 v[184:187], v204 offset:18432
	ds_read_b128 v[188:191], v204 offset:19456
	ds_read_b128 v[192:195], v204 offset:20480
	ds_read_b128 v[206:209], v204 offset:21504
	ds_read_b128 v[210:213], v204 offset:22528
	ds_read_b128 v[214:217], v204 offset:23552
	global_load_lds_dwordx4 v170, s[74:75]
	s_add_i32 m0, s86, 0x2000
	s_add_u32 s86, s74, 0x200000
	s_addc_u32 s87, s75, 0
	s_add_i32 s88, s81, s1
	global_load_lds_dwordx4 v174, s[74:75]
	s_mov_b32 m0, s88
	s_nop 0
	global_load_lds_dwordx4 v170, s[86:87]
	s_add_i32 m0, s88, 0x2000
	s_nop 0
	global_load_lds_dwordx4 v174, s[86:87]
	s_mov_b32 m0, s4
	s_nop 0
	global_load_lds_dwordx4 v168, s[76:77]
	s_mov_b32 m0, s5
	s_nop 0
	global_load_lds_dwordx4 v172, s[76:77]
	s_waitcnt vmcnt(8)
	s_waitcnt lgkmcnt(0)
	s_barrier
	s_setprio 1
	s_waitcnt lgkmcnt(0)
	v_mfma_f32_16x16x32_bf16 v[60:63], v[128:131], v[160:163], v[60:63]
	v_mfma_f32_16x16x32_bf16 v[56:59], v[136:139], v[160:163], v[56:59]
	v_mfma_f32_16x16x32_bf16 v[44:47], v[128:131], v[184:187], v[44:47]
	v_mfma_f32_16x16x32_bf16 v[40:43], v[136:139], v[184:187], v[40:43]
	v_mfma_f32_16x16x32_bf16 v[28:31], v[128:131], v[192:195], v[28:31]
	v_mfma_f32_16x16x32_bf16 v[24:27], v[136:139], v[192:195], v[24:27]
	v_mfma_f32_16x16x32_bf16 v[12:15], v[128:131], v[210:213], v[12:15]
	v_mfma_f32_16x16x32_bf16 v[8:11], v[136:139], v[210:213], v[8:11]
	v_mfma_f32_16x16x32_bf16 v[60:63], v[132:135], v[164:167], v[60:63]
	v_mfma_f32_16x16x32_bf16 v[56:59], v[140:143], v[164:167], v[56:59]
	v_mfma_f32_16x16x32_bf16 v[44:47], v[132:135], v[188:191], v[44:47]
	v_mfma_f32_16x16x32_bf16 v[40:43], v[140:143], v[188:191], v[40:43]
	v_mfma_f32_16x16x32_bf16 v[28:31], v[132:135], v[206:209], v[28:31]
	v_mfma_f32_16x16x32_bf16 v[24:27], v[140:143], v[206:209], v[24:27]
	v_mfma_f32_16x16x32_bf16 v[12:15], v[132:135], v[214:217], v[12:15]
	v_mfma_f32_16x16x32_bf16 v[8:11], v[140:143], v[214:217], v[8:11]
	s_setprio 0
	s_setprio 1
	v_mfma_f32_16x16x32_bf16 v[52:55], v[144:147], v[160:163], v[52:55]
	v_mfma_f32_16x16x32_bf16 v[48:51], v[152:155], v[160:163], v[48:51]
	v_mfma_f32_16x16x32_bf16 v[36:39], v[144:147], v[184:187], v[36:39]
	v_mfma_f32_16x16x32_bf16 v[32:35], v[152:155], v[184:187], v[32:35]
	v_mfma_f32_16x16x32_bf16 v[20:23], v[144:147], v[192:195], v[20:23]
	v_mfma_f32_16x16x32_bf16 v[16:19], v[152:155], v[192:195], v[16:19]
	v_mfma_f32_16x16x32_bf16 v[4:7], v[144:147], v[210:213], v[4:7]
	v_mfma_f32_16x16x32_bf16 v[0:3], v[152:155], v[210:213], v[0:3]
	v_mfma_f32_16x16x32_bf16 v[52:55], v[148:151], v[164:167], v[52:55]
	v_mfma_f32_16x16x32_bf16 v[48:51], v[156:159], v[164:167], v[48:51]
	v_mfma_f32_16x16x32_bf16 v[36:39], v[148:151], v[188:191], v[36:39]
	v_mfma_f32_16x16x32_bf16 v[32:35], v[156:159], v[188:191], v[32:35]
	v_mfma_f32_16x16x32_bf16 v[20:23], v[148:151], v[206:209], v[20:23]
	v_mfma_f32_16x16x32_bf16 v[16:19], v[156:159], v[206:209], v[16:19]
	v_mfma_f32_16x16x32_bf16 v[4:7], v[148:151], v[214:217], v[4:7]
	v_mfma_f32_16x16x32_bf16 v[0:3], v[156:159], v[214:217], v[0:3]
	s_setprio 0
	s_barrier
; #define PG8_STAGE(bufoff, gbase, voff) do { _Pragma("unroll") for (int _i = 0; _i < 2; ++_i) \
;         __builtin_amdgcn_global_load_lds((const unsigned*)((const char*)(gbase) + (voff)[_i]), (PG8_LAS unsigned*)(lds + (bufoff) + ldsw + _i * 8192), 16, 0, 0); } while (0)
; #define PG8_LDA(dst, b, h) do { _Pragma("unroll") for (int m = 0; m < 4; ++m) _Pragma("unroll") for (int k = 0; k < 2; ++k) dst[m][k] = *(const PG8_LAS bf16x8*)(lds + PG8_SA(b, h) + aoff + m * 2048 + k * 1024); } while (0)
; #define PG8_LDB(dst, b, h) do { _Pragma("unroll") for (int n = 0; n < 2; ++n) _Pragma("unroll") for (int k = 0; k < 2; ++k) dst[n][k] = *(const PG8_LAS bf16x8*)(lds + PG8_SB(b, h) + boff + n * 2048 + k * 1024); } while (0)
; #define PG8_MMA(ai, bj, At, Bt) do { __builtin_amdgcn_s_setprio(1); _Pragma("unroll") for (int m = 0; m < 4; ++m) _Pragma("unroll") for (int n = 0; n < 2; ++n) _Pragma("unroll") for (int k = 0; k < 2; ++k) \
;         acc[ai][bj][m][n] = __builtin_amdgcn_mfma_f32_16x16x32_bf16(Bt[n][k], At[m][k], acc[ai][bj][m][n], 0, 0, 0); __builtin_amdgcn_s_setprio(0); } while (0)
; #define PG8_WAIT_V(n) asm volatile("s_waitcnt vmcnt(" #n ")" ::: "memory")
; #define PG8_WAIT_L(n) asm volatile("s_waitcnt lgkmcnt(" #n ")" ::: "memory")
; #define PG8_BAR __builtin_amdgcn_s_barrier()
; #define PG8_SCHED __builtin_amdgcn_sched_barrier(0)
; template <class Epi, class Sched, bool ALIGN_EPI = false, bool SP2 = false>
; __device__ __forceinline__ void gemm_phase(PG8_LAS unsigned char* lds, const Gemm g, const Sched& S, const Epi& E) {
;     ...
;         for (int t = 0; t < nt; t += 2) {
;     ...
;             PG8_LDB(B0, 1, 0); PG8_LDB(B1, 1, 1); PG8_SCHED; PG8_LDA(At, 1, 0); PG8_STAGE(PG8_SA(0, 1), a2 + hstep, voffA);
;             PG8_WAIT_V(8); PG8_WAIT_L(0); PG8_BAR; PG8_MMA(0, 0, At, B0); PG8_MMA(0, 1, At, B1); PG8_BAR; PG8_SCHED;
;             PG8_LDA(At, 1, 1); PG8_STAGE(PG8_SB(1, 0), b3, voffB); PG8_STAGE(PG8_SB(1, 1), b3 + hstep, voffB); PG8_STAGE(PG8_SA(1, 0), a3, voffA);
;             PG8_WAIT_V(8); PG8_WAIT_L(0); PG8_BAR; PG8_MMA(1, 0, At, B0); PG8_MMA(1, 1, At, B1); PG8_BAR; PG8_SCHED;
	ds_read_b128 v[128:131], v218
	ds_read_b128 v[132:135], v218 offset:1024
	ds_read_b128 v[136:139], v218 offset:2048
	ds_read_b128 v[140:143], v218 offset:3072
	ds_read_b128 v[144:147], v219
	ds_read_b128 v[148:151], v219 offset:1024
	ds_read_b128 v[152:155], v219 offset:2048
	ds_read_b128 v[156:159], v219 offset:3072
	ds_read_b128 v[160:163], v204 offset:32768
	ds_read_b128 v[164:167], v204 offset:33792
	ds_read_b128 v[184:187], v204 offset:34816
	ds_read_b128 v[188:191], v204 offset:35840
	ds_read_b128 v[192:195], v204 offset:36864
	ds_read_b128 v[206:209], v204 offset:37888
	ds_read_b128 v[210:213], v204 offset:38912
	ds_read_b128 v[214:217], v204 offset:39936
	s_add_u32 s98, s76, 0x200000
	s_addc_u32 s99, s77, 0
	s_mov_b32 m0, s14
	s_add_u32 s100, s76, 0x80
	s_addc_u32 s101, s77, 0
	global_load_lds_dwordx4 v168, s[98:99]
	s_mov_b32 m0, s15
	s_nop 0
	global_load_lds_dwordx4 v172, s[98:99]
	s_add_i32 s86, 0, 0x18000
	s_add_i32 s87, 0, 0x1c000
	s_add_u32 s98, s74, 0x80
	s_addc_u32 s99, s75, 0
	s_add_i32 s76, s86, s1
	s_mov_b32 m0, s76
	s_waitcnt vmcnt(8)
	s_waitcnt lgkmcnt(0)
	s_barrier
	s_setprio 1
	s_waitcnt lgkmcnt(0)
	v_mfma_f32_16x16x32_bf16 v[124:127], v[128:131], v[160:163], v[124:127]
	v_mfma_f32_16x16x32_bf16 v[120:123], v[136:139], v[160:163], v[120:123]
	v_mfma_f32_16x16x32_bf16 v[116:119], v[128:131], v[184:187], v[116:119]
	v_mfma_f32_16x16x32_bf16 v[108:111], v[136:139], v[184:187], v[108:111]
	v_mfma_f32_16x16x32_bf16 v[92:95], v[128:131], v[192:195], v[92:95]
	v_mfma_f32_16x16x32_bf16 v[88:91], v[136:139], v[192:195], v[88:91]
	v_mfma_f32_16x16x32_bf16 v[76:79], v[128:131], v[210:213], v[76:79]
	v_mfma_f32_16x16x32_bf16 v[72:75], v[136:139], v[210:213], v[72:75]
	v_mfma_f32_16x16x32_bf16 v[124:127], v[132:135], v[164:167], v[124:127]
	v_mfma_f32_16x16x32_bf16 v[120:123], v[140:143], v[164:167], v[120:123]
	v_mfma_f32_16x16x32_bf16 v[116:119], v[132:135], v[188:191], v[116:119]
	v_mfma_f32_16x16x32_bf16 v[108:111], v[140:143], v[188:191], v[108:111]
	v_mfma_f32_16x16x32_bf16 v[92:95], v[132:135], v[206:209], v[92:95]
	v_mfma_f32_16x16x32_bf16 v[88:91], v[140:143], v[206:209], v[88:91]
	v_mfma_f32_16x16x32_bf16 v[76:79], v[132:135], v[214:217], v[76:79]
	v_mfma_f32_16x16x32_bf16 v[72:75], v[140:143], v[214:217], v[72:75]
	s_setprio 0
	s_setprio 1
	v_mfma_f32_16x16x32_bf16 v[112:115], v[144:147], v[160:163], v[112:115]
	v_mfma_f32_16x16x32_bf16 v[104:107], v[152:155], v[160:163], v[104:107]
	v_mfma_f32_16x16x32_bf16 v[100:103], v[144:147], v[184:187], v[100:103]
	v_mfma_f32_16x16x32_bf16 v[96:99], v[152:155], v[184:187], v[96:99]
	v_mfma_f32_16x16x32_bf16 v[84:87], v[144:147], v[192:195], v[84:87]
	v_mfma_f32_16x16x32_bf16 v[80:83], v[152:155], v[192:195], v[80:83]
	v_mfma_f32_16x16x32_bf16 v[68:71], v[144:147], v[210:213], v[68:71]
	v_mfma_f32_16x16x32_bf16 v[64:67], v[152:155], v[210:213], v[64:67]
	v_mfma_f32_16x16x32_bf16 v[112:115], v[148:151], v[164:167], v[112:115]
	v_mfma_f32_16x16x32_bf16 v[104:107], v[156:159], v[164:167], v[104:107]
	v_mfma_f32_16x16x32_bf16 v[100:103], v[148:151], v[188:191], v[100:103]
	v_mfma_f32_16x16x32_bf16 v[96:99], v[156:159], v[188:191], v[96:99]
	v_mfma_f32_16x16x32_bf16 v[84:87], v[148:151], v[206:209], v[84:87]
	v_mfma_f32_16x16x32_bf16 v[80:83], v[156:159], v[206:209], v[80:83]
	v_mfma_f32_16x16x32_bf16 v[68:71], v[148:151], v[214:217], v[68:71]
	v_mfma_f32_16x16x32_bf16 v[64:67], v[156:159], v[214:217], v[64:67]
	s_setprio 0
	s_barrier
	ds_read_b128 v[160:163], v204 offset:49152
	ds_read_b128 v[164:167], v204 offset:50176
	ds_read_b128 v[184:187], v204 offset:51200
	ds_read_b128 v[188:191], v204 offset:52224
	ds_read_b128 v[192:195], v204 offset:53248
	ds_read_b128 v[206:209], v204 offset:54272
	ds_read_b128 v[210:213], v204 offset:55296
	ds_read_b128 v[214:217], v204 offset:56320
	global_load_lds_dwordx4 v170, s[98:99]
	s_add_i32 m0, s76, 0x2000
	s_add_u32 s74, s74, 0x200080
	s_addc_u32 s75, s75, 0
	s_add_i32 s76, s87, s1
	global_load_lds_dwordx4 v174, s[98:99]
	s_mov_b32 m0, s76
	s_nop 0
	global_load_lds_dwordx4 v170, s[74:75]
	s_add_i32 m0, s76, 0x2000
	s_nop 0
	global_load_lds_dwordx4 v174, s[74:75]
	s_mov_b32 m0, s35
	s_nop 0
	global_load_lds_dwordx4 v168, s[100:101]
	s_mov_b32 m0, s71
	s_nop 0
	global_load_lds_dwordx4 v172, s[100:101]
	s_add_i32 s85, s85, 2
	s_add_u32 s72, s72, 0x100
	s_addc_u32 s73, s73, 0
	s_add_u32 s83, s83, 0x100
	s_addc_u32 s84, s84, 0
	s_cmpk_gt_u32 s85, 0x7d
	s_waitcnt vmcnt(8)
	s_waitcnt lgkmcnt(0)
	s_barrier
	s_setprio 1
	s_waitcnt lgkmcnt(0)
	v_mfma_f32_16x16x32_bf16 v[60:63], v[128:131], v[160:163], v[60:63]
	v_mfma_f32_16x16x32_bf16 v[56:59], v[136:139], v[160:163], v[56:59]
	v_mfma_f32_16x16x32_bf16 v[44:47], v[128:131], v[184:187], v[44:47]
	v_mfma_f32_16x16x32_bf16 v[40:43], v[136:139], v[184:187], v[40:43]
	v_mfma_f32_16x16x32_bf16 v[28:31], v[128:131], v[192:195], v[28:31]
	v_mfma_f32_16x16x32_bf16 v[24:27], v[136:139], v[192:195], v[24:27]
	v_mfma_f32_16x16x32_bf16 v[12:15], v[128:131], v[210:213], v[12:15]
	v_mfma_f32_16x16x32_bf16 v[8:11], v[136:139], v[210:213], v[8:11]
	v_mfma_f32_16x16x32_bf16 v[60:63], v[132:135], v[164:167], v[60:63]
	v_mfma_f32_16x16x32_bf16 v[56:59], v[140:143], v[164:167], v[56:59]
	v_mfma_f32_16x16x32_bf16 v[44:47], v[132:135], v[188:191], v[44:47]
	v_mfma_f32_16x16x32_bf16 v[40:43], v[140:143], v[188:191], v[40:43]
	v_mfma_f32_16x16x32_bf16 v[28:31], v[132:135], v[206:209], v[28:31]
	v_mfma_f32_16x16x32_bf16 v[24:27], v[140:143], v[206:209], v[24:27]
	v_mfma_f32_16x16x32_bf16 v[12:15], v[132:135], v[214:217], v[12:15]
	v_mfma_f32_16x16x32_bf16 v[8:11], v[140:143], v[214:217], v[8:11]
	s_setprio 0
	s_setprio 1
	v_mfma_f32_16x16x32_bf16 v[52:55], v[144:147], v[160:163], v[52:55]
	v_mfma_f32_16x16x32_bf16 v[48:51], v[152:155], v[160:163], v[48:51]
	v_mfma_f32_16x16x32_bf16 v[36:39], v[144:147], v[184:187], v[36:39]
	v_mfma_f32_16x16x32_bf16 v[32:35], v[152:155], v[184:187], v[32:35]
	v_mfma_f32_16x16x32_bf16 v[20:23], v[144:147], v[192:195], v[20:23]
	v_mfma_f32_16x16x32_bf16 v[16:19], v[152:155], v[192:195], v[16:19]
	v_mfma_f32_16x16x32_bf16 v[4:7], v[144:147], v[210:213], v[4:7]
	v_mfma_f32_16x16x32_bf16 v[0:3], v[152:155], v[210:213], v[0:3]
	v_mfma_f32_16x16x32_bf16 v[52:55], v[148:151], v[164:167], v[52:55]
	v_mfma_f32_16x16x32_bf16 v[48:51], v[156:159], v[164:167], v[48:51]
	v_mfma_f32_16x16x32_bf16 v[36:39], v[148:151], v[188:191], v[36:39]
	v_mfma_f32_16x16x32_bf16 v[32:35], v[156:159], v[188:191], v[32:35]
	v_mfma_f32_16x16x32_bf16 v[20:23], v[148:151], v[206:209], v[20:23]
	v_mfma_f32_16x16x32_bf16 v[16:19], v[156:159], v[206:209], v[16:19]
	v_mfma_f32_16x16x32_bf16 v[4:7], v[148:151], v[214:217], v[4:7]
	v_mfma_f32_16x16x32_bf16 v[0:3], v[156:159], v[214:217], v[0:3]
	s_setprio 0
	s_barrier
	s_cbranch_scc0 .LBB0_604
	s_and_b64 vcc, exec, s[48:49]
	s_cbranch_vccz .LBB0_607
	s_barrier

; #define PG8_STAGE(bufoff, gbase, voff) do { _Pragma("unroll") for (int _i = 0; _i < 2; ++_i) \
;         __builtin_amdgcn_global_load_lds((const unsigned*)((const char*)(gbase) + (voff)[_i]), (PG8_LAS unsigned*)(lds + (bufoff) + ldsw + _i * 8192), 16, 0, 0); } while (0)
; #define PG8_LDA(dst, b, h) do { _Pragma("unroll") for (int m = 0; m < 4; ++m) _Pragma("unroll") for (int k = 0; k < 2; ++k) dst[m][k] = *(const PG8_LAS bf16x8*)(lds + PG8_SA(b, h) + aoff + m * 2048 + k * 1024); } while (0)
; #define PG8_LDB(dst, b, h) do { _Pragma("unroll") for (int n = 0; n < 2; ++n) _Pragma("unroll") for (int k = 0; k < 2; ++k) dst[n][k] = *(const PG8_LAS bf16x8*)(lds + PG8_SB(b, h) + boff + n * 2048 + k * 1024); } while (0)
; #define PG8_MMA(ai, bj, At, Bt) do { __builtin_amdgcn_s_setprio(1); _Pragma("unroll") for (int m = 0; m < 4; ++m) _Pragma("unroll") for (int n = 0; n < 2; ++n) _Pragma("unroll") for (int k = 0; k < 2; ++k) \
;         acc[ai][bj][m][n] = __builtin_amdgcn_mfma_f32_16x16x32_bf16(Bt[n][k], At[m][k], acc[ai][bj][m][n], 0, 0, 0); __builtin_amdgcn_s_setprio(0); } while (0)
; #define PG8_WAIT_V(n) asm volatile("s_waitcnt vmcnt(" #n ")" ::: "memory")
; #define PG8_WAIT_L(n) asm volatile("s_waitcnt lgkmcnt(" #n ")" ::: "memory")
; template <class Epi, class Sched, bool ALIGN_EPI = false, bool SP2 = false>
; __device__ __forceinline__ void gemm_phase(PG8_LAS unsigned char* lds, const Gemm g, const Sched& S, const Epi& E) {
;     ...
;             const bool last = (t == nt - 2);
;             const char* a1 = cA + (size_t)(t + 1) * kstep;
;             const char* a2 = last ? nA : cA + (size_t)(t + 2) * kstep; const char* b2 = last ? nB : cB + (size_t)(t + 2) * kstep;
;             const char* a3 = a2 + kstep; const char* b3 = b2 + kstep;
;             if (last && has_next) S.a_ready(nxt);
;             if constexpr (SP2) {
;             PG8_LDB(B0, 0, 0); PG8_LDB(B1, 0, 1); PG8_SCHED; PG8_LDA(At, 0, 0); PG8_STAGE(PG8_SA(1, 1), a1 + hstep, voffA);
;             PG8_WAIT_V(8); PG8_WAIT_L(0); PG8_BAR; PG8_MMA(0, 0, At, B0); PG8_MMA(0, 1, At, B1); PG8_BAR; PG8_SCHED;
;             PG8_LDA(At, 0, 1); PG8_STAGE(PG8_SB(0, 0), b2, voffB); PG8_STAGE(PG8_SB(0, 1), b2 + hstep, voffB); PG8_STAGE(PG8_SA(0, 0), a2, voffA);
;             PG8_WAIT_V(8); PG8_WAIT_L(0); PG8_BAR; PG8_MMA(1, 0, At, B0); PG8_MMA(1, 1, At, B1); PG8_BAR; PG8_SCHED;
.LBB0_735:
	ds_read_b128 v[156:159], v151
	ds_read_b128 v[160:163], v151 offset:1024
	ds_read_b128 v[164:167], v151 offset:2048
	ds_read_b128 v[168:171], v151 offset:3072
	ds_read_b128 v[172:175], v152
	ds_read_b128 v[176:179], v152 offset:1024
	ds_read_b128 v[180:183], v152 offset:2048
	ds_read_b128 v[184:187], v152 offset:3072
	s_add_i32 m0, s4, 0xc000
	ds_read_b128 v[188:191], v153
	ds_read_b128 v[192:195], v153 offset:1024
	ds_read_b128 v[200:203], v153 offset:2048
	ds_read_b128 v[204:207], v153 offset:3072
	ds_read_b128 v[208:211], v153 offset:4096
	ds_read_b128 v[212:215], v153 offset:5120
	ds_read_b128 v[216:219], v153 offset:6144
	ds_read_b128 v[220:223], v153 offset:7168
	global_load_lds_dwordx4 v138, s[68:69]
	s_add_i32 m0, s4, 0xe000
	s_nop 0
	global_load_lds_dwordx4 v140, s[68:69]
	s_add_u32 s70, s68, 0xfff80080
	s_addc_u32 s71, s69, -1
	s_cmp_eq_u32 s82, 28
	s_cselect_b32 s73, s25, s71
	s_cselect_b32 s72, s61, s70
	s_cselect_b32 s71, s49, s81
	s_cselect_b32 s70, s79, s80
	s_add_i32 s83, s77, s1
	s_mov_b32 m0, s83
	s_waitcnt vmcnt(8)
	s_waitcnt lgkmcnt(0)
	s_barrier
	s_setprio 1
	s_waitcnt lgkmcnt(0)
	v_mfma_f32_16x16x32_bf16 v[124:127], v[156:159], v[188:191], v[124:127]
	v_mfma_f32_16x16x32_bf16 v[120:123], v[164:167], v[188:191], v[120:123]
	v_mfma_f32_16x16x32_bf16 v[108:111], v[156:159], v[200:203], v[108:111]
	v_mfma_f32_16x16x32_bf16 v[104:107], v[164:167], v[200:203], v[104:107]
	v_mfma_f32_16x16x32_bf16 v[96:99], v[156:159], v[208:211], v[96:99]
	v_mfma_f32_16x16x32_bf16 v[88:91], v[164:167], v[208:211], v[88:91]
	v_mfma_f32_16x16x32_bf16 v[80:83], v[156:159], v[216:219], v[80:83]
	v_mfma_f32_16x16x32_bf16 v[72:75], v[164:167], v[216:219], v[72:75]
	v_mfma_f32_16x16x32_bf16 v[124:127], v[160:163], v[192:195], v[124:127]
	v_mfma_f32_16x16x32_bf16 v[120:123], v[168:171], v[192:195], v[120:123]
	v_mfma_f32_16x16x32_bf16 v[108:111], v[160:163], v[204:207], v[108:111]
	v_mfma_f32_16x16x32_bf16 v[104:107], v[168:171], v[204:207], v[104:107]
	v_mfma_f32_16x16x32_bf16 v[96:99], v[160:163], v[212:215], v[96:99]
	v_mfma_f32_16x16x32_bf16 v[88:91], v[168:171], v[212:215], v[88:91]
	v_mfma_f32_16x16x32_bf16 v[80:83], v[160:163], v[220:223], v[80:83]
	v_mfma_f32_16x16x32_bf16 v[72:75], v[168:171], v[220:223], v[72:75]
	s_setprio 0
	s_setprio 1
	v_mfma_f32_16x16x32_bf16 v[116:119], v[172:175], v[188:191], v[116:119]
	v_mfma_f32_16x16x32_bf16 v[112:115], v[180:183], v[188:191], v[112:115]
	v_mfma_f32_16x16x32_bf16 v[100:103], v[172:175], v[200:203], v[100:103]
	v_mfma_f32_16x16x32_bf16 v[92:95], v[180:183], v[200:203], v[92:95]
	v_mfma_f32_16x16x32_bf16 v[84:87], v[172:175], v[208:211], v[84:87]
	v_mfma_f32_16x16x32_bf16 v[76:79], v[180:183], v[208:211], v[76:79]
	v_mfma_f32_16x16x32_bf16 v[68:71], v[172:175], v[216:219], v[68:71]
	v_mfma_f32_16x16x32_bf16 v[64:67], v[180:183], v[216:219], v[64:67]
	v_mfma_f32_16x16x32_bf16 v[116:119], v[176:179], v[192:195], v[116:119]
	v_mfma_f32_16x16x32_bf16 v[112:115], v[184:187], v[192:195], v[112:115]
	v_mfma_f32_16x16x32_bf16 v[100:103], v[176:179], v[204:207], v[100:103]
	v_mfma_f32_16x16x32_bf16 v[92:95], v[184:187], v[204:207], v[92:95]
	v_mfma_f32_16x16x32_bf16 v[84:87], v[176:179], v[212:215], v[84:87]
	v_mfma_f32_16x16x32_bf16 v[76:79], v[184:187], v[212:215], v[76:79]
	v_mfma_f32_16x16x32_bf16 v[68:71], v[176:179], v[220:223], v[68:71]
	v_mfma_f32_16x16x32_bf16 v[64:67], v[184:187], v[220:223], v[64:67]
	s_setprio 0
	s_barrier
	ds_read_b128 v[188:191], v153 offset:16384
	ds_read_b128 v[192:195], v153 offset:17408
	ds_read_b128 v[200:203], v153 offset:18432
	ds_read_b128 v[204:207], v153 offset:19456
	ds_read_b128 v[208:211], v153 offset:20480
	ds_read_b128 v[212:215], v153 offset:21504
	ds_read_b128 v[216:219], v153 offset:22528
	ds_read_b128 v[220:223], v153 offset:23552
	global_load_lds_dwordx4 v130, s[70:71]
	s_add_i32 m0, s83, 0x2000
	s_add_u32 s84, s70, 0x80000
	s_addc_u32 s85, s71, 0
	s_add_i32 s83, s78, s1
	global_load_lds_dwordx4 v134, s[70:71]
	s_mov_b32 m0, s83
	s_nop 0
	global_load_lds_dwordx4 v130, s[84:85]
	s_add_i32 m0, s83, 0x2000
	s_nop 0
	global_load_lds_dwordx4 v134, s[84:85]
	s_mov_b32 m0, s4
	s_nop 0
	global_load_lds_dwordx4 v128, s[72:73]
	s_mov_b32 m0, s5
	s_nop 0
	global_load_lds_dwordx4 v132, s[72:73]
	s_waitcnt vmcnt(8)
	s_waitcnt lgkmcnt(0)
	s_barrier
	s_setprio 1
	s_waitcnt lgkmcnt(0)
	v_mfma_f32_16x16x32_bf16 v[60:63], v[156:159], v[188:191], v[60:63]
	v_mfma_f32_16x16x32_bf16 v[56:59], v[164:167], v[188:191], v[56:59]
	v_mfma_f32_16x16x32_bf16 v[44:47], v[156:159], v[200:203], v[44:47]
	v_mfma_f32_16x16x32_bf16 v[40:43], v[164:167], v[200:203], v[40:43]
	v_mfma_f32_16x16x32_bf16 v[32:35], v[156:159], v[208:211], v[32:35]
	v_mfma_f32_16x16x32_bf16 v[24:27], v[164:167], v[208:211], v[24:27]
	v_mfma_f32_16x16x32_bf16 v[16:19], v[156:159], v[216:219], v[16:19]
	v_mfma_f32_16x16x32_bf16 v[8:11], v[164:167], v[216:219], v[8:11]
	v_mfma_f32_16x16x32_bf16 v[60:63], v[160:163], v[192:195], v[60:63]
	v_mfma_f32_16x16x32_bf16 v[56:59], v[168:171], v[192:195], v[56:59]
	v_mfma_f32_16x16x32_bf16 v[44:47], v[160:163], v[204:207], v[44:47]
	v_mfma_f32_16x16x32_bf16 v[40:43], v[168:171], v[204:207], v[40:43]
	v_mfma_f32_16x16x32_bf16 v[32:35], v[160:163], v[212:215], v[32:35]
	v_mfma_f32_16x16x32_bf16 v[24:27], v[168:171], v[212:215], v[24:27]
	v_mfma_f32_16x16x32_bf16 v[16:19], v[160:163], v[220:223], v[16:19]
	v_mfma_f32_16x16x32_bf16 v[8:11], v[168:171], v[220:223], v[8:11]
	s_setprio 0
	s_setprio 1
	v_mfma_f32_16x16x32_bf16 v[52:55], v[172:175], v[188:191], v[52:55]
	v_mfma_f32_16x16x32_bf16 v[48:51], v[180:183], v[188:191], v[48:51]
	v_mfma_f32_16x16x32_bf16 v[36:39], v[172:175], v[200:203], v[36:39]
	v_mfma_f32_16x16x32_bf16 v[28:31], v[180:183], v[200:203], v[28:31]
	v_mfma_f32_16x16x32_bf16 v[20:23], v[172:175], v[208:211], v[20:23]
	v_mfma_f32_16x16x32_bf16 v[12:15], v[180:183], v[208:211], v[12:15]
	v_mfma_f32_16x16x32_bf16 v[4:7], v[172:175], v[216:219], v[4:7]
	v_mfma_f32_16x16x32_bf16 v[0:3], v[180:183], v[216:219], v[0:3]
	v_mfma_f32_16x16x32_bf16 v[52:55], v[176:179], v[192:195], v[52:55]
	v_mfma_f32_16x16x32_bf16 v[48:51], v[184:187], v[192:195], v[48:51]
	v_mfma_f32_16x16x32_bf16 v[36:39], v[176:179], v[204:207], v[36:39]
	v_mfma_f32_16x16x32_bf16 v[28:31], v[184:187], v[204:207], v[28:31]
	v_mfma_f32_16x16x32_bf16 v[20:23], v[176:179], v[212:215], v[20:23]
	v_mfma_f32_16x16x32_bf16 v[12:15], v[184:187], v[212:215], v[12:15]
	v_mfma_f32_16x16x32_bf16 v[4:7], v[176:179], v[220:223], v[4:7]
	v_mfma_f32_16x16x32_bf16 v[0:3], v[184:187], v[220:223], v[0:3]
	s_setprio 0
	s_barrier
; #define PG8_STAGE(bufoff, gbase, voff) do { _Pragma("unroll") for (int _i = 0; _i < 2; ++_i) \
;         __builtin_amdgcn_global_load_lds((const unsigned*)((const char*)(gbase) + (voff)[_i]), (PG8_LAS unsigned*)(lds + (bufoff) + ldsw + _i * 8192), 16, 0, 0); } while (0)
; #define PG8_LDA(dst, b, h) do { _Pragma("unroll") for (int m = 0; m < 4; ++m) _Pragma("unroll") for (int k = 0; k < 2; ++k) dst[m][k] = *(const PG8_LAS bf16x8*)(lds + PG8_SA(b, h) + aoff + m * 2048 + k * 1024); } while (0)
; #define PG8_LDB(dst, b, h) do { _Pragma("unroll") for (int n = 0; n < 2; ++n) _Pragma("unroll") for (int k = 0; k < 2; ++k) dst[n][k] = *(const PG8_LAS bf16x8*)(lds + PG8_SB(b, h) + boff + n * 2048 + k * 1024); } while (0)
; #define PG8_MMA(ai, bj, At, Bt) do { __builtin_amdgcn_s_setprio(1); _Pragma("unroll") for (int m = 0; m < 4; ++m) _Pragma("unroll") for (int n = 0; n < 2; ++n) _Pragma("unroll") for (int k = 0; k < 2; ++k) \
;         acc[ai][bj][m][n] = __builtin_amdgcn_mfma_f32_16x16x32_bf16(Bt[n][k], At[m][k], acc[ai][bj][m][n], 0, 0, 0); __builtin_amdgcn_s_setprio(0); } while (0)
; #define PG8_WAIT_V(n) asm volatile("s_waitcnt vmcnt(" #n ")" ::: "memory")
; #define PG8_WAIT_L(n) asm volatile("s_waitcnt lgkmcnt(" #n ")" ::: "memory")
; #define PG8_BAR __builtin_amdgcn_s_barrier()
; #define PG8_SCHED __builtin_amdgcn_sched_barrier(0)
; template <class Epi, class Sched, bool ALIGN_EPI = false, bool SP2 = false>
; __device__ __forceinline__ void gemm_phase(PG8_LAS unsigned char* lds, const Gemm g, const Sched& S, const Epi& E) {
;     ...
;         for (int t = 0; t < nt; t += 2) {
;     ...
;             PG8_LDB(B0, 1, 0); PG8_LDB(B1, 1, 1); PG8_SCHED; PG8_LDA(At, 1, 0); PG8_STAGE(PG8_SA(0, 1), a2 + hstep, voffA);
;             PG8_WAIT_V(8); PG8_WAIT_L(0); PG8_BAR; PG8_MMA(0, 0, At, B0); PG8_MMA(0, 1, At, B1); PG8_BAR; PG8_SCHED;
;             PG8_LDA(At, 1, 1); PG8_STAGE(PG8_SB(1, 0), b3, voffB); PG8_STAGE(PG8_SB(1, 1), b3 + hstep, voffB); PG8_STAGE(PG8_SA(1, 0), a3, voffA);
;             PG8_WAIT_V(8); PG8_WAIT_L(0); PG8_BAR; PG8_MMA(1, 0, At, B0); PG8_MMA(1, 1, At, B1); PG8_BAR; PG8_SCHED;
	ds_read_b128 v[156:159], v196
	ds_read_b128 v[160:163], v196 offset:1024
	ds_read_b128 v[164:167], v196 offset:2048
	ds_read_b128 v[168:171], v196 offset:3072
	ds_read_b128 v[172:175], v197
	ds_read_b128 v[176:179], v197 offset:1024
	ds_read_b128 v[180:183], v197 offset:2048
	ds_read_b128 v[184:187], v197 offset:3072
	ds_read_b128 v[188:191], v153 offset:32768
	ds_read_b128 v[192:195], v153 offset:33792
	ds_read_b128 v[200:203], v153 offset:34816
	ds_read_b128 v[204:207], v153 offset:35840
	ds_read_b128 v[208:211], v153 offset:36864
	ds_read_b128 v[212:215], v153 offset:37888
	ds_read_b128 v[216:219], v153 offset:38912
	ds_read_b128 v[220:223], v153 offset:39936
	s_add_u32 s98, s72, 0x80000
	s_addc_u32 s99, s73, 0
	s_mov_b32 m0, s14
	s_add_u32 s100, s72, 0x80
	s_addc_u32 s101, s73, 0
	global_load_lds_dwordx4 v128, s[98:99]
	s_mov_b32 m0, s15
	s_nop 0
	global_load_lds_dwordx4 v132, s[98:99]
	s_add_i32 s83, 0, 0x18000
	s_add_i32 s84, 0, 0x1c000
	s_add_u32 s98, s70, 0x80
	s_addc_u32 s99, s71, 0
	s_add_i32 s72, s83, s1
	s_mov_b32 m0, s72
	s_waitcnt vmcnt(8)
	s_waitcnt lgkmcnt(0)
	s_barrier
	s_setprio 1
	s_waitcnt lgkmcnt(0)
	v_mfma_f32_16x16x32_bf16 v[124:127], v[156:159], v[188:191], v[124:127]
	v_mfma_f32_16x16x32_bf16 v[120:123], v[164:167], v[188:191], v[120:123]
	v_mfma_f32_16x16x32_bf16 v[108:111], v[156:159], v[200:203], v[108:111]
	v_mfma_f32_16x16x32_bf16 v[104:107], v[164:167], v[200:203], v[104:107]
	v_mfma_f32_16x16x32_bf16 v[96:99], v[156:159], v[208:211], v[96:99]
	v_mfma_f32_16x16x32_bf16 v[88:91], v[164:167], v[208:211], v[88:91]
	v_mfma_f32_16x16x32_bf16 v[80:83], v[156:159], v[216:219], v[80:83]
	v_mfma_f32_16x16x32_bf16 v[72:75], v[164:167], v[216:219], v[72:75]
	v_mfma_f32_16x16x32_bf16 v[124:127], v[160:163], v[192:195], v[124:127]
	v_mfma_f32_16x16x32_bf16 v[120:123], v[168:171], v[192:195], v[120:123]
	v_mfma_f32_16x16x32_bf16 v[108:111], v[160:163], v[204:207], v[108:111]
	v_mfma_f32_16x16x32_bf16 v[104:107], v[168:171], v[204:207], v[104:107]
	v_mfma_f32_16x16x32_bf16 v[96:99], v[160:163], v[212:215], v[96:99]
	v_mfma_f32_16x16x32_bf16 v[88:91], v[168:171], v[212:215], v[88:91]
	v_mfma_f32_16x16x32_bf16 v[80:83], v[160:163], v[220:223], v[80:83]
	v_mfma_f32_16x16x32_bf16 v[72:75], v[168:171], v[220:223], v[72:75]
	s_setprio 0
	s_setprio 1
	v_mfma_f32_16x16x32_bf16 v[116:119], v[172:175], v[188:191], v[116:119]
	v_mfma_f32_16x16x32_bf16 v[112:115], v[180:183], v[188:191], v[112:115]
	v_mfma_f32_16x16x32_bf16 v[100:103], v[172:175], v[200:203], v[100:103]
	v_mfma_f32_16x16x32_bf16 v[92:95], v[180:183], v[200:203], v[92:95]
	v_mfma_f32_16x16x32_bf16 v[84:87], v[172:175], v[208:211], v[84:87]
	v_mfma_f32_16x16x32_bf16 v[76:79], v[180:183], v[208:211], v[76:79]
	v_mfma_f32_16x16x32_bf16 v[68:71], v[172:175], v[216:219], v[68:71]
	v_mfma_f32_16x16x32_bf16 v[64:67], v[180:183], v[216:219], v[64:67]
	v_mfma_f32_16x16x32_bf16 v[116:119], v[176:179], v[192:195], v[116:119]
	v_mfma_f32_16x16x32_bf16 v[112:115], v[184:187], v[192:195], v[112:115]
	v_mfma_f32_16x16x32_bf16 v[100:103], v[176:179], v[204:207], v[100:103]
	v_mfma_f32_16x16x32_bf16 v[92:95], v[184:187], v[204:207], v[92:95]
	v_mfma_f32_16x16x32_bf16 v[84:87], v[176:179], v[212:215], v[84:87]
	v_mfma_f32_16x16x32_bf16 v[76:79], v[184:187], v[212:215], v[76:79]
	v_mfma_f32_16x16x32_bf16 v[68:71], v[176:179], v[220:223], v[68:71]
	v_mfma_f32_16x16x32_bf16 v[64:67], v[184:187], v[220:223], v[64:67]
	s_setprio 0
	s_barrier
	ds_read_b128 v[188:191], v153 offset:49152
	ds_read_b128 v[192:195], v153 offset:50176
	ds_read_b128 v[200:203], v153 offset:51200
	ds_read_b128 v[204:207], v153 offset:52224
	ds_read_b128 v[208:211], v153 offset:53248
	ds_read_b128 v[212:215], v153 offset:54272
	ds_read_b128 v[216:219], v153 offset:55296
	ds_read_b128 v[220:223], v153 offset:56320
	global_load_lds_dwordx4 v130, s[98:99]
	s_add_i32 m0, s72, 0x2000
	s_add_u32 s70, s70, 0x80080
	s_addc_u32 s71, s71, 0
	s_add_i32 s72, s84, s1
	global_load_lds_dwordx4 v134, s[98:99]
	s_mov_b32 m0, s72
	s_nop 0
	global_load_lds_dwordx4 v130, s[70:71]
	s_add_i32 m0, s72, 0x2000
	s_nop 0
	global_load_lds_dwordx4 v134, s[70:71]
	s_mov_b32 m0, s67
	s_nop 0
	global_load_lds_dwordx4 v128, s[100:101]
	s_mov_b32 m0, s74
	s_nop 0
	global_load_lds_dwordx4 v132, s[100:101]
	s_add_i32 s82, s82, 2
	s_add_u32 s68, s68, 0x100
	s_addc_u32 s69, s69, 0
	s_add_u32 s80, s80, 0x100
	s_addc_u32 s81, s81, 0
	s_cmp_gt_u32 s82, 29
	s_waitcnt vmcnt(8)
	s_waitcnt lgkmcnt(0)
	s_barrier
	s_setprio 1
	s_waitcnt lgkmcnt(0)
	v_mfma_f32_16x16x32_bf16 v[60:63], v[156:159], v[188:191], v[60:63]
	v_mfma_f32_16x16x32_bf16 v[56:59], v[164:167], v[188:191], v[56:59]
	v_mfma_f32_16x16x32_bf16 v[44:47], v[156:159], v[200:203], v[44:47]
	v_mfma_f32_16x16x32_bf16 v[40:43], v[164:167], v[200:203], v[40:43]
	v_mfma_f32_16x16x32_bf16 v[32:35], v[156:159], v[208:211], v[32:35]
	v_mfma_f32_16x16x32_bf16 v[24:27], v[164:167], v[208:211], v[24:27]
	v_mfma_f32_16x16x32_bf16 v[16:19], v[156:159], v[216:219], v[16:19]
	v_mfma_f32_16x16x32_bf16 v[8:11], v[164:167], v[216:219], v[8:11]
	v_mfma_f32_16x16x32_bf16 v[60:63], v[160:163], v[192:195], v[60:63]
	v_mfma_f32_16x16x32_bf16 v[56:59], v[168:171], v[192:195], v[56:59]
	v_mfma_f32_16x16x32_bf16 v[44:47], v[160:163], v[204:207], v[44:47]
	v_mfma_f32_16x16x32_bf16 v[40:43], v[168:171], v[204:207], v[40:43]
	v_mfma_f32_16x16x32_bf16 v[32:35], v[160:163], v[212:215], v[32:35]
	v_mfma_f32_16x16x32_bf16 v[24:27], v[168:171], v[212:215], v[24:27]
	v_mfma_f32_16x16x32_bf16 v[16:19], v[160:163], v[220:223], v[16:19]
	v_mfma_f32_16x16x32_bf16 v[8:11], v[168:171], v[220:223], v[8:11]
	s_setprio 0
	s_setprio 1
	v_mfma_f32_16x16x32_bf16 v[52:55], v[172:175], v[188:191], v[52:55]
	v_mfma_f32_16x16x32_bf16 v[48:51], v[180:183], v[188:191], v[48:51]
	v_mfma_f32_16x16x32_bf16 v[36:39], v[172:175], v[200:203], v[36:39]
	v_mfma_f32_16x16x32_bf16 v[28:31], v[180:183], v[200:203], v[28:31]
	v_mfma_f32_16x16x32_bf16 v[20:23], v[172:175], v[208:211], v[20:23]
	v_mfma_f32_16x16x32_bf16 v[12:15], v[180:183], v[208:211], v[12:15]
	v_mfma_f32_16x16x32_bf16 v[4:7], v[172:175], v[216:219], v[4:7]
	v_mfma_f32_16x16x32_bf16 v[0:3], v[180:183], v[216:219], v[0:3]
	v_mfma_f32_16x16x32_bf16 v[52:55], v[176:179], v[192:195], v[52:55]
	v_mfma_f32_16x16x32_bf16 v[48:51], v[184:187], v[192:195], v[48:51]
	v_mfma_f32_16x16x32_bf16 v[36:39], v[176:179], v[204:207], v[36:39]
	v_mfma_f32_16x16x32_bf16 v[28:31], v[184:187], v[204:207], v[28:31]
	v_mfma_f32_16x16x32_bf16 v[20:23], v[176:179], v[212:215], v[20:23]
	v_mfma_f32_16x16x32_bf16 v[12:15], v[184:187], v[212:215], v[12:15]
	v_mfma_f32_16x16x32_bf16 v[4:7], v[176:179], v[220:223], v[4:7]
	v_mfma_f32_16x16x32_bf16 v[0:3], v[184:187], v[220:223], v[0:3]
	s_setprio 0
	s_barrier
	s_cbranch_scc0 .LBB0_735
	s_and_b64 vcc, exec, s[38:39]
	s_cbranch_vccz .LBB0_738
	s_barrier

; #define PG8_STAGE(bufoff, gbase, voff) do { _Pragma("unroll") for (int _i = 0; _i < 2; ++_i) \
;         __builtin_amdgcn_global_load_lds((const unsigned*)((const char*)(gbase) + (voff)[_i]), (PG8_LAS unsigned*)(lds + (bufoff) + ldsw + _i * 8192), 16, 0, 0); } while (0)
; #define PG8_LDA(dst, b, h) do { _Pragma("unroll") for (int m = 0; m < 4; ++m) _Pragma("unroll") for (int k = 0; k < 2; ++k) dst[m][k] = *(const PG8_LAS bf16x8*)(lds + PG8_SA(b, h) + aoff + m * 2048 + k * 1024); } while (0)
; #define PG8_LDB(dst, b, h) do { _Pragma("unroll") for (int n = 0; n < 2; ++n) _Pragma("unroll") for (int k = 0; k < 2; ++k) dst[n][k] = *(const PG8_LAS bf16x8*)(lds + PG8_SB(b, h) + boff + n * 2048 + k * 1024); } while (0)
; #define PG8_MMA(ai, bj, At, Bt) do { __builtin_amdgcn_s_setprio(1); _Pragma("unroll") for (int m = 0; m < 4; ++m) _Pragma("unroll") for (int n = 0; n < 2; ++n) _Pragma("unroll") for (int k = 0; k < 2; ++k) \
;         acc[ai][bj][m][n] = __builtin_amdgcn_mfma_f32_16x16x32_bf16(Bt[n][k], At[m][k], acc[ai][bj][m][n], 0, 0, 0); __builtin_amdgcn_s_setprio(0); } while (0)
; #define PG8_WAIT_V(n) asm volatile("s_waitcnt vmcnt(" #n ")" ::: "memory")
; #define PG8_WAIT_L(n) asm volatile("s_waitcnt lgkmcnt(" #n ")" ::: "memory")
; template <class Epi, class Sched, bool ALIGN_EPI = false, bool SP2 = false>
; __device__ __forceinline__ void gemm_phase(PG8_LAS unsigned char* lds, const Gemm g, const Sched& S, const Epi& E) {
;     ...
;             const bool last = (t == nt - 2);
;             const char* a1 = cA + (size_t)(t + 1) * kstep;
;             const char* a2 = last ? nA : cA + (size_t)(t + 2) * kstep; const char* b2 = last ? nB : cB + (size_t)(t + 2) * kstep;
;             const char* a3 = a2 + kstep; const char* b3 = b2 + kstep;
;             if (last && has_next) S.a_ready(nxt);
;             if constexpr (SP2) {
;             PG8_LDB(B0, 0, 0); PG8_LDB(B1, 0, 1); PG8_SCHED; PG8_LDA(At, 0, 0); PG8_STAGE(PG8_SA(1, 1), a1 + hstep, voffA);
;             PG8_WAIT_V(8); PG8_WAIT_L(0); PG8_BAR; PG8_MMA(0, 0, At, B0); PG8_MMA(0, 1, At, B1); PG8_BAR; PG8_SCHED;
;             PG8_LDA(At, 0, 1); PG8_STAGE(PG8_SB(0, 0), b2, voffB); PG8_STAGE(PG8_SB(0, 1), b2 + hstep, voffB); PG8_STAGE(PG8_SA(0, 0), a2, voffA);
;             PG8_WAIT_V(8); PG8_WAIT_L(0); PG8_BAR; PG8_MMA(1, 0, At, B0); PG8_MMA(1, 1, At, B1); PG8_BAR; PG8_SCHED;
.LBB0_759:
	ds_read_b128 v[152:155], v149
	ds_read_b128 v[156:159], v149 offset:1024
	ds_read_b128 v[160:163], v149 offset:2048
	ds_read_b128 v[164:167], v149 offset:3072
	ds_read_b128 v[168:171], v150
	ds_read_b128 v[172:175], v150 offset:1024
	ds_read_b128 v[176:179], v150 offset:2048
	ds_read_b128 v[180:183], v150 offset:3072
	s_add_i32 m0, s6, 0xc000
	ds_read_b128 v[184:187], v151
	ds_read_b128 v[188:191], v151 offset:1024
	ds_read_b128 v[192:195], v151 offset:2048
	ds_read_b128 v[200:203], v151 offset:3072
	ds_read_b128 v[204:207], v151 offset:4096
	ds_read_b128 v[208:211], v151 offset:5120
	ds_read_b128 v[212:215], v151 offset:6144
	ds_read_b128 v[216:219], v151 offset:7168
	global_load_lds_dwordx4 v138, s[68:69]
	s_add_i32 m0, s6, 0xe000
	s_nop 0
	global_load_lds_dwordx4 v140, s[68:69]
	s_add_u32 s70, s68, 0xfff80080
	s_addc_u32 s71, s69, -1
	s_cmp_eq_u32 s83, 28
	s_cselect_b32 s73, s25, s71
	s_cselect_b32 s72, s61, s70
	s_cselect_b32 s71, s49, s82
	s_cselect_b32 s70, s80, s81
	s_add_i32 s84, s78, s5
	s_mov_b32 m0, s84
	s_waitcnt vmcnt(8)
	s_waitcnt lgkmcnt(0)
	s_barrier
	s_setprio 1
	s_waitcnt lgkmcnt(0)
	v_mfma_f32_16x16x32_bf16 v[124:127], v[152:155], v[184:187], v[124:127]
	v_mfma_f32_16x16x32_bf16 v[120:123], v[160:163], v[184:187], v[120:123]
	v_mfma_f32_16x16x32_bf16 v[112:115], v[152:155], v[192:195], v[112:115]
	v_mfma_f32_16x16x32_bf16 v[104:107], v[160:163], v[192:195], v[104:107]
	v_mfma_f32_16x16x32_bf16 v[100:103], v[152:155], v[204:207], v[100:103]
	v_mfma_f32_16x16x32_bf16 v[92:95], v[160:163], v[204:207], v[92:95]
	v_mfma_f32_16x16x32_bf16 v[84:87], v[152:155], v[212:215], v[84:87]
	v_mfma_f32_16x16x32_bf16 v[76:79], v[160:163], v[212:215], v[76:79]
	v_mfma_f32_16x16x32_bf16 v[124:127], v[156:159], v[188:191], v[124:127]
	v_mfma_f32_16x16x32_bf16 v[120:123], v[164:167], v[188:191], v[120:123]
	v_mfma_f32_16x16x32_bf16 v[112:115], v[156:159], v[200:203], v[112:115]
	v_mfma_f32_16x16x32_bf16 v[104:107], v[164:167], v[200:203], v[104:107]
	v_mfma_f32_16x16x32_bf16 v[100:103], v[156:159], v[208:211], v[100:103]
	v_mfma_f32_16x16x32_bf16 v[92:95], v[164:167], v[208:211], v[92:95]
	v_mfma_f32_16x16x32_bf16 v[84:87], v[156:159], v[216:219], v[84:87]
	v_mfma_f32_16x16x32_bf16 v[76:79], v[164:167], v[216:219], v[76:79]
	s_setprio 0
	s_setprio 1
	v_mfma_f32_16x16x32_bf16 v[116:119], v[168:171], v[184:187], v[116:119]
	v_mfma_f32_16x16x32_bf16 v[108:111], v[176:179], v[184:187], v[108:111]
	v_mfma_f32_16x16x32_bf16 v[96:99], v[168:171], v[192:195], v[96:99]
	v_mfma_f32_16x16x32_bf16 v[88:91], v[176:179], v[192:195], v[88:91]
	v_mfma_f32_16x16x32_bf16 v[80:83], v[168:171], v[204:207], v[80:83]
	v_mfma_f32_16x16x32_bf16 v[72:75], v[176:179], v[204:207], v[72:75]
	v_mfma_f32_16x16x32_bf16 v[68:71], v[168:171], v[212:215], v[68:71]
	v_mfma_f32_16x16x32_bf16 v[64:67], v[176:179], v[212:215], v[64:67]
	v_mfma_f32_16x16x32_bf16 v[116:119], v[172:175], v[188:191], v[116:119]
	v_mfma_f32_16x16x32_bf16 v[108:111], v[180:183], v[188:191], v[108:111]
	v_mfma_f32_16x16x32_bf16 v[96:99], v[172:175], v[200:203], v[96:99]
	v_mfma_f32_16x16x32_bf16 v[88:91], v[180:183], v[200:203], v[88:91]
	v_mfma_f32_16x16x32_bf16 v[80:83], v[172:175], v[208:211], v[80:83]
	v_mfma_f32_16x16x32_bf16 v[72:75], v[180:183], v[208:211], v[72:75]
	v_mfma_f32_16x16x32_bf16 v[68:71], v[172:175], v[216:219], v[68:71]
	v_mfma_f32_16x16x32_bf16 v[64:67], v[180:183], v[216:219], v[64:67]
	s_setprio 0
	s_barrier
	ds_read_b128 v[184:187], v151 offset:16384
	ds_read_b128 v[188:191], v151 offset:17408
	ds_read_b128 v[192:195], v151 offset:18432
	ds_read_b128 v[200:203], v151 offset:19456
	ds_read_b128 v[204:207], v151 offset:20480
	ds_read_b128 v[208:211], v151 offset:21504
	ds_read_b128 v[212:215], v151 offset:22528
	ds_read_b128 v[216:219], v151 offset:23552
	global_load_lds_dwordx4 v130, s[70:71]
	s_add_i32 m0, s84, 0x2000
	s_add_u32 s84, s70, 0x80000
	s_addc_u32 s85, s71, 0
	s_add_i32 s86, s79, s5
	global_load_lds_dwordx4 v134, s[70:71]
	s_mov_b32 m0, s86
	s_nop 0
	global_load_lds_dwordx4 v130, s[84:85]
	s_add_i32 m0, s86, 0x2000
	s_nop 0
	global_load_lds_dwordx4 v134, s[84:85]
	s_mov_b32 m0, s6
	s_nop 0
	global_load_lds_dwordx4 v128, s[72:73]
	s_mov_b32 m0, s7
	s_nop 0
	global_load_lds_dwordx4 v132, s[72:73]
	s_waitcnt vmcnt(8)
	s_waitcnt lgkmcnt(0)
	s_barrier
	s_setprio 1
	s_waitcnt lgkmcnt(0)
	v_mfma_f32_16x16x32_bf16 v[60:63], v[152:155], v[184:187], v[60:63]
	v_mfma_f32_16x16x32_bf16 v[56:59], v[160:163], v[184:187], v[56:59]
	v_mfma_f32_16x16x32_bf16 v[52:55], v[152:155], v[192:195], v[52:55]
	v_mfma_f32_16x16x32_bf16 v[44:47], v[160:163], v[192:195], v[44:47]
	v_mfma_f32_16x16x32_bf16 v[36:39], v[152:155], v[204:207], v[36:39]
	v_mfma_f32_16x16x32_bf16 v[28:31], v[160:163], v[204:207], v[28:31]
	v_mfma_f32_16x16x32_bf16 v[20:23], v[152:155], v[212:215], v[20:23]
	v_mfma_f32_16x16x32_bf16 v[12:15], v[160:163], v[212:215], v[12:15]
	v_mfma_f32_16x16x32_bf16 v[60:63], v[156:159], v[188:191], v[60:63]
	v_mfma_f32_16x16x32_bf16 v[56:59], v[164:167], v[188:191], v[56:59]
	v_mfma_f32_16x16x32_bf16 v[52:55], v[156:159], v[200:203], v[52:55]
	v_mfma_f32_16x16x32_bf16 v[44:47], v[164:167], v[200:203], v[44:47]
	v_mfma_f32_16x16x32_bf16 v[36:39], v[156:159], v[208:211], v[36:39]
	v_mfma_f32_16x16x32_bf16 v[28:31], v[164:167], v[208:211], v[28:31]
	v_mfma_f32_16x16x32_bf16 v[20:23], v[156:159], v[216:219], v[20:23]
	v_mfma_f32_16x16x32_bf16 v[12:15], v[164:167], v[216:219], v[12:15]
	s_setprio 0
	s_setprio 1
	v_mfma_f32_16x16x32_bf16 v[48:51], v[168:171], v[184:187], v[48:51]
	v_mfma_f32_16x16x32_bf16 v[40:43], v[176:179], v[184:187], v[40:43]
	v_mfma_f32_16x16x32_bf16 v[32:35], v[168:171], v[192:195], v[32:35]
	v_mfma_f32_16x16x32_bf16 v[24:27], v[176:179], v[192:195], v[24:27]
	v_mfma_f32_16x16x32_bf16 v[16:19], v[168:171], v[204:207], v[16:19]
	v_mfma_f32_16x16x32_bf16 v[8:11], v[176:179], v[204:207], v[8:11]
	v_mfma_f32_16x16x32_bf16 v[4:7], v[168:171], v[212:215], v[4:7]
	v_mfma_f32_16x16x32_bf16 v[0:3], v[176:179], v[212:215], v[0:3]
	v_mfma_f32_16x16x32_bf16 v[48:51], v[172:175], v[188:191], v[48:51]
	v_mfma_f32_16x16x32_bf16 v[40:43], v[180:183], v[188:191], v[40:43]
	v_mfma_f32_16x16x32_bf16 v[32:35], v[172:175], v[200:203], v[32:35]
	v_mfma_f32_16x16x32_bf16 v[24:27], v[180:183], v[200:203], v[24:27]
	v_mfma_f32_16x16x32_bf16 v[16:19], v[172:175], v[208:211], v[16:19]
	v_mfma_f32_16x16x32_bf16 v[8:11], v[180:183], v[208:211], v[8:11]
	v_mfma_f32_16x16x32_bf16 v[4:7], v[172:175], v[216:219], v[4:7]
	v_mfma_f32_16x16x32_bf16 v[0:3], v[180:183], v[216:219], v[0:3]
	s_setprio 0
	s_barrier
; #define PG8_STAGE(bufoff, gbase, voff) do { _Pragma("unroll") for (int _i = 0; _i < 2; ++_i) \
;         __builtin_amdgcn_global_load_lds((const unsigned*)((const char*)(gbase) + (voff)[_i]), (PG8_LAS unsigned*)(lds + (bufoff) + ldsw + _i * 8192), 16, 0, 0); } while (0)
; #define PG8_LDA(dst, b, h) do { _Pragma("unroll") for (int m = 0; m < 4; ++m) _Pragma("unroll") for (int k = 0; k < 2; ++k) dst[m][k] = *(const PG8_LAS bf16x8*)(lds + PG8_SA(b, h) + aoff + m * 2048 + k * 1024); } while (0)
; #define PG8_LDB(dst, b, h) do { _Pragma("unroll") for (int n = 0; n < 2; ++n) _Pragma("unroll") for (int k = 0; k < 2; ++k) dst[n][k] = *(const PG8_LAS bf16x8*)(lds + PG8_SB(b, h) + boff + n * 2048 + k * 1024); } while (0)
; #define PG8_MMA(ai, bj, At, Bt) do { __builtin_amdgcn_s_setprio(1); _Pragma("unroll") for (int m = 0; m < 4; ++m) _Pragma("unroll") for (int n = 0; n < 2; ++n) _Pragma("unroll") for (int k = 0; k < 2; ++k) \
;         acc[ai][bj][m][n] = __builtin_amdgcn_mfma_f32_16x16x32_bf16(Bt[n][k], At[m][k], acc[ai][bj][m][n], 0, 0, 0); __builtin_amdgcn_s_setprio(0); } while (0)
; #define PG8_WAIT_V(n) asm volatile("s_waitcnt vmcnt(" #n ")" ::: "memory")
; #define PG8_WAIT_L(n) asm volatile("s_waitcnt lgkmcnt(" #n ")" ::: "memory")
; #define PG8_BAR __builtin_amdgcn_s_barrier()
; #define PG8_SCHED __builtin_amdgcn_sched_barrier(0)
; template <class Epi, class Sched, bool ALIGN_EPI = false, bool SP2 = false>
; __device__ __forceinline__ void gemm_phase(PG8_LAS unsigned char* lds, const Gemm g, const Sched& S, const Epi& E) {
;     ...
;         for (int t = 0; t < nt; t += 2) {
;     ...
;             PG8_LDB(B0, 1, 0); PG8_LDB(B1, 1, 1); PG8_SCHED; PG8_LDA(At, 1, 0); PG8_STAGE(PG8_SA(0, 1), a2 + hstep, voffA);
;             PG8_WAIT_V(8); PG8_WAIT_L(0); PG8_BAR; PG8_MMA(0, 0, At, B0); PG8_MMA(0, 1, At, B1); PG8_BAR; PG8_SCHED;
;             PG8_LDA(At, 1, 1); PG8_STAGE(PG8_SB(1, 0), b3, voffB); PG8_STAGE(PG8_SB(1, 1), b3 + hstep, voffB); PG8_STAGE(PG8_SA(1, 0), a3, voffA);
;             PG8_WAIT_V(8); PG8_WAIT_L(0); PG8_BAR; PG8_MMA(1, 0, At, B0); PG8_MMA(1, 1, At, B1); PG8_BAR; PG8_SCHED;
	ds_read_b128 v[152:155], v198
	ds_read_b128 v[156:159], v198 offset:1024
	ds_read_b128 v[160:163], v198 offset:2048
	ds_read_b128 v[164:167], v198 offset:3072
	ds_read_b128 v[168:171], v199
	ds_read_b128 v[172:175], v199 offset:1024
	ds_read_b128 v[176:179], v199 offset:2048
	ds_read_b128 v[180:183], v199 offset:3072
	ds_read_b128 v[184:187], v151 offset:32768
	ds_read_b128 v[188:191], v151 offset:33792
	ds_read_b128 v[192:195], v151 offset:34816
	ds_read_b128 v[200:203], v151 offset:35840
	ds_read_b128 v[204:207], v151 offset:36864
	ds_read_b128 v[208:211], v151 offset:37888
	ds_read_b128 v[212:215], v151 offset:38912
	ds_read_b128 v[216:219], v151 offset:39936
	s_add_u32 s98, s72, 0x80000
	s_addc_u32 s99, s73, 0
	s_mov_b32 m0, s14
	s_add_u32 s100, s72, 0x80
	s_addc_u32 s101, s73, 0
	global_load_lds_dwordx4 v128, s[98:99]
	s_mov_b32 m0, s15
	s_nop 0
	global_load_lds_dwordx4 v132, s[98:99]
	s_add_i32 s84, 0, 0x18000
	s_add_i32 s85, 0, 0x1c000
	s_add_u32 s98, s70, 0x80
	s_addc_u32 s99, s71, 0
	s_add_i32 s72, s84, s5
	s_mov_b32 m0, s72
	s_waitcnt vmcnt(8)
	s_waitcnt lgkmcnt(0)
	s_barrier
	s_setprio 1
	s_waitcnt lgkmcnt(0)
	v_mfma_f32_16x16x32_bf16 v[124:127], v[152:155], v[184:187], v[124:127]
	v_mfma_f32_16x16x32_bf16 v[120:123], v[160:163], v[184:187], v[120:123]
	v_mfma_f32_16x16x32_bf16 v[112:115], v[152:155], v[192:195], v[112:115]
	v_mfma_f32_16x16x32_bf16 v[104:107], v[160:163], v[192:195], v[104:107]
	v_mfma_f32_16x16x32_bf16 v[100:103], v[152:155], v[204:207], v[100:103]
	v_mfma_f32_16x16x32_bf16 v[92:95], v[160:163], v[204:207], v[92:95]
	v_mfma_f32_16x16x32_bf16 v[84:87], v[152:155], v[212:215], v[84:87]
	v_mfma_f32_16x16x32_bf16 v[76:79], v[160:163], v[212:215], v[76:79]
	v_mfma_f32_16x16x32_bf16 v[124:127], v[156:159], v[188:191], v[124:127]
	v_mfma_f32_16x16x32_bf16 v[120:123], v[164:167], v[188:191], v[120:123]
	v_mfma_f32_16x16x32_bf16 v[112:115], v[156:159], v[200:203], v[112:115]
	v_mfma_f32_16x16x32_bf16 v[104:107], v[164:167], v[200:203], v[104:107]
	v_mfma_f32_16x16x32_bf16 v[100:103], v[156:159], v[208:211], v[100:103]
	v_mfma_f32_16x16x32_bf16 v[92:95], v[164:167], v[208:211], v[92:95]
	v_mfma_f32_16x16x32_bf16 v[84:87], v[156:159], v[216:219], v[84:87]
	v_mfma_f32_16x16x32_bf16 v[76:79], v[164:167], v[216:219], v[76:79]
	s_setprio 0
	s_setprio 1
	v_mfma_f32_16x16x32_bf16 v[116:119], v[168:171], v[184:187], v[116:119]
	v_mfma_f32_16x16x32_bf16 v[108:111], v[176:179], v[184:187], v[108:111]
	v_mfma_f32_16x16x32_bf16 v[96:99], v[168:171], v[192:195], v[96:99]
	v_mfma_f32_16x16x32_bf16 v[88:91], v[176:179], v[192:195], v[88:91]
	v_mfma_f32_16x16x32_bf16 v[80:83], v[168:171], v[204:207], v[80:83]
	v_mfma_f32_16x16x32_bf16 v[72:75], v[176:179], v[204:207], v[72:75]
	v_mfma_f32_16x16x32_bf16 v[68:71], v[168:171], v[212:215], v[68:71]
	v_mfma_f32_16x16x32_bf16 v[64:67], v[176:179], v[212:215], v[64:67]
	v_mfma_f32_16x16x32_bf16 v[116:119], v[172:175], v[188:191], v[116:119]
	v_mfma_f32_16x16x32_bf16 v[108:111], v[180:183], v[188:191], v[108:111]
	v_mfma_f32_16x16x32_bf16 v[96:99], v[172:175], v[200:203], v[96:99]
	v_mfma_f32_16x16x32_bf16 v[88:91], v[180:183], v[200:203], v[88:91]
	v_mfma_f32_16x16x32_bf16 v[80:83], v[172:175], v[208:211], v[80:83]
	v_mfma_f32_16x16x32_bf16 v[72:75], v[180:183], v[208:211], v[72:75]
	v_mfma_f32_16x16x32_bf16 v[68:71], v[172:175], v[216:219], v[68:71]
	v_mfma_f32_16x16x32_bf16 v[64:67], v[180:183], v[216:219], v[64:67]
	s_setprio 0
	s_barrier
	ds_read_b128 v[184:187], v151 offset:49152
	ds_read_b128 v[188:191], v151 offset:50176
	ds_read_b128 v[192:195], v151 offset:51200
	ds_read_b128 v[200:203], v151 offset:52224
	ds_read_b128 v[204:207], v151 offset:53248
	ds_read_b128 v[208:211], v151 offset:54272
	ds_read_b128 v[212:215], v151 offset:55296
	ds_read_b128 v[216:219], v151 offset:56320
	global_load_lds_dwordx4 v130, s[98:99]
	s_add_i32 m0, s72, 0x2000
	s_add_u32 s70, s70, 0x80080
	s_addc_u32 s71, s71, 0
	s_add_i32 s72, s85, s5
	global_load_lds_dwordx4 v134, s[98:99]
	s_mov_b32 m0, s72
	s_nop 0
	global_load_lds_dwordx4 v130, s[70:71]
	s_add_i32 m0, s72, 0x2000
	s_nop 0
	global_load_lds_dwordx4 v134, s[70:71]
	s_mov_b32 m0, s74
	s_nop 0
	global_load_lds_dwordx4 v128, s[100:101]
	s_mov_b32 m0, s75
	s_nop 0
	global_load_lds_dwordx4 v132, s[100:101]
	s_add_i32 s83, s83, 2
	s_add_u32 s68, s68, 0x100
	s_addc_u32 s69, s69, 0
	s_add_u32 s81, s81, 0x100
	s_addc_u32 s82, s82, 0
	s_cmp_gt_u32 s83, 29
	s_waitcnt vmcnt(8)
	s_waitcnt lgkmcnt(0)
	s_barrier
	s_setprio 1
	s_waitcnt lgkmcnt(0)
	v_mfma_f32_16x16x32_bf16 v[60:63], v[152:155], v[184:187], v[60:63]
	v_mfma_f32_16x16x32_bf16 v[56:59], v[160:163], v[184:187], v[56:59]
	v_mfma_f32_16x16x32_bf16 v[52:55], v[152:155], v[192:195], v[52:55]
	v_mfma_f32_16x16x32_bf16 v[44:47], v[160:163], v[192:195], v[44:47]
	v_mfma_f32_16x16x32_bf16 v[36:39], v[152:155], v[204:207], v[36:39]
	v_mfma_f32_16x16x32_bf16 v[28:31], v[160:163], v[204:207], v[28:31]
	v_mfma_f32_16x16x32_bf16 v[20:23], v[152:155], v[212:215], v[20:23]
	v_mfma_f32_16x16x32_bf16 v[12:15], v[160:163], v[212:215], v[12:15]
	v_mfma_f32_16x16x32_bf16 v[60:63], v[156:159], v[188:191], v[60:63]
	v_mfma_f32_16x16x32_bf16 v[56:59], v[164:167], v[188:191], v[56:59]
	v_mfma_f32_16x16x32_bf16 v[52:55], v[156:159], v[200:203], v[52:55]
	v_mfma_f32_16x16x32_bf16 v[44:47], v[164:167], v[200:203], v[44:47]
	v_mfma_f32_16x16x32_bf16 v[36:39], v[156:159], v[208:211], v[36:39]
	v_mfma_f32_16x16x32_bf16 v[28:31], v[164:167], v[208:211], v[28:31]
	v_mfma_f32_16x16x32_bf16 v[20:23], v[156:159], v[216:219], v[20:23]
	v_mfma_f32_16x16x32_bf16 v[12:15], v[164:167], v[216:219], v[12:15]
	s_setprio 0
	s_setprio 1
	v_mfma_f32_16x16x32_bf16 v[48:51], v[168:171], v[184:187], v[48:51]
	v_mfma_f32_16x16x32_bf16 v[40:43], v[176:179], v[184:187], v[40:43]
	v_mfma_f32_16x16x32_bf16 v[32:35], v[168:171], v[192:195], v[32:35]
	v_mfma_f32_16x16x32_bf16 v[24:27], v[176:179], v[192:195], v[24:27]
	v_mfma_f32_16x16x32_bf16 v[16:19], v[168:171], v[204:207], v[16:19]
	v_mfma_f32_16x16x32_bf16 v[8:11], v[176:179], v[204:207], v[8:11]
	v_mfma_f32_16x16x32_bf16 v[4:7], v[168:171], v[212:215], v[4:7]
	v_mfma_f32_16x16x32_bf16 v[0:3], v[176:179], v[212:215], v[0:3]
	v_mfma_f32_16x16x32_bf16 v[48:51], v[172:175], v[188:191], v[48:51]
	v_mfma_f32_16x16x32_bf16 v[40:43], v[180:183], v[188:191], v[40:43]
	v_mfma_f32_16x16x32_bf16 v[32:35], v[172:175], v[200:203], v[32:35]
	v_mfma_f32_16x16x32_bf16 v[24:27], v[180:183], v[200:203], v[24:27]
	v_mfma_f32_16x16x32_bf16 v[16:19], v[172:175], v[208:211], v[16:19]
	v_mfma_f32_16x16x32_bf16 v[8:11], v[180:183], v[208:211], v[8:11]
	v_mfma_f32_16x16x32_bf16 v[4:7], v[172:175], v[216:219], v[4:7]
	v_mfma_f32_16x16x32_bf16 v[0:3], v[180:183], v[216:219], v[0:3]
	s_setprio 0
	s_barrier
	s_cbranch_scc0 .LBB0_759
	s_and_b64 vcc, exec, s[46:47]
	s_cbranch_vccz .LBB0_762
	s_barrier

; #define PG8_STAGE(bufoff, gbase, voff) do { _Pragma("unroll") for (int _i = 0; _i < 2; ++_i) \
;         __builtin_amdgcn_global_load_lds((const unsigned*)((const char*)(gbase) + (voff)[_i]), (PG8_LAS unsigned*)(lds + (bufoff) + ldsw + _i * 8192), 16, 0, 0); } while (0)
; #define PG8_LDA(dst, b, h) do { _Pragma("unroll") for (int m = 0; m < 4; ++m) _Pragma("unroll") for (int k = 0; k < 2; ++k) dst[m][k] = *(const PG8_LAS bf16x8*)(lds + PG8_SA(b, h) + aoff + m * 2048 + k * 1024); } while (0)
; #define PG8_LDB(dst, b, h) do { _Pragma("unroll") for (int n = 0; n < 2; ++n) _Pragma("unroll") for (int k = 0; k < 2; ++k) dst[n][k] = *(const PG8_LAS bf16x8*)(lds + PG8_SB(b, h) + boff + n * 2048 + k * 1024); } while (0)
; #define PG8_MMA(ai, bj, At, Bt) do { __builtin_amdgcn_s_setprio(1); _Pragma("unroll") for (int m = 0; m < 4; ++m) _Pragma("unroll") for (int n = 0; n < 2; ++n) _Pragma("unroll") for (int k = 0; k < 2; ++k) \
;         acc[ai][bj][m][n] = __builtin_amdgcn_mfma_f32_16x16x32_bf16(Bt[n][k], At[m][k], acc[ai][bj][m][n], 0, 0, 0); __builtin_amdgcn_s_setprio(0); } while (0)
; #define PG8_WAIT_V(n) asm volatile("s_waitcnt vmcnt(" #n ")" ::: "memory")
; #define PG8_WAIT_L(n) asm volatile("s_waitcnt lgkmcnt(" #n ")" ::: "memory")
; #define PG8_BAR __builtin_amdgcn_s_barrier()
; template <class Epi, class Sched, bool ALIGN_EPI = false, bool SP2 = false>
; __device__ __forceinline__ void gemm_phase(PG8_LAS unsigned char* lds, const Gemm g, const Sched& S, const Epi& E) {
;     ...
;             const char* a1 = cA + (size_t)(t + 1) * kstep;
;             const char* a2 = last ? nA : cA + (size_t)(t + 2) * kstep; const char* b2 = last ? nB : cB + (size_t)(t + 2) * kstep;
;             const char* a3 = a2 + kstep; const char* b3 = b2 + kstep;
;             if (last && has_next) S.a_ready(nxt);
;             if constexpr (SP2) {
;             PG8_LDB(B0, 0, 0); PG8_LDB(B1, 0, 1); PG8_SCHED; PG8_LDA(At, 0, 0); PG8_STAGE(PG8_SA(1, 1), a1 + hstep, voffA);
;             PG8_WAIT_V(8); PG8_WAIT_L(0); PG8_BAR; PG8_MMA(0, 0, At, B0); PG8_MMA(0, 1, At, B1); PG8_BAR; PG8_SCHED;
;             PG8_LDA(At, 0, 1); PG8_STAGE(PG8_SB(0, 0), b2, voffB); PG8_STAGE(PG8_SB(0, 1), b2 + hstep, voffB); PG8_STAGE(PG8_SA(0, 0), a2, voffA);
;             PG8_WAIT_V(8); PG8_WAIT_L(0); PG8_BAR; PG8_MMA(1, 0, At, B0); PG8_MMA(1, 1, At, B1); PG8_BAR; PG8_SCHED;
.LBB0_1053:
	ds_read_b128 v[128:131], v202
	ds_read_b128 v[132:135], v202 offset:1024
	ds_read_b128 v[136:139], v202 offset:2048
	ds_read_b128 v[140:143], v202 offset:3072
	ds_read_b128 v[144:147], v203
	ds_read_b128 v[148:151], v203 offset:1024
	ds_read_b128 v[152:155], v203 offset:2048
	ds_read_b128 v[156:159], v203 offset:3072
	s_add_i32 m0, s3, 0xc000
	ds_read_b128 v[160:163], v204
	ds_read_b128 v[164:167], v204 offset:1024
	ds_read_b128 v[184:187], v204 offset:2048
	ds_read_b128 v[188:191], v204 offset:3072
	ds_read_b128 v[192:195], v204 offset:4096
	ds_read_b128 v[206:209], v204 offset:5120
	ds_read_b128 v[210:213], v204 offset:6144
	ds_read_b128 v[214:217], v204 offset:7168
	global_load_lds_dwordx4 v176, s[60:61]
	s_add_i32 m0, s3, 0xe000
	s_nop 0
	global_load_lds_dwordx4 v178, s[60:61]
	s_add_u32 s62, s60, 0xfff80080
	s_addc_u32 s63, s61, -1
	s_cmp_eq_u32 s72, 28
	s_cselect_b32 s65, s25, s63
	s_cselect_b32 s64, s43, s62
	s_cselect_b32 s63, s39, s71
	s_cselect_b32 s62, s69, s70
	s_add_i32 s73, s67, s1
	s_mov_b32 m0, s73
	s_waitcnt vmcnt(8)
	s_waitcnt lgkmcnt(0)
	s_barrier
	s_setprio 1
	s_waitcnt lgkmcnt(0)
	v_mfma_f32_16x16x32_bf16 v[124:127], v[128:131], v[160:163], v[124:127]
	v_mfma_f32_16x16x32_bf16 v[120:123], v[136:139], v[160:163], v[120:123]
	v_mfma_f32_16x16x32_bf16 v[116:119], v[128:131], v[184:187], v[116:119]
	v_mfma_f32_16x16x32_bf16 v[108:111], v[136:139], v[184:187], v[108:111]
	v_mfma_f32_16x16x32_bf16 v[92:95], v[128:131], v[192:195], v[92:95]
	v_mfma_f32_16x16x32_bf16 v[88:91], v[136:139], v[192:195], v[88:91]
	v_mfma_f32_16x16x32_bf16 v[76:79], v[128:131], v[210:213], v[76:79]
	v_mfma_f32_16x16x32_bf16 v[72:75], v[136:139], v[210:213], v[72:75]
	v_mfma_f32_16x16x32_bf16 v[124:127], v[132:135], v[164:167], v[124:127]
	v_mfma_f32_16x16x32_bf16 v[120:123], v[140:143], v[164:167], v[120:123]
	v_mfma_f32_16x16x32_bf16 v[116:119], v[132:135], v[188:191], v[116:119]
	v_mfma_f32_16x16x32_bf16 v[108:111], v[140:143], v[188:191], v[108:111]
	v_mfma_f32_16x16x32_bf16 v[92:95], v[132:135], v[206:209], v[92:95]
	v_mfma_f32_16x16x32_bf16 v[88:91], v[140:143], v[206:209], v[88:91]
	v_mfma_f32_16x16x32_bf16 v[76:79], v[132:135], v[214:217], v[76:79]
	v_mfma_f32_16x16x32_bf16 v[72:75], v[140:143], v[214:217], v[72:75]
	s_setprio 0
	s_setprio 1
	v_mfma_f32_16x16x32_bf16 v[112:115], v[144:147], v[160:163], v[112:115]
	v_mfma_f32_16x16x32_bf16 v[104:107], v[152:155], v[160:163], v[104:107]
	v_mfma_f32_16x16x32_bf16 v[100:103], v[144:147], v[184:187], v[100:103]
	v_mfma_f32_16x16x32_bf16 v[96:99], v[152:155], v[184:187], v[96:99]
	v_mfma_f32_16x16x32_bf16 v[84:87], v[144:147], v[192:195], v[84:87]
	v_mfma_f32_16x16x32_bf16 v[80:83], v[152:155], v[192:195], v[80:83]
	v_mfma_f32_16x16x32_bf16 v[68:71], v[144:147], v[210:213], v[68:71]
	v_mfma_f32_16x16x32_bf16 v[64:67], v[152:155], v[210:213], v[64:67]
	v_mfma_f32_16x16x32_bf16 v[112:115], v[148:151], v[164:167], v[112:115]
	v_mfma_f32_16x16x32_bf16 v[104:107], v[156:159], v[164:167], v[104:107]
	v_mfma_f32_16x16x32_bf16 v[100:103], v[148:151], v[188:191], v[100:103]
	v_mfma_f32_16x16x32_bf16 v[96:99], v[156:159], v[188:191], v[96:99]
	v_mfma_f32_16x16x32_bf16 v[84:87], v[148:151], v[206:209], v[84:87]
	v_mfma_f32_16x16x32_bf16 v[80:83], v[156:159], v[206:209], v[80:83]
	v_mfma_f32_16x16x32_bf16 v[68:71], v[148:151], v[214:217], v[68:71]
	v_mfma_f32_16x16x32_bf16 v[64:67], v[156:159], v[214:217], v[64:67]
	s_setprio 0
	s_barrier
	ds_read_b128 v[160:163], v204 offset:16384
	ds_read_b128 v[164:167], v204 offset:17408
	ds_read_b128 v[184:187], v204 offset:18432
	ds_read_b128 v[188:191], v204 offset:19456
	ds_read_b128 v[192:195], v204 offset:20480
	ds_read_b128 v[206:209], v204 offset:21504
	ds_read_b128 v[210:213], v204 offset:22528
	ds_read_b128 v[214:217], v204 offset:23552
	global_load_lds_dwordx4 v170, s[62:63]
	s_add_i32 m0, s73, 0x2000
	s_add_u32 s74, s62, 0x80000
	s_addc_u32 s75, s63, 0
	s_add_i32 s73, s68, s1
	global_load_lds_dwordx4 v174, s[62:63]
	s_mov_b32 m0, s73
	s_nop 0
	global_load_lds_dwordx4 v170, s[74:75]
	s_add_i32 m0, s73, 0x2000
	s_nop 0
	global_load_lds_dwordx4 v174, s[74:75]
	s_mov_b32 m0, s3
	s_nop 0
	global_load_lds_dwordx4 v168, s[64:65]
	s_mov_b32 m0, s4
	s_nop 0
	global_load_lds_dwordx4 v172, s[64:65]
	s_waitcnt vmcnt(8)
	s_waitcnt lgkmcnt(0)
	s_barrier
	s_setprio 1
	s_waitcnt lgkmcnt(0)
	v_mfma_f32_16x16x32_bf16 v[60:63], v[128:131], v[160:163], v[60:63]
	v_mfma_f32_16x16x32_bf16 v[56:59], v[136:139], v[160:163], v[56:59]
	v_mfma_f32_16x16x32_bf16 v[44:47], v[128:131], v[184:187], v[44:47]
	v_mfma_f32_16x16x32_bf16 v[40:43], v[136:139], v[184:187], v[40:43]
	v_mfma_f32_16x16x32_bf16 v[28:31], v[128:131], v[192:195], v[28:31]
	v_mfma_f32_16x16x32_bf16 v[24:27], v[136:139], v[192:195], v[24:27]
	v_mfma_f32_16x16x32_bf16 v[12:15], v[128:131], v[210:213], v[12:15]
	v_mfma_f32_16x16x32_bf16 v[8:11], v[136:139], v[210:213], v[8:11]
	v_mfma_f32_16x16x32_bf16 v[60:63], v[132:135], v[164:167], v[60:63]
	v_mfma_f32_16x16x32_bf16 v[56:59], v[140:143], v[164:167], v[56:59]
	v_mfma_f32_16x16x32_bf16 v[44:47], v[132:135], v[188:191], v[44:47]
	v_mfma_f32_16x16x32_bf16 v[40:43], v[140:143], v[188:191], v[40:43]
	v_mfma_f32_16x16x32_bf16 v[28:31], v[132:135], v[206:209], v[28:31]
	v_mfma_f32_16x16x32_bf16 v[24:27], v[140:143], v[206:209], v[24:27]
	v_mfma_f32_16x16x32_bf16 v[12:15], v[132:135], v[214:217], v[12:15]
	v_mfma_f32_16x16x32_bf16 v[8:11], v[140:143], v[214:217], v[8:11]
	s_setprio 0
	s_setprio 1
	v_mfma_f32_16x16x32_bf16 v[52:55], v[144:147], v[160:163], v[52:55]
	v_mfma_f32_16x16x32_bf16 v[48:51], v[152:155], v[160:163], v[48:51]
	v_mfma_f32_16x16x32_bf16 v[36:39], v[144:147], v[184:187], v[36:39]
	v_mfma_f32_16x16x32_bf16 v[32:35], v[152:155], v[184:187], v[32:35]
	v_mfma_f32_16x16x32_bf16 v[20:23], v[144:147], v[192:195], v[20:23]
	v_mfma_f32_16x16x32_bf16 v[16:19], v[152:155], v[192:195], v[16:19]
	v_mfma_f32_16x16x32_bf16 v[4:7], v[144:147], v[210:213], v[4:7]
	v_mfma_f32_16x16x32_bf16 v[0:3], v[152:155], v[210:213], v[0:3]
	v_mfma_f32_16x16x32_bf16 v[52:55], v[148:151], v[164:167], v[52:55]
	v_mfma_f32_16x16x32_bf16 v[48:51], v[156:159], v[164:167], v[48:51]
	v_mfma_f32_16x16x32_bf16 v[36:39], v[148:151], v[188:191], v[36:39]
	v_mfma_f32_16x16x32_bf16 v[32:35], v[156:159], v[188:191], v[32:35]
	v_mfma_f32_16x16x32_bf16 v[20:23], v[148:151], v[206:209], v[20:23]
	v_mfma_f32_16x16x32_bf16 v[16:19], v[156:159], v[206:209], v[16:19]
	v_mfma_f32_16x16x32_bf16 v[4:7], v[148:151], v[214:217], v[4:7]
	v_mfma_f32_16x16x32_bf16 v[0:3], v[156:159], v[214:217], v[0:3]
	s_setprio 0
	s_barrier
; #define PG8_STAGE(bufoff, gbase, voff) do { _Pragma("unroll") for (int _i = 0; _i < 2; ++_i) \
;         __builtin_amdgcn_global_load_lds((const unsigned*)((const char*)(gbase) + (voff)[_i]), (PG8_LAS unsigned*)(lds + (bufoff) + ldsw + _i * 8192), 16, 0, 0); } while (0)
; #define PG8_LDA(dst, b, h) do { _Pragma("unroll") for (int m = 0; m < 4; ++m) _Pragma("unroll") for (int k = 0; k < 2; ++k) dst[m][k] = *(const PG8_LAS bf16x8*)(lds + PG8_SA(b, h) + aoff + m * 2048 + k * 1024); } while (0)
; #define PG8_LDB(dst, b, h) do { _Pragma("unroll") for (int n = 0; n < 2; ++n) _Pragma("unroll") for (int k = 0; k < 2; ++k) dst[n][k] = *(const PG8_LAS bf16x8*)(lds + PG8_SB(b, h) + boff + n * 2048 + k * 1024); } while (0)
; #define PG8_MMA(ai, bj, At, Bt) do { __builtin_amdgcn_s_setprio(1); _Pragma("unroll") for (int m = 0; m < 4; ++m) _Pragma("unroll") for (int n = 0; n < 2; ++n) _Pragma("unroll") for (int k = 0; k < 2; ++k) \
;         acc[ai][bj][m][n] = __builtin_amdgcn_mfma_f32_16x16x32_bf16(Bt[n][k], At[m][k], acc[ai][bj][m][n], 0, 0, 0); __builtin_amdgcn_s_setprio(0); } while (0)
; #define PG8_WAIT_V(n) asm volatile("s_waitcnt vmcnt(" #n ")" ::: "memory")
; #define PG8_WAIT_L(n) asm volatile("s_waitcnt lgkmcnt(" #n ")" ::: "memory")
; #define PG8_BAR __builtin_amdgcn_s_barrier()
; #define PG8_SCHED __builtin_amdgcn_sched_barrier(0)
; template <class Epi, class Sched, bool ALIGN_EPI = false, bool SP2 = false>
; __device__ __forceinline__ void gemm_phase(PG8_LAS unsigned char* lds, const Gemm g, const Sched& S, const Epi& E) {
;     ...
;         for (int t = 0; t < nt; t += 2) {
;             const bool last = (t == nt - 2);
;             const char* a1 = cA + (size_t)(t + 1) * kstep;
;             const char* a2 = last ? nA : cA + (size_t)(t + 2) * kstep; const char* b2 = last ? nB : cB + (size_t)(t + 2) * kstep;
;     ...
;             PG8_LDB(B0, 1, 0); PG8_LDB(B1, 1, 1); PG8_SCHED; PG8_LDA(At, 1, 0); PG8_STAGE(PG8_SA(0, 1), a2 + hstep, voffA);
;             PG8_WAIT_V(8); PG8_WAIT_L(0); PG8_BAR; PG8_MMA(0, 0, At, B0); PG8_MMA(0, 1, At, B1); PG8_BAR; PG8_SCHED;
;             PG8_LDA(At, 1, 1); PG8_STAGE(PG8_SB(1, 0), b3, voffB); PG8_STAGE(PG8_SB(1, 1), b3 + hstep, voffB); PG8_STAGE(PG8_SA(1, 0), a3, voffA);
;             PG8_WAIT_V(8); PG8_WAIT_L(0); PG8_BAR; PG8_MMA(1, 0, At, B0); PG8_MMA(1, 1, At, B1); PG8_BAR; PG8_SCHED;
	ds_read_b128 v[128:131], v218
	ds_read_b128 v[132:135], v218 offset:1024
	ds_read_b128 v[136:139], v218 offset:2048
	ds_read_b128 v[140:143], v218 offset:3072
	ds_read_b128 v[144:147], v219
	ds_read_b128 v[148:151], v219 offset:1024
	ds_read_b128 v[152:155], v219 offset:2048
	ds_read_b128 v[156:159], v219 offset:3072
	ds_read_b128 v[160:163], v204 offset:32768
	ds_read_b128 v[164:167], v204 offset:33792
	ds_read_b128 v[184:187], v204 offset:34816
	ds_read_b128 v[188:191], v204 offset:35840
	ds_read_b128 v[192:195], v204 offset:36864
	ds_read_b128 v[206:209], v204 offset:37888
	ds_read_b128 v[210:213], v204 offset:38912
	ds_read_b128 v[214:217], v204 offset:39936
	s_add_u32 s98, s64, 0x80000
	s_addc_u32 s99, s65, 0
	s_mov_b32 m0, s5
	s_add_u32 s100, s64, 0x80
	s_addc_u32 s101, s65, 0
	global_load_lds_dwordx4 v168, s[98:99]
	s_mov_b32 m0, s14
	s_nop 0
	global_load_lds_dwordx4 v172, s[98:99]
	s_add_i32 s73, 0, 0x18000
	s_add_i32 s74, 0, 0x1c000
	s_add_u32 s98, s62, 0x80
	s_addc_u32 s99, s63, 0
	s_add_i32 s64, s73, s1
	s_mov_b32 m0, s64
	s_waitcnt vmcnt(8)
	s_waitcnt lgkmcnt(0)
	s_barrier
	s_setprio 1
	s_waitcnt lgkmcnt(0)
	v_mfma_f32_16x16x32_bf16 v[124:127], v[128:131], v[160:163], v[124:127]
	v_mfma_f32_16x16x32_bf16 v[120:123], v[136:139], v[160:163], v[120:123]
	v_mfma_f32_16x16x32_bf16 v[116:119], v[128:131], v[184:187], v[116:119]
	v_mfma_f32_16x16x32_bf16 v[108:111], v[136:139], v[184:187], v[108:111]
	v_mfma_f32_16x16x32_bf16 v[92:95], v[128:131], v[192:195], v[92:95]
	v_mfma_f32_16x16x32_bf16 v[88:91], v[136:139], v[192:195], v[88:91]
	v_mfma_f32_16x16x32_bf16 v[76:79], v[128:131], v[210:213], v[76:79]
	v_mfma_f32_16x16x32_bf16 v[72:75], v[136:139], v[210:213], v[72:75]
	v_mfma_f32_16x16x32_bf16 v[124:127], v[132:135], v[164:167], v[124:127]
	v_mfma_f32_16x16x32_bf16 v[120:123], v[140:143], v[164:167], v[120:123]
	v_mfma_f32_16x16x32_bf16 v[116:119], v[132:135], v[188:191], v[116:119]
	v_mfma_f32_16x16x32_bf16 v[108:111], v[140:143], v[188:191], v[108:111]
	v_mfma_f32_16x16x32_bf16 v[92:95], v[132:135], v[206:209], v[92:95]
	v_mfma_f32_16x16x32_bf16 v[88:91], v[140:143], v[206:209], v[88:91]
	v_mfma_f32_16x16x32_bf16 v[76:79], v[132:135], v[214:217], v[76:79]
	v_mfma_f32_16x16x32_bf16 v[72:75], v[140:143], v[214:217], v[72:75]
	s_setprio 0
	s_setprio 1
	v_mfma_f32_16x16x32_bf16 v[112:115], v[144:147], v[160:163], v[112:115]
	v_mfma_f32_16x16x32_bf16 v[104:107], v[152:155], v[160:163], v[104:107]
	v_mfma_f32_16x16x32_bf16 v[100:103], v[144:147], v[184:187], v[100:103]
	v_mfma_f32_16x16x32_bf16 v[96:99], v[152:155], v[184:187], v[96:99]
	v_mfma_f32_16x16x32_bf16 v[84:87], v[144:147], v[192:195], v[84:87]
	v_mfma_f32_16x16x32_bf16 v[80:83], v[152:155], v[192:195], v[80:83]
	v_mfma_f32_16x16x32_bf16 v[68:71], v[144:147], v[210:213], v[68:71]
	v_mfma_f32_16x16x32_bf16 v[64:67], v[152:155], v[210:213], v[64:67]
	v_mfma_f32_16x16x32_bf16 v[112:115], v[148:151], v[164:167], v[112:115]
	v_mfma_f32_16x16x32_bf16 v[104:107], v[156:159], v[164:167], v[104:107]
	v_mfma_f32_16x16x32_bf16 v[100:103], v[148:151], v[188:191], v[100:103]
	v_mfma_f32_16x16x32_bf16 v[96:99], v[156:159], v[188:191], v[96:99]
	v_mfma_f32_16x16x32_bf16 v[84:87], v[148:151], v[206:209], v[84:87]
	v_mfma_f32_16x16x32_bf16 v[80:83], v[156:159], v[206:209], v[80:83]
	v_mfma_f32_16x16x32_bf16 v[68:71], v[148:151], v[214:217], v[68:71]
	v_mfma_f32_16x16x32_bf16 v[64:67], v[156:159], v[214:217], v[64:67]
	s_setprio 0
	s_barrier
	ds_read_b128 v[160:163], v204 offset:49152
	ds_read_b128 v[164:167], v204 offset:50176
	ds_read_b128 v[184:187], v204 offset:51200
	ds_read_b128 v[188:191], v204 offset:52224
	ds_read_b128 v[192:195], v204 offset:53248
	ds_read_b128 v[206:209], v204 offset:54272
	ds_read_b128 v[210:213], v204 offset:55296
	ds_read_b128 v[214:217], v204 offset:56320
	global_load_lds_dwordx4 v170, s[98:99]
	s_add_i32 m0, s64, 0x2000
	s_add_u32 s62, s62, 0x80080
	s_addc_u32 s63, s63, 0
	s_add_i32 s64, s74, s1
	global_load_lds_dwordx4 v174, s[98:99]
	s_mov_b32 m0, s64
	s_nop 0
	global_load_lds_dwordx4 v170, s[62:63]
	s_add_i32 m0, s64, 0x2000
	s_nop 0
	global_load_lds_dwordx4 v174, s[62:63]
	s_mov_b32 m0, s33
	s_nop 0
	global_load_lds_dwordx4 v168, s[100:101]
	s_mov_b32 m0, s35
	s_nop 0
	global_load_lds_dwordx4 v172, s[100:101]
	s_add_i32 s72, s72, 2
	s_add_u32 s60, s60, 0x100
	s_addc_u32 s61, s61, 0
	s_add_u32 s70, s70, 0x100
	s_addc_u32 s71, s71, 0
	s_cmp_gt_u32 s72, 29
	s_waitcnt vmcnt(8)
	s_waitcnt lgkmcnt(0)
	s_barrier
	s_setprio 1
	s_waitcnt lgkmcnt(0)
	v_mfma_f32_16x16x32_bf16 v[60:63], v[128:131], v[160:163], v[60:63]
	v_mfma_f32_16x16x32_bf16 v[56:59], v[136:139], v[160:163], v[56:59]
	v_mfma_f32_16x16x32_bf16 v[44:47], v[128:131], v[184:187], v[44:47]
	v_mfma_f32_16x16x32_bf16 v[40:43], v[136:139], v[184:187], v[40:43]
	v_mfma_f32_16x16x32_bf16 v[28:31], v[128:131], v[192:195], v[28:31]
	v_mfma_f32_16x16x32_bf16 v[24:27], v[136:139], v[192:195], v[24:27]
	v_mfma_f32_16x16x32_bf16 v[12:15], v[128:131], v[210:213], v[12:15]
	v_mfma_f32_16x16x32_bf16 v[8:11], v[136:139], v[210:213], v[8:11]
	v_mfma_f32_16x16x32_bf16 v[60:63], v[132:135], v[164:167], v[60:63]
	v_mfma_f32_16x16x32_bf16 v[56:59], v[140:143], v[164:167], v[56:59]
	v_mfma_f32_16x16x32_bf16 v[44:47], v[132:135], v[188:191], v[44:47]
	v_mfma_f32_16x16x32_bf16 v[40:43], v[140:143], v[188:191], v[40:43]
	v_mfma_f32_16x16x32_bf16 v[28:31], v[132:135], v[206:209], v[28:31]
	v_mfma_f32_16x16x32_bf16 v[24:27], v[140:143], v[206:209], v[24:27]
	v_mfma_f32_16x16x32_bf16 v[12:15], v[132:135], v[214:217], v[12:15]
	v_mfma_f32_16x16x32_bf16 v[8:11], v[140:143], v[214:217], v[8:11]
	s_setprio 0
	s_setprio 1
	v_mfma_f32_16x16x32_bf16 v[52:55], v[144:147], v[160:163], v[52:55]
	v_mfma_f32_16x16x32_bf16 v[48:51], v[152:155], v[160:163], v[48:51]
	v_mfma_f32_16x16x32_bf16 v[36:39], v[144:147], v[184:187], v[36:39]
	v_mfma_f32_16x16x32_bf16 v[32:35], v[152:155], v[184:187], v[32:35]
	v_mfma_f32_16x16x32_bf16 v[20:23], v[144:147], v[192:195], v[20:23]
	v_mfma_f32_16x16x32_bf16 v[16:19], v[152:155], v[192:195], v[16:19]
	v_mfma_f32_16x16x32_bf16 v[4:7], v[144:147], v[210:213], v[4:7]
	v_mfma_f32_16x16x32_bf16 v[0:3], v[152:155], v[210:213], v[0:3]
	v_mfma_f32_16x16x32_bf16 v[52:55], v[148:151], v[164:167], v[52:55]
	v_mfma_f32_16x16x32_bf16 v[48:51], v[156:159], v[164:167], v[48:51]
	v_mfma_f32_16x16x32_bf16 v[36:39], v[148:151], v[188:191], v[36:39]
	v_mfma_f32_16x16x32_bf16 v[32:35], v[156:159], v[188:191], v[32:35]
	v_mfma_f32_16x16x32_bf16 v[20:23], v[148:151], v[206:209], v[20:23]
	v_mfma_f32_16x16x32_bf16 v[16:19], v[156:159], v[206:209], v[16:19]
	v_mfma_f32_16x16x32_bf16 v[4:7], v[148:151], v[214:217], v[4:7]
	v_mfma_f32_16x16x32_bf16 v[0:3], v[156:159], v[214:217], v[0:3]
	s_setprio 0
	s_barrier
	s_cbranch_scc0 .LBB0_1053
	s_and_b64 vcc, exec, s[16:17]
	s_cbranch_vccz .LBB0_1056
	s_barrier

; #define PG8_STAGE(bufoff, gbase, voff) do { _Pragma("unroll") for (int _i = 0; _i < 2; ++_i) \
;         __builtin_amdgcn_global_load_lds((const unsigned*)((const char*)(gbase) + (voff)[_i]), (PG8_LAS unsigned*)(lds + (bufoff) + ldsw + _i * 8192), 16, 0, 0); } while (0)
; #define PG8_LDA(dst, b, h) do { _Pragma("unroll") for (int m = 0; m < 4; ++m) _Pragma("unroll") for (int k = 0; k < 2; ++k) dst[m][k] = *(const PG8_LAS bf16x8*)(lds + PG8_SA(b, h) + aoff + m * 2048 + k * 1024); } while (0)
; #define PG8_LDB(dst, b, h) do { _Pragma("unroll") for (int n = 0; n < 2; ++n) _Pragma("unroll") for (int k = 0; k < 2; ++k) dst[n][k] = *(const PG8_LAS bf16x8*)(lds + PG8_SB(b, h) + boff + n * 2048 + k * 1024); } while (0)
; #define PG8_MMA(ai, bj, At, Bt) do { __builtin_amdgcn_s_setprio(1); _Pragma("unroll") for (int m = 0; m < 4; ++m) _Pragma("unroll") for (int n = 0; n < 2; ++n) _Pragma("unroll") for (int k = 0; k < 2; ++k) \
;         acc[ai][bj][m][n] = __builtin_amdgcn_mfma_f32_16x16x32_bf16(Bt[n][k], At[m][k], acc[ai][bj][m][n], 0, 0, 0); __builtin_amdgcn_s_setprio(0); } while (0)
; #define PG8_WAIT_V(n) asm volatile("s_waitcnt vmcnt(" #n ")" ::: "memory")
; #define PG8_WAIT_L(n) asm volatile("s_waitcnt lgkmcnt(" #n ")" ::: "memory")
; #define PG8_BAR __builtin_amdgcn_s_barrier()
; template <class Epi, class Sched, bool ALIGN_EPI = false, bool SP2 = false>
; __device__ __forceinline__ void gemm_phase(PG8_LAS unsigned char* lds, const Gemm g, const Sched& S, const Epi& E) {
;     ...
;             const char* a1 = cA + (size_t)(t + 1) * kstep;
;             const char* a2 = last ? nA : cA + (size_t)(t + 2) * kstep; const char* b2 = last ? nB : cB + (size_t)(t + 2) * kstep;
;             const char* a3 = a2 + kstep; const char* b3 = b2 + kstep;
;             if (last && has_next) S.a_ready(nxt);
;             if constexpr (SP2) {
;             PG8_LDB(B0, 0, 0); PG8_LDB(B1, 0, 1); PG8_SCHED; PG8_LDA(At, 0, 0); PG8_STAGE(PG8_SA(1, 1), a1 + hstep, voffA);
;             PG8_WAIT_V(8); PG8_WAIT_L(0); PG8_BAR; PG8_MMA(0, 0, At, B0); PG8_MMA(0, 1, At, B1); PG8_BAR; PG8_SCHED;
;             PG8_LDA(At, 0, 1); PG8_STAGE(PG8_SB(0, 0), b2, voffB); PG8_STAGE(PG8_SB(0, 1), b2 + hstep, voffB); PG8_STAGE(PG8_SA(0, 0), a2, voffA);
;             PG8_WAIT_V(8); PG8_WAIT_L(0); PG8_BAR; PG8_MMA(1, 0, At, B0); PG8_MMA(1, 1, At, B1); PG8_BAR; PG8_SCHED;
.LBB0_1184:
	ds_read_b128 v[152:155], v149
	ds_read_b128 v[156:159], v149 offset:1024
	ds_read_b128 v[160:163], v149 offset:2048
	ds_read_b128 v[164:167], v149 offset:3072
	ds_read_b128 v[168:171], v150
	ds_read_b128 v[172:175], v150 offset:1024
	ds_read_b128 v[176:179], v150 offset:2048
	ds_read_b128 v[180:183], v150 offset:3072
	s_add_i32 m0, s3, 0xc000
	ds_read_b128 v[184:187], v151
	ds_read_b128 v[188:191], v151 offset:1024
	ds_read_b128 v[192:195], v151 offset:2048
	ds_read_b128 v[196:199], v151 offset:3072
	ds_read_b128 v[200:203], v151 offset:4096
	ds_read_b128 v[204:207], v151 offset:5120
	ds_read_b128 v[208:211], v151 offset:6144
	ds_read_b128 v[212:215], v151 offset:7168
	global_load_lds_dwordx4 v136, s[50:51]
	s_add_i32 m0, s3, 0xe000
	s_nop 0
	global_load_lds_dwordx4 v138, s[50:51]
	s_add_u32 s58, s50, 0xfff80080
	s_addc_u32 s59, s51, -1
	s_cmp_eq_u32 s74, 28
	s_cselect_b32 s61, s25, s59
	s_cselect_b32 s60, s41, s58
	s_cselect_b32 s59, s39, s73
	s_cselect_b32 s58, s71, s72
	s_add_i32 s75, s65, s1
	s_mov_b32 m0, s75
	s_waitcnt vmcnt(8)
	s_waitcnt lgkmcnt(0)
	s_barrier
	s_setprio 1
	s_waitcnt lgkmcnt(0)
	v_mfma_f32_16x16x32_bf16 v[124:127], v[152:155], v[184:187], v[124:127]
	v_mfma_f32_16x16x32_bf16 v[120:123], v[160:163], v[184:187], v[120:123]
	v_mfma_f32_16x16x32_bf16 v[108:111], v[152:155], v[192:195], v[108:111]
	v_mfma_f32_16x16x32_bf16 v[104:107], v[160:163], v[192:195], v[104:107]
	v_mfma_f32_16x16x32_bf16 v[92:95], v[152:155], v[200:203], v[92:95]
	v_mfma_f32_16x16x32_bf16 v[88:91], v[160:163], v[200:203], v[88:91]
	v_mfma_f32_16x16x32_bf16 v[76:79], v[152:155], v[208:211], v[76:79]
	v_mfma_f32_16x16x32_bf16 v[72:75], v[160:163], v[208:211], v[72:75]
	v_mfma_f32_16x16x32_bf16 v[124:127], v[156:159], v[188:191], v[124:127]
	v_mfma_f32_16x16x32_bf16 v[120:123], v[164:167], v[188:191], v[120:123]
	v_mfma_f32_16x16x32_bf16 v[108:111], v[156:159], v[196:199], v[108:111]
	v_mfma_f32_16x16x32_bf16 v[104:107], v[164:167], v[196:199], v[104:107]
	v_mfma_f32_16x16x32_bf16 v[92:95], v[156:159], v[204:207], v[92:95]
	v_mfma_f32_16x16x32_bf16 v[88:91], v[164:167], v[204:207], v[88:91]
	v_mfma_f32_16x16x32_bf16 v[76:79], v[156:159], v[212:215], v[76:79]
	v_mfma_f32_16x16x32_bf16 v[72:75], v[164:167], v[212:215], v[72:75]
	s_setprio 0
	s_setprio 1
	v_mfma_f32_16x16x32_bf16 v[116:119], v[168:171], v[184:187], v[116:119]
	v_mfma_f32_16x16x32_bf16 v[112:115], v[176:179], v[184:187], v[112:115]
	v_mfma_f32_16x16x32_bf16 v[100:103], v[168:171], v[192:195], v[100:103]
	v_mfma_f32_16x16x32_bf16 v[96:99], v[176:179], v[192:195], v[96:99]
	v_mfma_f32_16x16x32_bf16 v[84:87], v[168:171], v[200:203], v[84:87]
	v_mfma_f32_16x16x32_bf16 v[80:83], v[176:179], v[200:203], v[80:83]
	v_mfma_f32_16x16x32_bf16 v[68:71], v[168:171], v[208:211], v[68:71]
	v_mfma_f32_16x16x32_bf16 v[64:67], v[176:179], v[208:211], v[64:67]
	v_mfma_f32_16x16x32_bf16 v[116:119], v[172:175], v[188:191], v[116:119]
	v_mfma_f32_16x16x32_bf16 v[112:115], v[180:183], v[188:191], v[112:115]
	v_mfma_f32_16x16x32_bf16 v[100:103], v[172:175], v[196:199], v[100:103]
	v_mfma_f32_16x16x32_bf16 v[96:99], v[180:183], v[196:199], v[96:99]
	v_mfma_f32_16x16x32_bf16 v[84:87], v[172:175], v[204:207], v[84:87]
	v_mfma_f32_16x16x32_bf16 v[80:83], v[180:183], v[204:207], v[80:83]
	v_mfma_f32_16x16x32_bf16 v[68:71], v[172:175], v[212:215], v[68:71]
	v_mfma_f32_16x16x32_bf16 v[64:67], v[180:183], v[212:215], v[64:67]
	s_setprio 0
	s_barrier
	ds_read_b128 v[184:187], v151 offset:16384
	ds_read_b128 v[188:191], v151 offset:17408
	ds_read_b128 v[192:195], v151 offset:18432
	ds_read_b128 v[196:199], v151 offset:19456
	ds_read_b128 v[200:203], v151 offset:20480
	ds_read_b128 v[204:207], v151 offset:21504
	ds_read_b128 v[208:211], v151 offset:22528
	ds_read_b128 v[212:215], v151 offset:23552
	global_load_lds_dwordx4 v130, s[58:59]
	s_add_i32 m0, s75, 0x2000
	s_add_u32 s76, s58, 0x80000
	s_addc_u32 s77, s59, 0
	s_add_i32 s75, s66, s1
	global_load_lds_dwordx4 v134, s[58:59]
	s_mov_b32 m0, s75
	s_nop 0
	global_load_lds_dwordx4 v130, s[76:77]
	s_add_i32 m0, s75, 0x2000
	s_nop 0
	global_load_lds_dwordx4 v134, s[76:77]
	s_mov_b32 m0, s3
	s_nop 0
	global_load_lds_dwordx4 v128, s[60:61]
	s_mov_b32 m0, s14
	s_nop 0
	global_load_lds_dwordx4 v132, s[60:61]
	s_waitcnt vmcnt(8)
	s_waitcnt lgkmcnt(0)
	s_barrier
	s_setprio 1
	s_waitcnt lgkmcnt(0)
	v_mfma_f32_16x16x32_bf16 v[60:63], v[152:155], v[184:187], v[60:63]
	v_mfma_f32_16x16x32_bf16 v[56:59], v[160:163], v[184:187], v[56:59]
	v_mfma_f32_16x16x32_bf16 v[44:47], v[152:155], v[192:195], v[44:47]
	v_mfma_f32_16x16x32_bf16 v[40:43], v[160:163], v[192:195], v[40:43]
	v_mfma_f32_16x16x32_bf16 v[28:31], v[152:155], v[200:203], v[28:31]
	v_mfma_f32_16x16x32_bf16 v[24:27], v[160:163], v[200:203], v[24:27]
	v_mfma_f32_16x16x32_bf16 v[12:15], v[152:155], v[208:211], v[12:15]
	v_mfma_f32_16x16x32_bf16 v[8:11], v[160:163], v[208:211], v[8:11]
	v_mfma_f32_16x16x32_bf16 v[60:63], v[156:159], v[188:191], v[60:63]
	v_mfma_f32_16x16x32_bf16 v[56:59], v[164:167], v[188:191], v[56:59]
	v_mfma_f32_16x16x32_bf16 v[44:47], v[156:159], v[196:199], v[44:47]
	v_mfma_f32_16x16x32_bf16 v[40:43], v[164:167], v[196:199], v[40:43]
	v_mfma_f32_16x16x32_bf16 v[28:31], v[156:159], v[204:207], v[28:31]
	v_mfma_f32_16x16x32_bf16 v[24:27], v[164:167], v[204:207], v[24:27]
	v_mfma_f32_16x16x32_bf16 v[12:15], v[156:159], v[212:215], v[12:15]
	v_mfma_f32_16x16x32_bf16 v[8:11], v[164:167], v[212:215], v[8:11]
	s_setprio 0
	s_setprio 1
	v_mfma_f32_16x16x32_bf16 v[52:55], v[168:171], v[184:187], v[52:55]
	v_mfma_f32_16x16x32_bf16 v[48:51], v[176:179], v[184:187], v[48:51]
	v_mfma_f32_16x16x32_bf16 v[36:39], v[168:171], v[192:195], v[36:39]
	v_mfma_f32_16x16x32_bf16 v[32:35], v[176:179], v[192:195], v[32:35]
	v_mfma_f32_16x16x32_bf16 v[20:23], v[168:171], v[200:203], v[20:23]
	v_mfma_f32_16x16x32_bf16 v[16:19], v[176:179], v[200:203], v[16:19]
	v_mfma_f32_16x16x32_bf16 v[4:7], v[168:171], v[208:211], v[4:7]
	v_mfma_f32_16x16x32_bf16 v[0:3], v[176:179], v[208:211], v[0:3]
	v_mfma_f32_16x16x32_bf16 v[52:55], v[172:175], v[188:191], v[52:55]
	v_mfma_f32_16x16x32_bf16 v[48:51], v[180:183], v[188:191], v[48:51]
	v_mfma_f32_16x16x32_bf16 v[36:39], v[172:175], v[196:199], v[36:39]
	v_mfma_f32_16x16x32_bf16 v[32:35], v[180:183], v[196:199], v[32:35]
	v_mfma_f32_16x16x32_bf16 v[20:23], v[172:175], v[204:207], v[20:23]
	v_mfma_f32_16x16x32_bf16 v[16:19], v[180:183], v[204:207], v[16:19]
	v_mfma_f32_16x16x32_bf16 v[4:7], v[172:175], v[212:215], v[4:7]
	v_mfma_f32_16x16x32_bf16 v[0:3], v[180:183], v[212:215], v[0:3]
	s_setprio 0
	s_barrier
; #define PG8_STAGE(bufoff, gbase, voff) do { _Pragma("unroll") for (int _i = 0; _i < 2; ++_i) \
;         __builtin_amdgcn_global_load_lds((const unsigned*)((const char*)(gbase) + (voff)[_i]), (PG8_LAS unsigned*)(lds + (bufoff) + ldsw + _i * 8192), 16, 0, 0); } while (0)
; #define PG8_LDA(dst, b, h) do { _Pragma("unroll") for (int m = 0; m < 4; ++m) _Pragma("unroll") for (int k = 0; k < 2; ++k) dst[m][k] = *(const PG8_LAS bf16x8*)(lds + PG8_SA(b, h) + aoff + m * 2048 + k * 1024); } while (0)
; #define PG8_LDB(dst, b, h) do { _Pragma("unroll") for (int n = 0; n < 2; ++n) _Pragma("unroll") for (int k = 0; k < 2; ++k) dst[n][k] = *(const PG8_LAS bf16x8*)(lds + PG8_SB(b, h) + boff + n * 2048 + k * 1024); } while (0)
; #define PG8_MMA(ai, bj, At, Bt) do { __builtin_amdgcn_s_setprio(1); _Pragma("unroll") for (int m = 0; m < 4; ++m) _Pragma("unroll") for (int n = 0; n < 2; ++n) _Pragma("unroll") for (int k = 0; k < 2; ++k) \
;         acc[ai][bj][m][n] = __builtin_amdgcn_mfma_f32_16x16x32_bf16(Bt[n][k], At[m][k], acc[ai][bj][m][n], 0, 0, 0); __builtin_amdgcn_s_setprio(0); } while (0)
; #define PG8_WAIT_V(n) asm volatile("s_waitcnt vmcnt(" #n ")" ::: "memory")
; #define PG8_WAIT_L(n) asm volatile("s_waitcnt lgkmcnt(" #n ")" ::: "memory")
; #define PG8_BAR __builtin_amdgcn_s_barrier()
; #define PG8_SCHED __builtin_amdgcn_sched_barrier(0)
; template <class Epi, class Sched, bool ALIGN_EPI = false, bool SP2 = false>
; __device__ __forceinline__ void gemm_phase(PG8_LAS unsigned char* lds, const Gemm g, const Sched& S, const Epi& E) {
;     ...
;         for (int t = 0; t < nt; t += 2) {
;             const bool last = (t == nt - 2);
;             const char* a1 = cA + (size_t)(t + 1) * kstep;
;             const char* a2 = last ? nA : cA + (size_t)(t + 2) * kstep; const char* b2 = last ? nB : cB + (size_t)(t + 2) * kstep;
;     ...
;             PG8_LDB(B0, 1, 0); PG8_LDB(B1, 1, 1); PG8_SCHED; PG8_LDA(At, 1, 0); PG8_STAGE(PG8_SA(0, 1), a2 + hstep, voffA);
;             PG8_WAIT_V(8); PG8_WAIT_L(0); PG8_BAR; PG8_MMA(0, 0, At, B0); PG8_MMA(0, 1, At, B1); PG8_BAR; PG8_SCHED;
;             PG8_LDA(At, 1, 1); PG8_STAGE(PG8_SB(1, 0), b3, voffB); PG8_STAGE(PG8_SB(1, 1), b3 + hstep, voffB); PG8_STAGE(PG8_SA(1, 0), a3, voffA);
;             PG8_WAIT_V(8); PG8_WAIT_L(0); PG8_BAR; PG8_MMA(1, 0, At, B0); PG8_MMA(1, 1, At, B1); PG8_BAR; PG8_SCHED;
	ds_read_b128 v[152:155], v216
	ds_read_b128 v[156:159], v216 offset:1024
	ds_read_b128 v[160:163], v216 offset:2048
	ds_read_b128 v[164:167], v216 offset:3072
	ds_read_b128 v[168:171], v217
	ds_read_b128 v[172:175], v217 offset:1024
	ds_read_b128 v[176:179], v217 offset:2048
	ds_read_b128 v[180:183], v217 offset:3072
	ds_read_b128 v[184:187], v151 offset:32768
	ds_read_b128 v[188:191], v151 offset:33792
	ds_read_b128 v[192:195], v151 offset:34816
	ds_read_b128 v[196:199], v151 offset:35840
	ds_read_b128 v[200:203], v151 offset:36864
	ds_read_b128 v[204:207], v151 offset:37888
	ds_read_b128 v[208:211], v151 offset:38912
	ds_read_b128 v[212:215], v151 offset:39936
	s_add_u32 s98, s60, 0x80000
	s_addc_u32 s99, s61, 0
	s_mov_b32 m0, s15
	s_add_u32 s100, s60, 0x80
	s_addc_u32 s101, s61, 0
	global_load_lds_dwordx4 v128, s[98:99]
	s_mov_b32 m0, s33
	s_nop 0
	global_load_lds_dwordx4 v132, s[98:99]
	s_add_i32 s75, 0, 0x18000
	s_add_i32 s76, 0, 0x1c000
	s_add_u32 s98, s58, 0x80
	s_addc_u32 s99, s59, 0
	s_add_i32 s60, s75, s1
	s_mov_b32 m0, s60
	s_waitcnt vmcnt(8)
	s_waitcnt lgkmcnt(0)
	s_barrier
	s_setprio 1
	s_waitcnt lgkmcnt(0)
	v_mfma_f32_16x16x32_bf16 v[124:127], v[152:155], v[184:187], v[124:127]
	v_mfma_f32_16x16x32_bf16 v[120:123], v[160:163], v[184:187], v[120:123]
	v_mfma_f32_16x16x32_bf16 v[108:111], v[152:155], v[192:195], v[108:111]
	v_mfma_f32_16x16x32_bf16 v[104:107], v[160:163], v[192:195], v[104:107]
	v_mfma_f32_16x16x32_bf16 v[92:95], v[152:155], v[200:203], v[92:95]
	v_mfma_f32_16x16x32_bf16 v[88:91], v[160:163], v[200:203], v[88:91]
	v_mfma_f32_16x16x32_bf16 v[76:79], v[152:155], v[208:211], v[76:79]
	v_mfma_f32_16x16x32_bf16 v[72:75], v[160:163], v[208:211], v[72:75]
	v_mfma_f32_16x16x32_bf16 v[124:127], v[156:159], v[188:191], v[124:127]
	v_mfma_f32_16x16x32_bf16 v[120:123], v[164:167], v[188:191], v[120:123]
	v_mfma_f32_16x16x32_bf16 v[108:111], v[156:159], v[196:199], v[108:111]
	v_mfma_f32_16x16x32_bf16 v[104:107], v[164:167], v[196:199], v[104:107]
	v_mfma_f32_16x16x32_bf16 v[92:95], v[156:159], v[204:207], v[92:95]
	v_mfma_f32_16x16x32_bf16 v[88:91], v[164:167], v[204:207], v[88:91]
	v_mfma_f32_16x16x32_bf16 v[76:79], v[156:159], v[212:215], v[76:79]
	v_mfma_f32_16x16x32_bf16 v[72:75], v[164:167], v[212:215], v[72:75]
	s_setprio 0
	s_setprio 1
	v_mfma_f32_16x16x32_bf16 v[116:119], v[168:171], v[184:187], v[116:119]
	v_mfma_f32_16x16x32_bf16 v[112:115], v[176:179], v[184:187], v[112:115]
	v_mfma_f32_16x16x32_bf16 v[100:103], v[168:171], v[192:195], v[100:103]
	v_mfma_f32_16x16x32_bf16 v[96:99], v[176:179], v[192:195], v[96:99]
	v_mfma_f32_16x16x32_bf16 v[84:87], v[168:171], v[200:203], v[84:87]
	v_mfma_f32_16x16x32_bf16 v[80:83], v[176:179], v[200:203], v[80:83]
	v_mfma_f32_16x16x32_bf16 v[68:71], v[168:171], v[208:211], v[68:71]
	v_mfma_f32_16x16x32_bf16 v[64:67], v[176:179], v[208:211], v[64:67]
	v_mfma_f32_16x16x32_bf16 v[116:119], v[172:175], v[188:191], v[116:119]
	v_mfma_f32_16x16x32_bf16 v[112:115], v[180:183], v[188:191], v[112:115]
	v_mfma_f32_16x16x32_bf16 v[100:103], v[172:175], v[196:199], v[100:103]
	v_mfma_f32_16x16x32_bf16 v[96:99], v[180:183], v[196:199], v[96:99]
	v_mfma_f32_16x16x32_bf16 v[84:87], v[172:175], v[204:207], v[84:87]
	v_mfma_f32_16x16x32_bf16 v[80:83], v[180:183], v[204:207], v[80:83]
	v_mfma_f32_16x16x32_bf16 v[68:71], v[172:175], v[212:215], v[68:71]
	v_mfma_f32_16x16x32_bf16 v[64:67], v[180:183], v[212:215], v[64:67]
	s_setprio 0
	s_barrier
	ds_read_b128 v[184:187], v151 offset:49152
	ds_read_b128 v[188:191], v151 offset:50176
	ds_read_b128 v[192:195], v151 offset:51200
	ds_read_b128 v[196:199], v151 offset:52224
	ds_read_b128 v[200:203], v151 offset:53248
	ds_read_b128 v[204:207], v151 offset:54272
	ds_read_b128 v[208:211], v151 offset:55296
	ds_read_b128 v[212:215], v151 offset:56320
	global_load_lds_dwordx4 v130, s[98:99]
	s_add_i32 m0, s60, 0x2000
	s_add_u32 s58, s58, 0x80080
	s_addc_u32 s59, s59, 0
	s_add_i32 s60, s76, s1
	global_load_lds_dwordx4 v134, s[98:99]
	s_mov_b32 m0, s60
	s_nop 0
	global_load_lds_dwordx4 v130, s[58:59]
	s_add_i32 m0, s60, 0x2000
	s_nop 0
	global_load_lds_dwordx4 v134, s[58:59]
	s_mov_b32 m0, s49
	s_nop 0
	global_load_lds_dwordx4 v128, s[100:101]
	s_mov_b32 m0, s62
	s_nop 0
	global_load_lds_dwordx4 v132, s[100:101]
	s_add_i32 s74, s74, 2
	s_add_u32 s50, s50, 0x100
	s_addc_u32 s51, s51, 0
	s_add_u32 s72, s72, 0x100
	s_addc_u32 s73, s73, 0
	s_cmp_gt_u32 s74, 29
	s_waitcnt vmcnt(8)
	s_waitcnt lgkmcnt(0)
	s_barrier
	s_setprio 1
	s_waitcnt lgkmcnt(0)
	v_mfma_f32_16x16x32_bf16 v[60:63], v[152:155], v[184:187], v[60:63]
	v_mfma_f32_16x16x32_bf16 v[56:59], v[160:163], v[184:187], v[56:59]
	v_mfma_f32_16x16x32_bf16 v[44:47], v[152:155], v[192:195], v[44:47]
	v_mfma_f32_16x16x32_bf16 v[40:43], v[160:163], v[192:195], v[40:43]
	v_mfma_f32_16x16x32_bf16 v[28:31], v[152:155], v[200:203], v[28:31]
	v_mfma_f32_16x16x32_bf16 v[24:27], v[160:163], v[200:203], v[24:27]
	v_mfma_f32_16x16x32_bf16 v[12:15], v[152:155], v[208:211], v[12:15]
	v_mfma_f32_16x16x32_bf16 v[8:11], v[160:163], v[208:211], v[8:11]
	v_mfma_f32_16x16x32_bf16 v[60:63], v[156:159], v[188:191], v[60:63]
	v_mfma_f32_16x16x32_bf16 v[56:59], v[164:167], v[188:191], v[56:59]
	v_mfma_f32_16x16x32_bf16 v[44:47], v[156:159], v[196:199], v[44:47]
	v_mfma_f32_16x16x32_bf16 v[40:43], v[164:167], v[196:199], v[40:43]
	v_mfma_f32_16x16x32_bf16 v[28:31], v[156:159], v[204:207], v[28:31]
	v_mfma_f32_16x16x32_bf16 v[24:27], v[164:167], v[204:207], v[24:27]
	v_mfma_f32_16x16x32_bf16 v[12:15], v[156:159], v[212:215], v[12:15]
	v_mfma_f32_16x16x32_bf16 v[8:11], v[164:167], v[212:215], v[8:11]
	s_setprio 0
	s_setprio 1
	v_mfma_f32_16x16x32_bf16 v[52:55], v[168:171], v[184:187], v[52:55]
	v_mfma_f32_16x16x32_bf16 v[48:51], v[176:179], v[184:187], v[48:51]
	v_mfma_f32_16x16x32_bf16 v[36:39], v[168:171], v[192:195], v[36:39]
	v_mfma_f32_16x16x32_bf16 v[32:35], v[176:179], v[192:195], v[32:35]
	v_mfma_f32_16x16x32_bf16 v[20:23], v[168:171], v[200:203], v[20:23]
	v_mfma_f32_16x16x32_bf16 v[16:19], v[176:179], v[200:203], v[16:19]
	v_mfma_f32_16x16x32_bf16 v[4:7], v[168:171], v[208:211], v[4:7]
	v_mfma_f32_16x16x32_bf16 v[0:3], v[176:179], v[208:211], v[0:3]
	v_mfma_f32_16x16x32_bf16 v[52:55], v[172:175], v[188:191], v[52:55]
	v_mfma_f32_16x16x32_bf16 v[48:51], v[180:183], v[188:191], v[48:51]
	v_mfma_f32_16x16x32_bf16 v[36:39], v[172:175], v[196:199], v[36:39]
	v_mfma_f32_16x16x32_bf16 v[32:35], v[180:183], v[196:199], v[32:35]
	v_mfma_f32_16x16x32_bf16 v[20:23], v[172:175], v[204:207], v[20:23]
	v_mfma_f32_16x16x32_bf16 v[16:19], v[180:183], v[204:207], v[16:19]
	v_mfma_f32_16x16x32_bf16 v[4:7], v[172:175], v[212:215], v[4:7]
	v_mfma_f32_16x16x32_bf16 v[0:3], v[180:183], v[212:215], v[0:3]
	s_setprio 0
	s_barrier
	s_cbranch_scc0 .LBB0_1184
	s_and_b64 vcc, exec, s[12:13]
	s_cbranch_vccz .LBB0_1187
	s_barrier

; #define PG8_STAGE(bufoff, gbase, voff) do { _Pragma("unroll") for (int _i = 0; _i < 2; ++_i) \
;         __builtin_amdgcn_global_load_lds((const unsigned*)((const char*)(gbase) + (voff)[_i]), (PG8_LAS unsigned*)(lds + (bufoff) + ldsw + _i * 8192), 16, 0, 0); } while (0)
; #define PG8_LDA(dst, b, h) do { _Pragma("unroll") for (int m = 0; m < 4; ++m) _Pragma("unroll") for (int k = 0; k < 2; ++k) dst[m][k] = *(const PG8_LAS bf16x8*)(lds + PG8_SA(b, h) + aoff + m * 2048 + k * 1024); } while (0)
; #define PG8_LDB(dst, b, h) do { _Pragma("unroll") for (int n = 0; n < 2; ++n) _Pragma("unroll") for (int k = 0; k < 2; ++k) dst[n][k] = *(const PG8_LAS bf16x8*)(lds + PG8_SB(b, h) + boff + n * 2048 + k * 1024); } while (0)
; #define PG8_MMA(ai, bj, At, Bt) do { __builtin_amdgcn_s_setprio(1); _Pragma("unroll") for (int m = 0; m < 4; ++m) _Pragma("unroll") for (int n = 0; n < 2; ++n) _Pragma("unroll") for (int k = 0; k < 2; ++k) \
;         acc[ai][bj][m][n] = __builtin_amdgcn_mfma_f32_16x16x32_bf16(Bt[n][k], At[m][k], acc[ai][bj][m][n], 0, 0, 0); __builtin_amdgcn_s_setprio(0); } while (0)
; #define PG8_WAIT_V(n) asm volatile("s_waitcnt vmcnt(" #n ")" ::: "memory")
; #define PG8_WAIT_L(n) asm volatile("s_waitcnt lgkmcnt(" #n ")" ::: "memory")
; #define PG8_BAR __builtin_amdgcn_s_barrier()
; template <class Epi, class Sched, bool ALIGN_EPI = false, bool SP2 = false>
; __device__ __forceinline__ void gemm_phase(PG8_LAS unsigned char* lds, const Gemm g, const Sched& S, const Epi& E) {
;     ...
;             const char* a1 = cA + (size_t)(t + 1) * kstep;
;             const char* a2 = last ? nA : cA + (size_t)(t + 2) * kstep; const char* b2 = last ? nB : cB + (size_t)(t + 2) * kstep;
;             const char* a3 = a2 + kstep; const char* b3 = b2 + kstep;
;             if (last && has_next) S.a_ready(nxt);
;             if constexpr (SP2) {
;             PG8_LDB(B0, 0, 0); PG8_LDB(B1, 0, 1); PG8_SCHED; PG8_LDA(At, 0, 0); PG8_STAGE(PG8_SA(1, 1), a1 + hstep, voffA);
;             PG8_WAIT_V(8); PG8_WAIT_L(0); PG8_BAR; PG8_MMA(0, 0, At, B0); PG8_MMA(0, 1, At, B1); PG8_BAR; PG8_SCHED;
;             PG8_LDA(At, 0, 1); PG8_STAGE(PG8_SB(0, 0), b2, voffB); PG8_STAGE(PG8_SB(0, 1), b2 + hstep, voffB); PG8_STAGE(PG8_SA(0, 0), a2, voffA);
;             PG8_WAIT_V(8); PG8_WAIT_L(0); PG8_BAR; PG8_MMA(1, 0, At, B0); PG8_MMA(1, 1, At, B1); PG8_BAR; PG8_SCHED;
.LBB0_1260:
	ds_read_b128 v[128:131], v202
	ds_read_b128 v[132:135], v202 offset:1024
	ds_read_b128 v[136:139], v202 offset:2048
	ds_read_b128 v[140:143], v202 offset:3072
	ds_read_b128 v[144:147], v203
	ds_read_b128 v[148:151], v203 offset:1024
	ds_read_b128 v[152:155], v203 offset:2048
	ds_read_b128 v[156:159], v203 offset:3072
	s_add_i32 m0, s14, 0xc000
	ds_read_b128 v[160:163], v204
	ds_read_b128 v[164:167], v204 offset:1024
	ds_read_b128 v[184:187], v204 offset:2048
	ds_read_b128 v[188:191], v204 offset:3072
	ds_read_b128 v[192:195], v204 offset:4096
	ds_read_b128 v[206:209], v204 offset:5120
	ds_read_b128 v[210:213], v204 offset:6144
	ds_read_b128 v[214:217], v204 offset:7168
	global_load_lds_dwordx4 v176, s[50:51]
	s_add_i32 m0, s14, 0xe000
	s_nop 0
	global_load_lds_dwordx4 v178, s[50:51]
	s_add_u32 s58, s50, 0xffe00080
	s_addc_u32 s59, s51, -1
	s_cmpk_eq_i32 s72, 0x7c
	s_cselect_b32 s61, s25, s59
	s_cselect_b32 s60, s41, s58
	s_cselect_b32 s59, s39, s71
	s_cselect_b32 s58, s69, s70
	s_add_i32 s73, s67, s1
	s_mov_b32 m0, s73
	s_waitcnt vmcnt(8)
	s_waitcnt lgkmcnt(0)
	s_barrier
	s_setprio 1
	s_waitcnt lgkmcnt(0)
	v_mfma_f32_16x16x32_bf16 v[124:127], v[128:131], v[160:163], v[124:127]
	v_mfma_f32_16x16x32_bf16 v[120:123], v[136:139], v[160:163], v[120:123]
	v_mfma_f32_16x16x32_bf16 v[116:119], v[128:131], v[184:187], v[116:119]
	v_mfma_f32_16x16x32_bf16 v[108:111], v[136:139], v[184:187], v[108:111]
	v_mfma_f32_16x16x32_bf16 v[92:95], v[128:131], v[192:195], v[92:95]
	v_mfma_f32_16x16x32_bf16 v[88:91], v[136:139], v[192:195], v[88:91]
	v_mfma_f32_16x16x32_bf16 v[76:79], v[128:131], v[210:213], v[76:79]
	v_mfma_f32_16x16x32_bf16 v[72:75], v[136:139], v[210:213], v[72:75]
	v_mfma_f32_16x16x32_bf16 v[124:127], v[132:135], v[164:167], v[124:127]
	v_mfma_f32_16x16x32_bf16 v[120:123], v[140:143], v[164:167], v[120:123]
	v_mfma_f32_16x16x32_bf16 v[116:119], v[132:135], v[188:191], v[116:119]
	v_mfma_f32_16x16x32_bf16 v[108:111], v[140:143], v[188:191], v[108:111]
	v_mfma_f32_16x16x32_bf16 v[92:95], v[132:135], v[206:209], v[92:95]
	v_mfma_f32_16x16x32_bf16 v[88:91], v[140:143], v[206:209], v[88:91]
	v_mfma_f32_16x16x32_bf16 v[76:79], v[132:135], v[214:217], v[76:79]
	v_mfma_f32_16x16x32_bf16 v[72:75], v[140:143], v[214:217], v[72:75]
	s_setprio 0
	s_setprio 1
	v_mfma_f32_16x16x32_bf16 v[112:115], v[144:147], v[160:163], v[112:115]
	v_mfma_f32_16x16x32_bf16 v[104:107], v[152:155], v[160:163], v[104:107]
	v_mfma_f32_16x16x32_bf16 v[100:103], v[144:147], v[184:187], v[100:103]
	v_mfma_f32_16x16x32_bf16 v[96:99], v[152:155], v[184:187], v[96:99]
	v_mfma_f32_16x16x32_bf16 v[84:87], v[144:147], v[192:195], v[84:87]
	v_mfma_f32_16x16x32_bf16 v[80:83], v[152:155], v[192:195], v[80:83]
	v_mfma_f32_16x16x32_bf16 v[68:71], v[144:147], v[210:213], v[68:71]
	v_mfma_f32_16x16x32_bf16 v[64:67], v[152:155], v[210:213], v[64:67]
	v_mfma_f32_16x16x32_bf16 v[112:115], v[148:151], v[164:167], v[112:115]
	v_mfma_f32_16x16x32_bf16 v[104:107], v[156:159], v[164:167], v[104:107]
	v_mfma_f32_16x16x32_bf16 v[100:103], v[148:151], v[188:191], v[100:103]
	v_mfma_f32_16x16x32_bf16 v[96:99], v[156:159], v[188:191], v[96:99]
	v_mfma_f32_16x16x32_bf16 v[84:87], v[148:151], v[206:209], v[84:87]
	v_mfma_f32_16x16x32_bf16 v[80:83], v[156:159], v[206:209], v[80:83]
	v_mfma_f32_16x16x32_bf16 v[68:71], v[148:151], v[214:217], v[68:71]
	v_mfma_f32_16x16x32_bf16 v[64:67], v[156:159], v[214:217], v[64:67]
	s_setprio 0
	s_barrier
	ds_read_b128 v[160:163], v204 offset:16384
	ds_read_b128 v[164:167], v204 offset:17408
	ds_read_b128 v[184:187], v204 offset:18432
	ds_read_b128 v[188:191], v204 offset:19456
	ds_read_b128 v[192:195], v204 offset:20480
	ds_read_b128 v[206:209], v204 offset:21504
	ds_read_b128 v[210:213], v204 offset:22528
	ds_read_b128 v[214:217], v204 offset:23552
	global_load_lds_dwordx4 v170, s[58:59]
	s_add_i32 m0, s73, 0x2000
	s_add_u32 s74, s58, 0x200000
	s_addc_u32 s75, s59, 0
	s_add_i32 s73, s68, s1
	global_load_lds_dwordx4 v174, s[58:59]
	s_mov_b32 m0, s73
	s_nop 0
	global_load_lds_dwordx4 v170, s[74:75]
	s_add_i32 m0, s73, 0x2000
	s_nop 0
	global_load_lds_dwordx4 v174, s[74:75]
	s_mov_b32 m0, s14
	s_nop 0
	global_load_lds_dwordx4 v168, s[60:61]
	s_mov_b32 m0, s15
	s_nop 0
	global_load_lds_dwordx4 v172, s[60:61]
	s_waitcnt vmcnt(8)
	s_waitcnt lgkmcnt(0)
	s_barrier
	s_setprio 1
	s_waitcnt lgkmcnt(0)
	v_mfma_f32_16x16x32_bf16 v[60:63], v[128:131], v[160:163], v[60:63]
	v_mfma_f32_16x16x32_bf16 v[56:59], v[136:139], v[160:163], v[56:59]
	v_mfma_f32_16x16x32_bf16 v[44:47], v[128:131], v[184:187], v[44:47]
	v_mfma_f32_16x16x32_bf16 v[40:43], v[136:139], v[184:187], v[40:43]
	v_mfma_f32_16x16x32_bf16 v[28:31], v[128:131], v[192:195], v[28:31]
	v_mfma_f32_16x16x32_bf16 v[24:27], v[136:139], v[192:195], v[24:27]
	v_mfma_f32_16x16x32_bf16 v[12:15], v[128:131], v[210:213], v[12:15]
	v_mfma_f32_16x16x32_bf16 v[8:11], v[136:139], v[210:213], v[8:11]
	v_mfma_f32_16x16x32_bf16 v[60:63], v[132:135], v[164:167], v[60:63]
	v_mfma_f32_16x16x32_bf16 v[56:59], v[140:143], v[164:167], v[56:59]
	v_mfma_f32_16x16x32_bf16 v[44:47], v[132:135], v[188:191], v[44:47]
	v_mfma_f32_16x16x32_bf16 v[40:43], v[140:143], v[188:191], v[40:43]
	v_mfma_f32_16x16x32_bf16 v[28:31], v[132:135], v[206:209], v[28:31]
	v_mfma_f32_16x16x32_bf16 v[24:27], v[140:143], v[206:209], v[24:27]
	v_mfma_f32_16x16x32_bf16 v[12:15], v[132:135], v[214:217], v[12:15]
	v_mfma_f32_16x16x32_bf16 v[8:11], v[140:143], v[214:217], v[8:11]
	s_setprio 0
	s_setprio 1
	v_mfma_f32_16x16x32_bf16 v[52:55], v[144:147], v[160:163], v[52:55]
	v_mfma_f32_16x16x32_bf16 v[48:51], v[152:155], v[160:163], v[48:51]
	v_mfma_f32_16x16x32_bf16 v[36:39], v[144:147], v[184:187], v[36:39]
	v_mfma_f32_16x16x32_bf16 v[32:35], v[152:155], v[184:187], v[32:35]
	v_mfma_f32_16x16x32_bf16 v[20:23], v[144:147], v[192:195], v[20:23]
	v_mfma_f32_16x16x32_bf16 v[16:19], v[152:155], v[192:195], v[16:19]
	v_mfma_f32_16x16x32_bf16 v[4:7], v[144:147], v[210:213], v[4:7]
	v_mfma_f32_16x16x32_bf16 v[0:3], v[152:155], v[210:213], v[0:3]
	v_mfma_f32_16x16x32_bf16 v[52:55], v[148:151], v[164:167], v[52:55]
	v_mfma_f32_16x16x32_bf16 v[48:51], v[156:159], v[164:167], v[48:51]
	v_mfma_f32_16x16x32_bf16 v[36:39], v[148:151], v[188:191], v[36:39]
	v_mfma_f32_16x16x32_bf16 v[32:35], v[156:159], v[188:191], v[32:35]
	v_mfma_f32_16x16x32_bf16 v[20:23], v[148:151], v[206:209], v[20:23]
	v_mfma_f32_16x16x32_bf16 v[16:19], v[156:159], v[206:209], v[16:19]
	v_mfma_f32_16x16x32_bf16 v[4:7], v[148:151], v[214:217], v[4:7]
	v_mfma_f32_16x16x32_bf16 v[0:3], v[156:159], v[214:217], v[0:3]
	s_setprio 0
	s_barrier
; #define PG8_STAGE(bufoff, gbase, voff) do { _Pragma("unroll") for (int _i = 0; _i < 2; ++_i) \
;         __builtin_amdgcn_global_load_lds((const unsigned*)((const char*)(gbase) + (voff)[_i]), (PG8_LAS unsigned*)(lds + (bufoff) + ldsw + _i * 8192), 16, 0, 0); } while (0)
; #define PG8_LDA(dst, b, h) do { _Pragma("unroll") for (int m = 0; m < 4; ++m) _Pragma("unroll") for (int k = 0; k < 2; ++k) dst[m][k] = *(const PG8_LAS bf16x8*)(lds + PG8_SA(b, h) + aoff + m * 2048 + k * 1024); } while (0)
; #define PG8_LDB(dst, b, h) do { _Pragma("unroll") for (int n = 0; n < 2; ++n) _Pragma("unroll") for (int k = 0; k < 2; ++k) dst[n][k] = *(const PG8_LAS bf16x8*)(lds + PG8_SB(b, h) + boff + n * 2048 + k * 1024); } while (0)
; #define PG8_MMA(ai, bj, At, Bt) do { __builtin_amdgcn_s_setprio(1); _Pragma("unroll") for (int m = 0; m < 4; ++m) _Pragma("unroll") for (int n = 0; n < 2; ++n) _Pragma("unroll") for (int k = 0; k < 2; ++k) \
;         acc[ai][bj][m][n] = __builtin_amdgcn_mfma_f32_16x16x32_bf16(Bt[n][k], At[m][k], acc[ai][bj][m][n], 0, 0, 0); __builtin_amdgcn_s_setprio(0); } while (0)
; #define PG8_WAIT_V(n) asm volatile("s_waitcnt vmcnt(" #n ")" ::: "memory")
; #define PG8_WAIT_L(n) asm volatile("s_waitcnt lgkmcnt(" #n ")" ::: "memory")
; #define PG8_BAR __builtin_amdgcn_s_barrier()
; #define PG8_SCHED __builtin_amdgcn_sched_barrier(0)
; template <class Epi, class Sched, bool ALIGN_EPI = false, bool SP2 = false>
; __device__ __forceinline__ void gemm_phase(PG8_LAS unsigned char* lds, const Gemm g, const Sched& S, const Epi& E) {
;     ...
;         for (int t = 0; t < nt; t += 2) {
;             const bool last = (t == nt - 2);
;             const char* a1 = cA + (size_t)(t + 1) * kstep;
;             const char* a2 = last ? nA : cA + (size_t)(t + 2) * kstep; const char* b2 = last ? nB : cB + (size_t)(t + 2) * kstep;
;     ...
;             PG8_LDB(B0, 1, 0); PG8_LDB(B1, 1, 1); PG8_SCHED; PG8_LDA(At, 1, 0); PG8_STAGE(PG8_SA(0, 1), a2 + hstep, voffA);
;             PG8_WAIT_V(8); PG8_WAIT_L(0); PG8_BAR; PG8_MMA(0, 0, At, B0); PG8_MMA(0, 1, At, B1); PG8_BAR; PG8_SCHED;
;             PG8_LDA(At, 1, 1); PG8_STAGE(PG8_SB(1, 0), b3, voffB); PG8_STAGE(PG8_SB(1, 1), b3 + hstep, voffB); PG8_STAGE(PG8_SA(1, 0), a3, voffA);
;             PG8_WAIT_V(8); PG8_WAIT_L(0); PG8_BAR; PG8_MMA(1, 0, At, B0); PG8_MMA(1, 1, At, B1); PG8_BAR; PG8_SCHED;
	ds_read_b128 v[128:131], v218
	ds_read_b128 v[132:135], v218 offset:1024
	ds_read_b128 v[136:139], v218 offset:2048
	ds_read_b128 v[140:143], v218 offset:3072
	ds_read_b128 v[144:147], v219
	ds_read_b128 v[148:151], v219 offset:1024
	ds_read_b128 v[152:155], v219 offset:2048
	ds_read_b128 v[156:159], v219 offset:3072
	ds_read_b128 v[160:163], v204 offset:32768
	ds_read_b128 v[164:167], v204 offset:33792
	ds_read_b128 v[184:187], v204 offset:34816
	ds_read_b128 v[188:191], v204 offset:35840
	ds_read_b128 v[192:195], v204 offset:36864
	ds_read_b128 v[206:209], v204 offset:37888
	ds_read_b128 v[210:213], v204 offset:38912
	ds_read_b128 v[214:217], v204 offset:39936
	s_add_u32 s98, s60, 0x200000
	s_addc_u32 s99, s61, 0
	s_mov_b32 m0, s33
	s_add_u32 s100, s60, 0x80
	s_addc_u32 s101, s61, 0
	global_load_lds_dwordx4 v168, s[98:99]
	s_mov_b32 m0, s49
	s_nop 0
	global_load_lds_dwordx4 v172, s[98:99]
	s_add_i32 s73, 0, 0x18000
	s_add_i32 s74, 0, 0x1c000
	s_add_u32 s98, s58, 0x80
	s_addc_u32 s99, s59, 0
	s_add_i32 s60, s73, s1
	s_mov_b32 m0, s60
	s_waitcnt vmcnt(8)
	s_waitcnt lgkmcnt(0)
	s_barrier
	s_setprio 1
	s_waitcnt lgkmcnt(0)
	v_mfma_f32_16x16x32_bf16 v[124:127], v[128:131], v[160:163], v[124:127]
	v_mfma_f32_16x16x32_bf16 v[120:123], v[136:139], v[160:163], v[120:123]
	v_mfma_f32_16x16x32_bf16 v[116:119], v[128:131], v[184:187], v[116:119]
	v_mfma_f32_16x16x32_bf16 v[108:111], v[136:139], v[184:187], v[108:111]
	v_mfma_f32_16x16x32_bf16 v[92:95], v[128:131], v[192:195], v[92:95]
	v_mfma_f32_16x16x32_bf16 v[88:91], v[136:139], v[192:195], v[88:91]
	v_mfma_f32_16x16x32_bf16 v[76:79], v[128:131], v[210:213], v[76:79]
	v_mfma_f32_16x16x32_bf16 v[72:75], v[136:139], v[210:213], v[72:75]
	v_mfma_f32_16x16x32_bf16 v[124:127], v[132:135], v[164:167], v[124:127]
	v_mfma_f32_16x16x32_bf16 v[120:123], v[140:143], v[164:167], v[120:123]
	v_mfma_f32_16x16x32_bf16 v[116:119], v[132:135], v[188:191], v[116:119]
	v_mfma_f32_16x16x32_bf16 v[108:111], v[140:143], v[188:191], v[108:111]
	v_mfma_f32_16x16x32_bf16 v[92:95], v[132:135], v[206:209], v[92:95]
	v_mfma_f32_16x16x32_bf16 v[88:91], v[140:143], v[206:209], v[88:91]
	v_mfma_f32_16x16x32_bf16 v[76:79], v[132:135], v[214:217], v[76:79]
	v_mfma_f32_16x16x32_bf16 v[72:75], v[140:143], v[214:217], v[72:75]
	s_setprio 0
	s_setprio 1
	v_mfma_f32_16x16x32_bf16 v[112:115], v[144:147], v[160:163], v[112:115]
	v_mfma_f32_16x16x32_bf16 v[104:107], v[152:155], v[160:163], v[104:107]
	v_mfma_f32_16x16x32_bf16 v[100:103], v[144:147], v[184:187], v[100:103]
	v_mfma_f32_16x16x32_bf16 v[96:99], v[152:155], v[184:187], v[96:99]
	v_mfma_f32_16x16x32_bf16 v[84:87], v[144:147], v[192:195], v[84:87]
	v_mfma_f32_16x16x32_bf16 v[80:83], v[152:155], v[192:195], v[80:83]
	v_mfma_f32_16x16x32_bf16 v[68:71], v[144:147], v[210:213], v[68:71]
	v_mfma_f32_16x16x32_bf16 v[64:67], v[152:155], v[210:213], v[64:67]
	v_mfma_f32_16x16x32_bf16 v[112:115], v[148:151], v[164:167], v[112:115]
	v_mfma_f32_16x16x32_bf16 v[104:107], v[156:159], v[164:167], v[104:107]
	v_mfma_f32_16x16x32_bf16 v[100:103], v[148:151], v[188:191], v[100:103]
	v_mfma_f32_16x16x32_bf16 v[96:99], v[156:159], v[188:191], v[96:99]
	v_mfma_f32_16x16x32_bf16 v[84:87], v[148:151], v[206:209], v[84:87]
	v_mfma_f32_16x16x32_bf16 v[80:83], v[156:159], v[206:209], v[80:83]
	v_mfma_f32_16x16x32_bf16 v[68:71], v[148:151], v[214:217], v[68:71]
	v_mfma_f32_16x16x32_bf16 v[64:67], v[156:159], v[214:217], v[64:67]
	s_setprio 0
	s_barrier
	ds_read_b128 v[160:163], v204 offset:49152
	ds_read_b128 v[164:167], v204 offset:50176
	ds_read_b128 v[184:187], v204 offset:51200
	ds_read_b128 v[188:191], v204 offset:52224
	ds_read_b128 v[192:195], v204 offset:53248
	ds_read_b128 v[206:209], v204 offset:54272
	ds_read_b128 v[210:213], v204 offset:55296
	ds_read_b128 v[214:217], v204 offset:56320
	global_load_lds_dwordx4 v170, s[98:99]
	s_add_i32 m0, s60, 0x2000
	s_add_u32 s58, s58, 0x200080
	s_addc_u32 s59, s59, 0
	s_add_i32 s60, s74, s1
	global_load_lds_dwordx4 v174, s[98:99]
	s_mov_b32 m0, s60
	s_nop 0
	global_load_lds_dwordx4 v170, s[58:59]
	s_add_i32 m0, s60, 0x2000
	s_nop 0
	global_load_lds_dwordx4 v174, s[58:59]
	s_mov_b32 m0, s63
	s_nop 0
	global_load_lds_dwordx4 v168, s[100:101]
	s_mov_b32 m0, s64
	s_nop 0
	global_load_lds_dwordx4 v172, s[100:101]
	s_add_i32 s72, s72, 2
	s_add_u32 s50, s50, 0x100
	s_addc_u32 s51, s51, 0
	s_add_u32 s70, s70, 0x100
	s_addc_u32 s71, s71, 0
	s_cmpk_gt_u32 s72, 0x7d
	s_waitcnt vmcnt(8)
	s_waitcnt lgkmcnt(0)
	s_barrier
	s_setprio 1
	s_waitcnt lgkmcnt(0)
	v_mfma_f32_16x16x32_bf16 v[60:63], v[128:131], v[160:163], v[60:63]
	v_mfma_f32_16x16x32_bf16 v[56:59], v[136:139], v[160:163], v[56:59]
	v_mfma_f32_16x16x32_bf16 v[44:47], v[128:131], v[184:187], v[44:47]
	v_mfma_f32_16x16x32_bf16 v[40:43], v[136:139], v[184:187], v[40:43]
	v_mfma_f32_16x16x32_bf16 v[28:31], v[128:131], v[192:195], v[28:31]
	v_mfma_f32_16x16x32_bf16 v[24:27], v[136:139], v[192:195], v[24:27]
	v_mfma_f32_16x16x32_bf16 v[12:15], v[128:131], v[210:213], v[12:15]
	v_mfma_f32_16x16x32_bf16 v[8:11], v[136:139], v[210:213], v[8:11]
	v_mfma_f32_16x16x32_bf16 v[60:63], v[132:135], v[164:167], v[60:63]
	v_mfma_f32_16x16x32_bf16 v[56:59], v[140:143], v[164:167], v[56:59]
	v_mfma_f32_16x16x32_bf16 v[44:47], v[132:135], v[188:191], v[44:47]
	v_mfma_f32_16x16x32_bf16 v[40:43], v[140:143], v[188:191], v[40:43]
	v_mfma_f32_16x16x32_bf16 v[28:31], v[132:135], v[206:209], v[28:31]
	v_mfma_f32_16x16x32_bf16 v[24:27], v[140:143], v[206:209], v[24:27]
	v_mfma_f32_16x16x32_bf16 v[12:15], v[132:135], v[214:217], v[12:15]
	v_mfma_f32_16x16x32_bf16 v[8:11], v[140:143], v[214:217], v[8:11]
	s_setprio 0
	s_setprio 1
	v_mfma_f32_16x16x32_bf16 v[52:55], v[144:147], v[160:163], v[52:55]
	v_mfma_f32_16x16x32_bf16 v[48:51], v[152:155], v[160:163], v[48:51]
	v_mfma_f32_16x16x32_bf16 v[36:39], v[144:147], v[184:187], v[36:39]
	v_mfma_f32_16x16x32_bf16 v[32:35], v[152:155], v[184:187], v[32:35]
	v_mfma_f32_16x16x32_bf16 v[20:23], v[144:147], v[192:195], v[20:23]
	v_mfma_f32_16x16x32_bf16 v[16:19], v[152:155], v[192:195], v[16:19]
	v_mfma_f32_16x16x32_bf16 v[4:7], v[144:147], v[210:213], v[4:7]
	v_mfma_f32_16x16x32_bf16 v[0:3], v[152:155], v[210:213], v[0:3]
	v_mfma_f32_16x16x32_bf16 v[52:55], v[148:151], v[164:167], v[52:55]
	v_mfma_f32_16x16x32_bf16 v[48:51], v[156:159], v[164:167], v[48:51]
	v_mfma_f32_16x16x32_bf16 v[36:39], v[148:151], v[188:191], v[36:39]
	v_mfma_f32_16x16x32_bf16 v[32:35], v[156:159], v[188:191], v[32:35]
	v_mfma_f32_16x16x32_bf16 v[20:23], v[148:151], v[206:209], v[20:23]
	v_mfma_f32_16x16x32_bf16 v[16:19], v[156:159], v[206:209], v[16:19]
	v_mfma_f32_16x16x32_bf16 v[4:7], v[148:151], v[214:217], v[4:7]
	v_mfma_f32_16x16x32_bf16 v[0:3], v[156:159], v[214:217], v[0:3]
	s_setprio 0
	s_barrier
	s_cbranch_scc0 .LBB0_1260
	s_and_b64 vcc, exec, s[12:13]
	s_cbranch_vccz .LBB0_1263
	s_barrier

; #define PG8_STAGE(bufoff, gbase, voff) do { _Pragma("unroll") for (int _i = 0; _i < 2; ++_i) \
;         __builtin_amdgcn_global_load_lds((const unsigned*)((const char*)(gbase) + (voff)[_i]), (PG8_LAS unsigned*)(lds + (bufoff) + ldsw + _i * 8192), 16, 0, 0); } while (0)
; #define PG8_LDA(dst, b, h) do { _Pragma("unroll") for (int m = 0; m < 4; ++m) _Pragma("unroll") for (int k = 0; k < 2; ++k) dst[m][k] = *(const PG8_LAS bf16x8*)(lds + PG8_SA(b, h) + aoff + m * 2048 + k * 1024); } while (0)
; #define PG8_LDB(dst, b, h) do { _Pragma("unroll") for (int n = 0; n < 2; ++n) _Pragma("unroll") for (int k = 0; k < 2; ++k) dst[n][k] = *(const PG8_LAS bf16x8*)(lds + PG8_SB(b, h) + boff + n * 2048 + k * 1024); } while (0)
; #define PG8_MMA(ai, bj, At, Bt) do { __builtin_amdgcn_s_setprio(1); _Pragma("unroll") for (int m = 0; m < 4; ++m) _Pragma("unroll") for (int n = 0; n < 2; ++n) _Pragma("unroll") for (int k = 0; k < 2; ++k) \
;         acc[ai][bj][m][n] = __builtin_amdgcn_mfma_f32_16x16x32_bf16(Bt[n][k], At[m][k], acc[ai][bj][m][n], 0, 0, 0); __builtin_amdgcn_s_setprio(0); } while (0)
; #define PG8_WAIT_V(n) asm volatile("s_waitcnt vmcnt(" #n ")" ::: "memory")
; #define PG8_WAIT_L(n) asm volatile("s_waitcnt lgkmcnt(" #n ")" ::: "memory")
; #define PG8_BAR __builtin_amdgcn_s_barrier()
; template <class Epi, class Sched, bool ALIGN_EPI = false, bool SP2 = false>
; __device__ __forceinline__ void gemm_phase(PG8_LAS unsigned char* lds, const Gemm g, const Sched& S, const Epi& E) {
;     ...
;             const char* a1 = cA + (size_t)(t + 1) * kstep;
;             const char* a2 = last ? nA : cA + (size_t)(t + 2) * kstep; const char* b2 = last ? nB : cB + (size_t)(t + 2) * kstep;
;             const char* a3 = a2 + kstep; const char* b3 = b2 + kstep;
;             if (last && has_next) S.a_ready(nxt);
;             if constexpr (SP2) {
;             PG8_LDB(B0, 0, 0); PG8_LDB(B1, 0, 1); PG8_SCHED; PG8_LDA(At, 0, 0); PG8_STAGE(PG8_SA(1, 1), a1 + hstep, voffA);
;             PG8_WAIT_V(8); PG8_WAIT_L(0); PG8_BAR; PG8_MMA(0, 0, At, B0); PG8_MMA(0, 1, At, B1); PG8_BAR; PG8_SCHED;
;             PG8_LDA(At, 0, 1); PG8_STAGE(PG8_SB(0, 0), b2, voffB); PG8_STAGE(PG8_SB(0, 1), b2 + hstep, voffB); PG8_STAGE(PG8_SA(0, 0), a2, voffA);
;             PG8_WAIT_V(8); PG8_WAIT_L(0); PG8_BAR; PG8_MMA(1, 0, At, B0); PG8_MMA(1, 1, At, B1); PG8_BAR; PG8_SCHED;
.LBB0_1336:
	ds_read_b128 v[152:155], v149
	ds_read_b128 v[156:159], v149 offset:1024
	ds_read_b128 v[160:163], v149 offset:2048
	ds_read_b128 v[164:167], v149 offset:3072
	ds_read_b128 v[168:171], v150
	ds_read_b128 v[172:175], v150 offset:1024
	ds_read_b128 v[176:179], v150 offset:2048
	ds_read_b128 v[180:183], v150 offset:3072
	s_add_i32 m0, s33, 0xc000
	ds_read_b128 v[184:187], v151
	ds_read_b128 v[188:191], v151 offset:1024
	ds_read_b128 v[192:195], v151 offset:2048
	ds_read_b128 v[196:199], v151 offset:3072
	ds_read_b128 v[200:203], v151 offset:4096
	ds_read_b128 v[204:207], v151 offset:5120
	ds_read_b128 v[208:211], v151 offset:6144
	ds_read_b128 v[212:215], v151 offset:7168
	global_load_lds_dwordx4 v136, s[46:47]
	s_add_i32 m0, s33, 0xe000
	s_nop 0
	global_load_lds_dwordx4 v138, s[46:47]
	s_add_u32 s48, s46, 0xfff80080
	s_addc_u32 s49, s47, -1
	s_cmp_eq_u32 s74, 28
	s_cselect_b32 s51, s25, s49
	s_cselect_b32 s50, s29, s48
	s_cselect_b32 s49, s23, s73
	s_cselect_b32 s48, s71, s72
	s_add_i32 s75, s65, s1
	s_mov_b32 m0, s75
	s_waitcnt vmcnt(8)
	s_waitcnt lgkmcnt(0)
	s_barrier
	s_setprio 1
	s_waitcnt lgkmcnt(0)
	v_mfma_f32_16x16x32_bf16 v[124:127], v[152:155], v[184:187], v[124:127]
	v_mfma_f32_16x16x32_bf16 v[120:123], v[160:163], v[184:187], v[120:123]
	v_mfma_f32_16x16x32_bf16 v[108:111], v[152:155], v[192:195], v[108:111]
	v_mfma_f32_16x16x32_bf16 v[104:107], v[160:163], v[192:195], v[104:107]
	v_mfma_f32_16x16x32_bf16 v[92:95], v[152:155], v[200:203], v[92:95]
	v_mfma_f32_16x16x32_bf16 v[88:91], v[160:163], v[200:203], v[88:91]
	v_mfma_f32_16x16x32_bf16 v[76:79], v[152:155], v[208:211], v[76:79]
	v_mfma_f32_16x16x32_bf16 v[72:75], v[160:163], v[208:211], v[72:75]
	v_mfma_f32_16x16x32_bf16 v[124:127], v[156:159], v[188:191], v[124:127]
	v_mfma_f32_16x16x32_bf16 v[120:123], v[164:167], v[188:191], v[120:123]
	v_mfma_f32_16x16x32_bf16 v[108:111], v[156:159], v[196:199], v[108:111]
	v_mfma_f32_16x16x32_bf16 v[104:107], v[164:167], v[196:199], v[104:107]
	v_mfma_f32_16x16x32_bf16 v[92:95], v[156:159], v[204:207], v[92:95]
	v_mfma_f32_16x16x32_bf16 v[88:91], v[164:167], v[204:207], v[88:91]
	v_mfma_f32_16x16x32_bf16 v[76:79], v[156:159], v[212:215], v[76:79]
	v_mfma_f32_16x16x32_bf16 v[72:75], v[164:167], v[212:215], v[72:75]
	s_setprio 0
	s_setprio 1
	v_mfma_f32_16x16x32_bf16 v[116:119], v[168:171], v[184:187], v[116:119]
	v_mfma_f32_16x16x32_bf16 v[112:115], v[176:179], v[184:187], v[112:115]
	v_mfma_f32_16x16x32_bf16 v[100:103], v[168:171], v[192:195], v[100:103]
	v_mfma_f32_16x16x32_bf16 v[96:99], v[176:179], v[192:195], v[96:99]
	v_mfma_f32_16x16x32_bf16 v[84:87], v[168:171], v[200:203], v[84:87]
	v_mfma_f32_16x16x32_bf16 v[80:83], v[176:179], v[200:203], v[80:83]
	v_mfma_f32_16x16x32_bf16 v[68:71], v[168:171], v[208:211], v[68:71]
	v_mfma_f32_16x16x32_bf16 v[64:67], v[176:179], v[208:211], v[64:67]
	v_mfma_f32_16x16x32_bf16 v[116:119], v[172:175], v[188:191], v[116:119]
	v_mfma_f32_16x16x32_bf16 v[112:115], v[180:183], v[188:191], v[112:115]
	v_mfma_f32_16x16x32_bf16 v[100:103], v[172:175], v[196:199], v[100:103]
	v_mfma_f32_16x16x32_bf16 v[96:99], v[180:183], v[196:199], v[96:99]
	v_mfma_f32_16x16x32_bf16 v[84:87], v[172:175], v[204:207], v[84:87]
	v_mfma_f32_16x16x32_bf16 v[80:83], v[180:183], v[204:207], v[80:83]
	v_mfma_f32_16x16x32_bf16 v[68:71], v[172:175], v[212:215], v[68:71]
	v_mfma_f32_16x16x32_bf16 v[64:67], v[180:183], v[212:215], v[64:67]
	s_setprio 0
	s_barrier
	ds_read_b128 v[184:187], v151 offset:16384
	ds_read_b128 v[188:191], v151 offset:17408
	ds_read_b128 v[192:195], v151 offset:18432
	ds_read_b128 v[196:199], v151 offset:19456
	ds_read_b128 v[200:203], v151 offset:20480
	ds_read_b128 v[204:207], v151 offset:21504
	ds_read_b128 v[208:211], v151 offset:22528
	ds_read_b128 v[212:215], v151 offset:23552
	global_load_lds_dwordx4 v130, s[48:49]
	s_add_i32 m0, s75, 0x2000
	s_add_u32 s76, s48, 0x80000
	s_addc_u32 s77, s49, 0
	s_add_i32 s75, s66, s1
	global_load_lds_dwordx4 v134, s[48:49]
	s_mov_b32 m0, s75
	s_nop 0
	global_load_lds_dwordx4 v130, s[76:77]
	s_add_i32 m0, s75, 0x2000
	s_nop 0
	global_load_lds_dwordx4 v134, s[76:77]
	s_mov_b32 m0, s33
	s_nop 0
	global_load_lds_dwordx4 v128, s[50:51]
	s_mov_b32 m0, s43
	s_nop 0
	global_load_lds_dwordx4 v132, s[50:51]
	s_waitcnt vmcnt(8)
	s_waitcnt lgkmcnt(0)
	s_barrier
	s_setprio 1
	s_waitcnt lgkmcnt(0)
	v_mfma_f32_16x16x32_bf16 v[60:63], v[152:155], v[184:187], v[60:63]
	v_mfma_f32_16x16x32_bf16 v[56:59], v[160:163], v[184:187], v[56:59]
	v_mfma_f32_16x16x32_bf16 v[44:47], v[152:155], v[192:195], v[44:47]
	v_mfma_f32_16x16x32_bf16 v[40:43], v[160:163], v[192:195], v[40:43]
	v_mfma_f32_16x16x32_bf16 v[28:31], v[152:155], v[200:203], v[28:31]
	v_mfma_f32_16x16x32_bf16 v[24:27], v[160:163], v[200:203], v[24:27]
	v_mfma_f32_16x16x32_bf16 v[12:15], v[152:155], v[208:211], v[12:15]
	v_mfma_f32_16x16x32_bf16 v[8:11], v[160:163], v[208:211], v[8:11]
	v_mfma_f32_16x16x32_bf16 v[60:63], v[156:159], v[188:191], v[60:63]
	v_mfma_f32_16x16x32_bf16 v[56:59], v[164:167], v[188:191], v[56:59]
	v_mfma_f32_16x16x32_bf16 v[44:47], v[156:159], v[196:199], v[44:47]
	v_mfma_f32_16x16x32_bf16 v[40:43], v[164:167], v[196:199], v[40:43]
	v_mfma_f32_16x16x32_bf16 v[28:31], v[156:159], v[204:207], v[28:31]
	v_mfma_f32_16x16x32_bf16 v[24:27], v[164:167], v[204:207], v[24:27]
	v_mfma_f32_16x16x32_bf16 v[12:15], v[156:159], v[212:215], v[12:15]
	v_mfma_f32_16x16x32_bf16 v[8:11], v[164:167], v[212:215], v[8:11]
	s_setprio 0
	s_setprio 1
	v_mfma_f32_16x16x32_bf16 v[52:55], v[168:171], v[184:187], v[52:55]
	v_mfma_f32_16x16x32_bf16 v[48:51], v[176:179], v[184:187], v[48:51]
	v_mfma_f32_16x16x32_bf16 v[36:39], v[168:171], v[192:195], v[36:39]
	v_mfma_f32_16x16x32_bf16 v[32:35], v[176:179], v[192:195], v[32:35]
	v_mfma_f32_16x16x32_bf16 v[20:23], v[168:171], v[200:203], v[20:23]
	v_mfma_f32_16x16x32_bf16 v[16:19], v[176:179], v[200:203], v[16:19]
	v_mfma_f32_16x16x32_bf16 v[4:7], v[168:171], v[208:211], v[4:7]
	v_mfma_f32_16x16x32_bf16 v[0:3], v[176:179], v[208:211], v[0:3]
	v_mfma_f32_16x16x32_bf16 v[52:55], v[172:175], v[188:191], v[52:55]
	v_mfma_f32_16x16x32_bf16 v[48:51], v[180:183], v[188:191], v[48:51]
	v_mfma_f32_16x16x32_bf16 v[36:39], v[172:175], v[196:199], v[36:39]
	v_mfma_f32_16x16x32_bf16 v[32:35], v[180:183], v[196:199], v[32:35]
	v_mfma_f32_16x16x32_bf16 v[20:23], v[172:175], v[204:207], v[20:23]
	v_mfma_f32_16x16x32_bf16 v[16:19], v[180:183], v[204:207], v[16:19]
	v_mfma_f32_16x16x32_bf16 v[4:7], v[172:175], v[212:215], v[4:7]
	v_mfma_f32_16x16x32_bf16 v[0:3], v[180:183], v[212:215], v[0:3]
	s_setprio 0
	s_barrier
; #define PG8_STAGE(bufoff, gbase, voff) do { _Pragma("unroll") for (int _i = 0; _i < 2; ++_i) \
;         __builtin_amdgcn_global_load_lds((const unsigned*)((const char*)(gbase) + (voff)[_i]), (PG8_LAS unsigned*)(lds + (bufoff) + ldsw + _i * 8192), 16, 0, 0); } while (0)
; #define PG8_LDA(dst, b, h) do { _Pragma("unroll") for (int m = 0; m < 4; ++m) _Pragma("unroll") for (int k = 0; k < 2; ++k) dst[m][k] = *(const PG8_LAS bf16x8*)(lds + PG8_SA(b, h) + aoff + m * 2048 + k * 1024); } while (0)
; #define PG8_LDB(dst, b, h) do { _Pragma("unroll") for (int n = 0; n < 2; ++n) _Pragma("unroll") for (int k = 0; k < 2; ++k) dst[n][k] = *(const PG8_LAS bf16x8*)(lds + PG8_SB(b, h) + boff + n * 2048 + k * 1024); } while (0)
; #define PG8_MMA(ai, bj, At, Bt) do { __builtin_amdgcn_s_setprio(1); _Pragma("unroll") for (int m = 0; m < 4; ++m) _Pragma("unroll") for (int n = 0; n < 2; ++n) _Pragma("unroll") for (int k = 0; k < 2; ++k) \
;         acc[ai][bj][m][n] = __builtin_amdgcn_mfma_f32_16x16x32_bf16(Bt[n][k], At[m][k], acc[ai][bj][m][n], 0, 0, 0); __builtin_amdgcn_s_setprio(0); } while (0)
; #define PG8_WAIT_V(n) asm volatile("s_waitcnt vmcnt(" #n ")" ::: "memory")
; #define PG8_WAIT_L(n) asm volatile("s_waitcnt lgkmcnt(" #n ")" ::: "memory")
; #define PG8_BAR __builtin_amdgcn_s_barrier()
; #define PG8_SCHED __builtin_amdgcn_sched_barrier(0)
; template <class Epi, class Sched, bool ALIGN_EPI = false, bool SP2 = false>
; __device__ __forceinline__ void gemm_phase(PG8_LAS unsigned char* lds, const Gemm g, const Sched& S, const Epi& E) {
;     ...
;         for (int t = 0; t < nt; t += 2) {
;             const bool last = (t == nt - 2);
;             const char* a1 = cA + (size_t)(t + 1) * kstep;
;             const char* a2 = last ? nA : cA + (size_t)(t + 2) * kstep; const char* b2 = last ? nB : cB + (size_t)(t + 2) * kstep;
;     ...
;             PG8_LDB(B0, 1, 0); PG8_LDB(B1, 1, 1); PG8_SCHED; PG8_LDA(At, 1, 0); PG8_STAGE(PG8_SA(0, 1), a2 + hstep, voffA);
;             PG8_WAIT_V(8); PG8_WAIT_L(0); PG8_BAR; PG8_MMA(0, 0, At, B0); PG8_MMA(0, 1, At, B1); PG8_BAR; PG8_SCHED;
;             PG8_LDA(At, 1, 1); PG8_STAGE(PG8_SB(1, 0), b3, voffB); PG8_STAGE(PG8_SB(1, 1), b3 + hstep, voffB); PG8_STAGE(PG8_SA(1, 0), a3, voffA);
;             PG8_WAIT_V(8); PG8_WAIT_L(0); PG8_BAR; PG8_MMA(1, 0, At, B0); PG8_MMA(1, 1, At, B1); PG8_BAR; PG8_SCHED;
	ds_read_b128 v[152:155], v216
	ds_read_b128 v[156:159], v216 offset:1024
	ds_read_b128 v[160:163], v216 offset:2048
	ds_read_b128 v[164:167], v216 offset:3072
	ds_read_b128 v[168:171], v217
	ds_read_b128 v[172:175], v217 offset:1024
	ds_read_b128 v[176:179], v217 offset:2048
	ds_read_b128 v[180:183], v217 offset:3072
	ds_read_b128 v[184:187], v151 offset:32768
	ds_read_b128 v[188:191], v151 offset:33792
	ds_read_b128 v[192:195], v151 offset:34816
	ds_read_b128 v[196:199], v151 offset:35840
	ds_read_b128 v[200:203], v151 offset:36864
	ds_read_b128 v[204:207], v151 offset:37888
	ds_read_b128 v[208:211], v151 offset:38912
	ds_read_b128 v[212:215], v151 offset:39936
	s_add_u32 s98, s50, 0x80000
	s_addc_u32 s99, s51, 0
	s_mov_b32 m0, s58
	s_add_u32 s100, s50, 0x80
	s_addc_u32 s101, s51, 0
	global_load_lds_dwordx4 v128, s[98:99]
	s_mov_b32 m0, s59
	s_nop 0
	global_load_lds_dwordx4 v132, s[98:99]
	s_add_i32 s75, 0, 0x18000
	s_add_i32 s76, 0, 0x1c000
	s_add_u32 s98, s48, 0x80
	s_addc_u32 s99, s49, 0
	s_add_i32 s50, s75, s1
	s_mov_b32 m0, s50
	s_waitcnt vmcnt(8)
	s_waitcnt lgkmcnt(0)
	s_barrier
	s_setprio 1
	s_waitcnt lgkmcnt(0)
	v_mfma_f32_16x16x32_bf16 v[124:127], v[152:155], v[184:187], v[124:127]
	v_mfma_f32_16x16x32_bf16 v[120:123], v[160:163], v[184:187], v[120:123]
	v_mfma_f32_16x16x32_bf16 v[108:111], v[152:155], v[192:195], v[108:111]
	v_mfma_f32_16x16x32_bf16 v[104:107], v[160:163], v[192:195], v[104:107]
	v_mfma_f32_16x16x32_bf16 v[92:95], v[152:155], v[200:203], v[92:95]
	v_mfma_f32_16x16x32_bf16 v[88:91], v[160:163], v[200:203], v[88:91]
	v_mfma_f32_16x16x32_bf16 v[76:79], v[152:155], v[208:211], v[76:79]
	v_mfma_f32_16x16x32_bf16 v[72:75], v[160:163], v[208:211], v[72:75]
	v_mfma_f32_16x16x32_bf16 v[124:127], v[156:159], v[188:191], v[124:127]
	v_mfma_f32_16x16x32_bf16 v[120:123], v[164:167], v[188:191], v[120:123]
	v_mfma_f32_16x16x32_bf16 v[108:111], v[156:159], v[196:199], v[108:111]
	v_mfma_f32_16x16x32_bf16 v[104:107], v[164:167], v[196:199], v[104:107]
	v_mfma_f32_16x16x32_bf16 v[92:95], v[156:159], v[204:207], v[92:95]
	v_mfma_f32_16x16x32_bf16 v[88:91], v[164:167], v[204:207], v[88:91]
	v_mfma_f32_16x16x32_bf16 v[76:79], v[156:159], v[212:215], v[76:79]
	v_mfma_f32_16x16x32_bf16 v[72:75], v[164:167], v[212:215], v[72:75]
	s_setprio 0
	s_setprio 1
	v_mfma_f32_16x16x32_bf16 v[116:119], v[168:171], v[184:187], v[116:119]
	v_mfma_f32_16x16x32_bf16 v[112:115], v[176:179], v[184:187], v[112:115]
	v_mfma_f32_16x16x32_bf16 v[100:103], v[168:171], v[192:195], v[100:103]
	v_mfma_f32_16x16x32_bf16 v[96:99], v[176:179], v[192:195], v[96:99]
	v_mfma_f32_16x16x32_bf16 v[84:87], v[168:171], v[200:203], v[84:87]
	v_mfma_f32_16x16x32_bf16 v[80:83], v[176:179], v[200:203], v[80:83]
	v_mfma_f32_16x16x32_bf16 v[68:71], v[168:171], v[208:211], v[68:71]
	v_mfma_f32_16x16x32_bf16 v[64:67], v[176:179], v[208:211], v[64:67]
	v_mfma_f32_16x16x32_bf16 v[116:119], v[172:175], v[188:191], v[116:119]
	v_mfma_f32_16x16x32_bf16 v[112:115], v[180:183], v[188:191], v[112:115]
	v_mfma_f32_16x16x32_bf16 v[100:103], v[172:175], v[196:199], v[100:103]
	v_mfma_f32_16x16x32_bf16 v[96:99], v[180:183], v[196:199], v[96:99]
	v_mfma_f32_16x16x32_bf16 v[84:87], v[172:175], v[204:207], v[84:87]
	v_mfma_f32_16x16x32_bf16 v[80:83], v[180:183], v[204:207], v[80:83]
	v_mfma_f32_16x16x32_bf16 v[68:71], v[172:175], v[212:215], v[68:71]
	v_mfma_f32_16x16x32_bf16 v[64:67], v[180:183], v[212:215], v[64:67]
	s_setprio 0
	s_barrier
	ds_read_b128 v[184:187], v151 offset:49152
	ds_read_b128 v[188:191], v151 offset:50176
	ds_read_b128 v[192:195], v151 offset:51200
	ds_read_b128 v[196:199], v151 offset:52224
	ds_read_b128 v[200:203], v151 offset:53248
	ds_read_b128 v[204:207], v151 offset:54272
	ds_read_b128 v[208:211], v151 offset:55296
	ds_read_b128 v[212:215], v151 offset:56320
	global_load_lds_dwordx4 v130, s[98:99]
	s_add_i32 m0, s50, 0x2000
	s_add_u32 s48, s48, 0x80080
	s_addc_u32 s49, s49, 0
	s_add_i32 s50, s76, s1
	global_load_lds_dwordx4 v134, s[98:99]
	s_mov_b32 m0, s50
	s_nop 0
	global_load_lds_dwordx4 v130, s[48:49]
	s_add_i32 m0, s50, 0x2000
	s_nop 0
	global_load_lds_dwordx4 v134, s[48:49]
	s_mov_b32 m0, s61
	s_nop 0
	global_load_lds_dwordx4 v128, s[100:101]
	s_mov_b32 m0, s62
	s_nop 0
	global_load_lds_dwordx4 v132, s[100:101]
	s_add_i32 s74, s74, 2
	s_add_u32 s46, s46, 0x100
	s_addc_u32 s47, s47, 0
	s_add_u32 s72, s72, 0x100
	s_addc_u32 s73, s73, 0
	s_cmp_gt_u32 s74, 29
	s_waitcnt vmcnt(8)
	s_waitcnt lgkmcnt(0)
	s_barrier
	s_setprio 1
	s_waitcnt lgkmcnt(0)
	v_mfma_f32_16x16x32_bf16 v[60:63], v[152:155], v[184:187], v[60:63]
	v_mfma_f32_16x16x32_bf16 v[56:59], v[160:163], v[184:187], v[56:59]
	v_mfma_f32_16x16x32_bf16 v[44:47], v[152:155], v[192:195], v[44:47]
	v_mfma_f32_16x16x32_bf16 v[40:43], v[160:163], v[192:195], v[40:43]
	v_mfma_f32_16x16x32_bf16 v[28:31], v[152:155], v[200:203], v[28:31]
	v_mfma_f32_16x16x32_bf16 v[24:27], v[160:163], v[200:203], v[24:27]
	v_mfma_f32_16x16x32_bf16 v[12:15], v[152:155], v[208:211], v[12:15]
	v_mfma_f32_16x16x32_bf16 v[8:11], v[160:163], v[208:211], v[8:11]
	v_mfma_f32_16x16x32_bf16 v[60:63], v[156:159], v[188:191], v[60:63]
	v_mfma_f32_16x16x32_bf16 v[56:59], v[164:167], v[188:191], v[56:59]
	v_mfma_f32_16x16x32_bf16 v[44:47], v[156:159], v[196:199], v[44:47]
	v_mfma_f32_16x16x32_bf16 v[40:43], v[164:167], v[196:199], v[40:43]
	v_mfma_f32_16x16x32_bf16 v[28:31], v[156:159], v[204:207], v[28:31]
	v_mfma_f32_16x16x32_bf16 v[24:27], v[164:167], v[204:207], v[24:27]
	v_mfma_f32_16x16x32_bf16 v[12:15], v[156:159], v[212:215], v[12:15]
	v_mfma_f32_16x16x32_bf16 v[8:11], v[164:167], v[212:215], v[8:11]
	s_setprio 0
	s_setprio 1
	v_mfma_f32_16x16x32_bf16 v[52:55], v[168:171], v[184:187], v[52:55]
	v_mfma_f32_16x16x32_bf16 v[48:51], v[176:179], v[184:187], v[48:51]
	v_mfma_f32_16x16x32_bf16 v[36:39], v[168:171], v[192:195], v[36:39]
	v_mfma_f32_16x16x32_bf16 v[32:35], v[176:179], v[192:195], v[32:35]
	v_mfma_f32_16x16x32_bf16 v[20:23], v[168:171], v[200:203], v[20:23]
	v_mfma_f32_16x16x32_bf16 v[16:19], v[176:179], v[200:203], v[16:19]
	v_mfma_f32_16x16x32_bf16 v[4:7], v[168:171], v[208:211], v[4:7]
	v_mfma_f32_16x16x32_bf16 v[0:3], v[176:179], v[208:211], v[0:3]
	v_mfma_f32_16x16x32_bf16 v[52:55], v[172:175], v[188:191], v[52:55]
	v_mfma_f32_16x16x32_bf16 v[48:51], v[180:183], v[188:191], v[48:51]
	v_mfma_f32_16x16x32_bf16 v[36:39], v[172:175], v[196:199], v[36:39]
	v_mfma_f32_16x16x32_bf16 v[32:35], v[180:183], v[196:199], v[32:35]
	v_mfma_f32_16x16x32_bf16 v[20:23], v[172:175], v[204:207], v[20:23]
	v_mfma_f32_16x16x32_bf16 v[16:19], v[180:183], v[204:207], v[16:19]
	v_mfma_f32_16x16x32_bf16 v[4:7], v[172:175], v[212:215], v[4:7]
	v_mfma_f32_16x16x32_bf16 v[0:3], v[180:183], v[212:215], v[0:3]
	s_setprio 0
	s_barrier
	s_cbranch_scc0 .LBB0_1336
	s_and_b64 vcc, exec, s[12:13]
	s_cbranch_vccz .LBB0_1339
	s_barrier

; #define PG8_STAGE(bufoff, gbase, voff) do { _Pragma("unroll") for (int _i = 0; _i < 2; ++_i) \
;         __builtin_amdgcn_global_load_lds((const unsigned*)((const char*)(gbase) + (voff)[_i]), (PG8_LAS unsigned*)(lds + (bufoff) + ldsw + _i * 8192), 16, 0, 0); } while (0)
; #define PG8_LDA(dst, b, h) do { _Pragma("unroll") for (int m = 0; m < 4; ++m) _Pragma("unroll") for (int k = 0; k < 2; ++k) dst[m][k] = *(const PG8_LAS bf16x8*)(lds + PG8_SA(b, h) + aoff + m * 2048 + k * 1024); } while (0)
; #define PG8_LDB(dst, b, h) do { _Pragma("unroll") for (int n = 0; n < 2; ++n) _Pragma("unroll") for (int k = 0; k < 2; ++k) dst[n][k] = *(const PG8_LAS bf16x8*)(lds + PG8_SB(b, h) + boff + n * 2048 + k * 1024); } while (0)
; #define PG8_MMA(ai, bj, At, Bt) do { __builtin_amdgcn_s_setprio(1); _Pragma("unroll") for (int m = 0; m < 4; ++m) _Pragma("unroll") for (int n = 0; n < 2; ++n) _Pragma("unroll") for (int k = 0; k < 2; ++k) \
;         acc[ai][bj][m][n] = __builtin_amdgcn_mfma_f32_16x16x32_bf16(Bt[n][k], At[m][k], acc[ai][bj][m][n], 0, 0, 0); __builtin_amdgcn_s_setprio(0); } while (0)
; #define PG8_WAIT_V(n) asm volatile("s_waitcnt vmcnt(" #n ")" ::: "memory")
; #define PG8_WAIT_L(n) asm volatile("s_waitcnt lgkmcnt(" #n ")" ::: "memory")
; #define PG8_BAR __builtin_amdgcn_s_barrier()
; template <class Epi, class Sched, bool ALIGN_EPI = false, bool SP2 = false>
; __device__ __forceinline__ void gemm_phase(PG8_LAS unsigned char* lds, const Gemm g, const Sched& S, const Epi& E) {
;     ...
;             const char* a1 = cA + (size_t)(t + 1) * kstep;
;             const char* a2 = last ? nA : cA + (size_t)(t + 2) * kstep; const char* b2 = last ? nB : cB + (size_t)(t + 2) * kstep;
;             const char* a3 = a2 + kstep; const char* b3 = b2 + kstep;
;             if (last && has_next) S.a_ready(nxt);
;             if constexpr (SP2) {
;             PG8_LDB(B0, 0, 0); PG8_LDB(B1, 0, 1); PG8_SCHED; PG8_LDA(At, 0, 0); PG8_STAGE(PG8_SA(1, 1), a1 + hstep, voffA);
;             PG8_WAIT_V(8); PG8_WAIT_L(0); PG8_BAR; PG8_MMA(0, 0, At, B0); PG8_MMA(0, 1, At, B1); PG8_BAR; PG8_SCHED;
;             PG8_LDA(At, 0, 1); PG8_STAGE(PG8_SB(0, 0), b2, voffB); PG8_STAGE(PG8_SB(0, 1), b2 + hstep, voffB); PG8_STAGE(PG8_SA(0, 0), a2, voffA);
;             PG8_WAIT_V(8); PG8_WAIT_L(0); PG8_BAR; PG8_MMA(1, 0, At, B0); PG8_MMA(1, 1, At, B1); PG8_BAR; PG8_SCHED;
.LBB0_1412:
	ds_read_b128 v[128:131], v202
	ds_read_b128 v[132:135], v202 offset:1024
	ds_read_b128 v[136:139], v202 offset:2048
	ds_read_b128 v[140:143], v202 offset:3072
	ds_read_b128 v[144:147], v203
	ds_read_b128 v[148:151], v203 offset:1024
	ds_read_b128 v[152:155], v203 offset:2048
	ds_read_b128 v[156:159], v203 offset:3072
	s_add_i32 m0, s33, 0xc000
	ds_read_b128 v[160:163], v204
	ds_read_b128 v[164:167], v204 offset:1024
	ds_read_b128 v[184:187], v204 offset:2048
	ds_read_b128 v[188:191], v204 offset:3072
	ds_read_b128 v[192:195], v204 offset:4096
	ds_read_b128 v[206:209], v204 offset:5120
	ds_read_b128 v[210:213], v204 offset:6144
	ds_read_b128 v[214:217], v204 offset:7168
	global_load_lds_dwordx4 v176, s[42:43]
	s_add_i32 m0, s33, 0xe000
	s_nop 0
	global_load_lds_dwordx4 v178, s[42:43]
	s_add_u32 s46, s42, 0xffe00080
	s_addc_u32 s47, s43, -1
	s_cmpk_eq_i32 s68, 0x7c
	s_cselect_b32 s49, s23, s47
	s_cselect_b32 s48, s25, s46
	s_cselect_b32 s47, s21, s67
	s_cselect_b32 s46, s65, s66
	s_add_i32 s69, s63, s1
	s_mov_b32 m0, s69
	s_waitcnt vmcnt(8)
	s_waitcnt lgkmcnt(0)
	s_barrier
	s_setprio 1
	s_waitcnt lgkmcnt(0)
	v_mfma_f32_16x16x32_bf16 v[124:127], v[128:131], v[160:163], v[124:127]
	v_mfma_f32_16x16x32_bf16 v[120:123], v[136:139], v[160:163], v[120:123]
	v_mfma_f32_16x16x32_bf16 v[116:119], v[128:131], v[184:187], v[116:119]
	v_mfma_f32_16x16x32_bf16 v[108:111], v[136:139], v[184:187], v[108:111]
	v_mfma_f32_16x16x32_bf16 v[92:95], v[128:131], v[192:195], v[92:95]
	v_mfma_f32_16x16x32_bf16 v[88:91], v[136:139], v[192:195], v[88:91]
	v_mfma_f32_16x16x32_bf16 v[76:79], v[128:131], v[210:213], v[76:79]
	v_mfma_f32_16x16x32_bf16 v[72:75], v[136:139], v[210:213], v[72:75]
	v_mfma_f32_16x16x32_bf16 v[124:127], v[132:135], v[164:167], v[124:127]
	v_mfma_f32_16x16x32_bf16 v[120:123], v[140:143], v[164:167], v[120:123]
	v_mfma_f32_16x16x32_bf16 v[116:119], v[132:135], v[188:191], v[116:119]
	v_mfma_f32_16x16x32_bf16 v[108:111], v[140:143], v[188:191], v[108:111]
	v_mfma_f32_16x16x32_bf16 v[92:95], v[132:135], v[206:209], v[92:95]
	v_mfma_f32_16x16x32_bf16 v[88:91], v[140:143], v[206:209], v[88:91]
	v_mfma_f32_16x16x32_bf16 v[76:79], v[132:135], v[214:217], v[76:79]
	v_mfma_f32_16x16x32_bf16 v[72:75], v[140:143], v[214:217], v[72:75]
	s_setprio 0
	s_setprio 1
	v_mfma_f32_16x16x32_bf16 v[112:115], v[144:147], v[160:163], v[112:115]
	v_mfma_f32_16x16x32_bf16 v[104:107], v[152:155], v[160:163], v[104:107]
	v_mfma_f32_16x16x32_bf16 v[100:103], v[144:147], v[184:187], v[100:103]
	v_mfma_f32_16x16x32_bf16 v[96:99], v[152:155], v[184:187], v[96:99]
	v_mfma_f32_16x16x32_bf16 v[84:87], v[144:147], v[192:195], v[84:87]
	v_mfma_f32_16x16x32_bf16 v[80:83], v[152:155], v[192:195], v[80:83]
	v_mfma_f32_16x16x32_bf16 v[68:71], v[144:147], v[210:213], v[68:71]
	v_mfma_f32_16x16x32_bf16 v[64:67], v[152:155], v[210:213], v[64:67]
	v_mfma_f32_16x16x32_bf16 v[112:115], v[148:151], v[164:167], v[112:115]
	v_mfma_f32_16x16x32_bf16 v[104:107], v[156:159], v[164:167], v[104:107]
	v_mfma_f32_16x16x32_bf16 v[100:103], v[148:151], v[188:191], v[100:103]
	v_mfma_f32_16x16x32_bf16 v[96:99], v[156:159], v[188:191], v[96:99]
	v_mfma_f32_16x16x32_bf16 v[84:87], v[148:151], v[206:209], v[84:87]
	v_mfma_f32_16x16x32_bf16 v[80:83], v[156:159], v[206:209], v[80:83]
	v_mfma_f32_16x16x32_bf16 v[68:71], v[148:151], v[214:217], v[68:71]
	v_mfma_f32_16x16x32_bf16 v[64:67], v[156:159], v[214:217], v[64:67]
	s_setprio 0
	s_barrier
	ds_read_b128 v[160:163], v204 offset:16384
	ds_read_b128 v[164:167], v204 offset:17408
	ds_read_b128 v[184:187], v204 offset:18432
	ds_read_b128 v[188:191], v204 offset:19456
	ds_read_b128 v[192:195], v204 offset:20480
	ds_read_b128 v[206:209], v204 offset:21504
	ds_read_b128 v[210:213], v204 offset:22528
	ds_read_b128 v[214:217], v204 offset:23552
	global_load_lds_dwordx4 v170, s[46:47]
	s_add_i32 m0, s69, 0x2000
	s_add_u32 s70, s46, 0x200000
	s_addc_u32 s71, s47, 0
	s_add_i32 s69, s64, s1
	global_load_lds_dwordx4 v174, s[46:47]
	s_mov_b32 m0, s69
	s_nop 0
	global_load_lds_dwordx4 v170, s[70:71]
	s_add_i32 m0, s69, 0x2000
	s_nop 0
	global_load_lds_dwordx4 v174, s[70:71]
	s_mov_b32 m0, s33
	s_nop 0
	global_load_lds_dwordx4 v168, s[48:49]
	s_mov_b32 m0, s41
	s_nop 0
	global_load_lds_dwordx4 v172, s[48:49]
	s_waitcnt vmcnt(8)
	s_waitcnt lgkmcnt(0)
	s_barrier
	s_setprio 1
	s_waitcnt lgkmcnt(0)
	v_mfma_f32_16x16x32_bf16 v[60:63], v[128:131], v[160:163], v[60:63]
	v_mfma_f32_16x16x32_bf16 v[56:59], v[136:139], v[160:163], v[56:59]
	v_mfma_f32_16x16x32_bf16 v[44:47], v[128:131], v[184:187], v[44:47]
	v_mfma_f32_16x16x32_bf16 v[40:43], v[136:139], v[184:187], v[40:43]
	v_mfma_f32_16x16x32_bf16 v[28:31], v[128:131], v[192:195], v[28:31]
	v_mfma_f32_16x16x32_bf16 v[24:27], v[136:139], v[192:195], v[24:27]
	v_mfma_f32_16x16x32_bf16 v[12:15], v[128:131], v[210:213], v[12:15]
	v_mfma_f32_16x16x32_bf16 v[8:11], v[136:139], v[210:213], v[8:11]
	v_mfma_f32_16x16x32_bf16 v[60:63], v[132:135], v[164:167], v[60:63]
	v_mfma_f32_16x16x32_bf16 v[56:59], v[140:143], v[164:167], v[56:59]
	v_mfma_f32_16x16x32_bf16 v[44:47], v[132:135], v[188:191], v[44:47]
	v_mfma_f32_16x16x32_bf16 v[40:43], v[140:143], v[188:191], v[40:43]
	v_mfma_f32_16x16x32_bf16 v[28:31], v[132:135], v[206:209], v[28:31]
	v_mfma_f32_16x16x32_bf16 v[24:27], v[140:143], v[206:209], v[24:27]
	v_mfma_f32_16x16x32_bf16 v[12:15], v[132:135], v[214:217], v[12:15]
	v_mfma_f32_16x16x32_bf16 v[8:11], v[140:143], v[214:217], v[8:11]
	s_setprio 0
	s_setprio 1
	v_mfma_f32_16x16x32_bf16 v[52:55], v[144:147], v[160:163], v[52:55]
	v_mfma_f32_16x16x32_bf16 v[48:51], v[152:155], v[160:163], v[48:51]
	v_mfma_f32_16x16x32_bf16 v[36:39], v[144:147], v[184:187], v[36:39]
	v_mfma_f32_16x16x32_bf16 v[32:35], v[152:155], v[184:187], v[32:35]
	v_mfma_f32_16x16x32_bf16 v[20:23], v[144:147], v[192:195], v[20:23]
	v_mfma_f32_16x16x32_bf16 v[16:19], v[152:155], v[192:195], v[16:19]
	v_mfma_f32_16x16x32_bf16 v[4:7], v[144:147], v[210:213], v[4:7]
	v_mfma_f32_16x16x32_bf16 v[0:3], v[152:155], v[210:213], v[0:3]
	v_mfma_f32_16x16x32_bf16 v[52:55], v[148:151], v[164:167], v[52:55]
	v_mfma_f32_16x16x32_bf16 v[48:51], v[156:159], v[164:167], v[48:51]
	v_mfma_f32_16x16x32_bf16 v[36:39], v[148:151], v[188:191], v[36:39]
	v_mfma_f32_16x16x32_bf16 v[32:35], v[156:159], v[188:191], v[32:35]
	v_mfma_f32_16x16x32_bf16 v[20:23], v[148:151], v[206:209], v[20:23]
	v_mfma_f32_16x16x32_bf16 v[16:19], v[156:159], v[206:209], v[16:19]
	v_mfma_f32_16x16x32_bf16 v[4:7], v[148:151], v[214:217], v[4:7]
	v_mfma_f32_16x16x32_bf16 v[0:3], v[156:159], v[214:217], v[0:3]
	s_setprio 0
	s_barrier
; #define PG8_STAGE(bufoff, gbase, voff) do { _Pragma("unroll") for (int _i = 0; _i < 2; ++_i) \
;         __builtin_amdgcn_global_load_lds((const unsigned*)((const char*)(gbase) + (voff)[_i]), (PG8_LAS unsigned*)(lds + (bufoff) + ldsw + _i * 8192), 16, 0, 0); } while (0)
; #define PG8_LDA(dst, b, h) do { _Pragma("unroll") for (int m = 0; m < 4; ++m) _Pragma("unroll") for (int k = 0; k < 2; ++k) dst[m][k] = *(const PG8_LAS bf16x8*)(lds + PG8_SA(b, h) + aoff + m * 2048 + k * 1024); } while (0)
; #define PG8_LDB(dst, b, h) do { _Pragma("unroll") for (int n = 0; n < 2; ++n) _Pragma("unroll") for (int k = 0; k < 2; ++k) dst[n][k] = *(const PG8_LAS bf16x8*)(lds + PG8_SB(b, h) + boff + n * 2048 + k * 1024); } while (0)
; #define PG8_MMA(ai, bj, At, Bt) do { __builtin_amdgcn_s_setprio(1); _Pragma("unroll") for (int m = 0; m < 4; ++m) _Pragma("unroll") for (int n = 0; n < 2; ++n) _Pragma("unroll") for (int k = 0; k < 2; ++k) \
;         acc[ai][bj][m][n] = __builtin_amdgcn_mfma_f32_16x16x32_bf16(Bt[n][k], At[m][k], acc[ai][bj][m][n], 0, 0, 0); __builtin_amdgcn_s_setprio(0); } while (0)
; #define PG8_WAIT_V(n) asm volatile("s_waitcnt vmcnt(" #n ")" ::: "memory")
; #define PG8_WAIT_L(n) asm volatile("s_waitcnt lgkmcnt(" #n ")" ::: "memory")
; #define PG8_BAR __builtin_amdgcn_s_barrier()
; #define PG8_SCHED __builtin_amdgcn_sched_barrier(0)
; template <class Epi, class Sched, bool ALIGN_EPI = false, bool SP2 = false>
; __device__ __forceinline__ void gemm_phase(PG8_LAS unsigned char* lds, const Gemm g, const Sched& S, const Epi& E) {
;     ...
;         for (int t = 0; t < nt; t += 2) {
;             const bool last = (t == nt - 2);
;             const char* a1 = cA + (size_t)(t + 1) * kstep;
;             const char* a2 = last ? nA : cA + (size_t)(t + 2) * kstep; const char* b2 = last ? nB : cB + (size_t)(t + 2) * kstep;
;     ...
;             PG8_LDB(B0, 1, 0); PG8_LDB(B1, 1, 1); PG8_SCHED; PG8_LDA(At, 1, 0); PG8_STAGE(PG8_SA(0, 1), a2 + hstep, voffA);
;             PG8_WAIT_V(8); PG8_WAIT_L(0); PG8_BAR; PG8_MMA(0, 0, At, B0); PG8_MMA(0, 1, At, B1); PG8_BAR; PG8_SCHED;
;             PG8_LDA(At, 1, 1); PG8_STAGE(PG8_SB(1, 0), b3, voffB); PG8_STAGE(PG8_SB(1, 1), b3 + hstep, voffB); PG8_STAGE(PG8_SA(1, 0), a3, voffA);
;             PG8_WAIT_V(8); PG8_WAIT_L(0); PG8_BAR; PG8_MMA(1, 0, At, B0); PG8_MMA(1, 1, At, B1); PG8_BAR; PG8_SCHED;
	ds_read_b128 v[128:131], v218
	ds_read_b128 v[132:135], v218 offset:1024
	ds_read_b128 v[136:139], v218 offset:2048
	ds_read_b128 v[140:143], v218 offset:3072
	ds_read_b128 v[144:147], v219
	ds_read_b128 v[148:151], v219 offset:1024
	ds_read_b128 v[152:155], v219 offset:2048
	ds_read_b128 v[156:159], v219 offset:3072
	ds_read_b128 v[160:163], v204 offset:32768
	ds_read_b128 v[164:167], v204 offset:33792
	ds_read_b128 v[184:187], v204 offset:34816
	ds_read_b128 v[188:191], v204 offset:35840
	ds_read_b128 v[192:195], v204 offset:36864
	ds_read_b128 v[206:209], v204 offset:37888
	ds_read_b128 v[210:213], v204 offset:38912
	ds_read_b128 v[214:217], v204 offset:39936
	s_add_u32 s98, s48, 0x200000
	s_addc_u32 s99, s49, 0
	s_mov_b32 m0, s50
	s_add_u32 s100, s48, 0x80
	s_addc_u32 s101, s49, 0
	global_load_lds_dwordx4 v168, s[98:99]
	s_mov_b32 m0, s51
	s_nop 0
	global_load_lds_dwordx4 v172, s[98:99]
	s_add_i32 s69, 0, 0x18000
	s_add_i32 s70, 0, 0x1c000
	s_add_u32 s98, s46, 0x80
	s_addc_u32 s99, s47, 0
	s_add_i32 s48, s69, s1
	s_mov_b32 m0, s48
	s_waitcnt vmcnt(8)
	s_waitcnt lgkmcnt(0)
	s_barrier
	s_setprio 1
	s_waitcnt lgkmcnt(0)
	v_mfma_f32_16x16x32_bf16 v[124:127], v[128:131], v[160:163], v[124:127]
	v_mfma_f32_16x16x32_bf16 v[120:123], v[136:139], v[160:163], v[120:123]
	v_mfma_f32_16x16x32_bf16 v[116:119], v[128:131], v[184:187], v[116:119]
	v_mfma_f32_16x16x32_bf16 v[108:111], v[136:139], v[184:187], v[108:111]
	v_mfma_f32_16x16x32_bf16 v[92:95], v[128:131], v[192:195], v[92:95]
	v_mfma_f32_16x16x32_bf16 v[88:91], v[136:139], v[192:195], v[88:91]
	v_mfma_f32_16x16x32_bf16 v[76:79], v[128:131], v[210:213], v[76:79]
	v_mfma_f32_16x16x32_bf16 v[72:75], v[136:139], v[210:213], v[72:75]
	v_mfma_f32_16x16x32_bf16 v[124:127], v[132:135], v[164:167], v[124:127]
	v_mfma_f32_16x16x32_bf16 v[120:123], v[140:143], v[164:167], v[120:123]
	v_mfma_f32_16x16x32_bf16 v[116:119], v[132:135], v[188:191], v[116:119]
	v_mfma_f32_16x16x32_bf16 v[108:111], v[140:143], v[188:191], v[108:111]
	v_mfma_f32_16x16x32_bf16 v[92:95], v[132:135], v[206:209], v[92:95]
	v_mfma_f32_16x16x32_bf16 v[88:91], v[140:143], v[206:209], v[88:91]
	v_mfma_f32_16x16x32_bf16 v[76:79], v[132:135], v[214:217], v[76:79]
	v_mfma_f32_16x16x32_bf16 v[72:75], v[140:143], v[214:217], v[72:75]
	s_setprio 0
	s_setprio 1
	v_mfma_f32_16x16x32_bf16 v[112:115], v[144:147], v[160:163], v[112:115]
	v_mfma_f32_16x16x32_bf16 v[104:107], v[152:155], v[160:163], v[104:107]
	v_mfma_f32_16x16x32_bf16 v[100:103], v[144:147], v[184:187], v[100:103]
	v_mfma_f32_16x16x32_bf16 v[96:99], v[152:155], v[184:187], v[96:99]
	v_mfma_f32_16x16x32_bf16 v[84:87], v[144:147], v[192:195], v[84:87]
	v_mfma_f32_16x16x32_bf16 v[80:83], v[152:155], v[192:195], v[80:83]
	v_mfma_f32_16x16x32_bf16 v[68:71], v[144:147], v[210:213], v[68:71]
	v_mfma_f32_16x16x32_bf16 v[64:67], v[152:155], v[210:213], v[64:67]
	v_mfma_f32_16x16x32_bf16 v[112:115], v[148:151], v[164:167], v[112:115]
	v_mfma_f32_16x16x32_bf16 v[104:107], v[156:159], v[164:167], v[104:107]
	v_mfma_f32_16x16x32_bf16 v[100:103], v[148:151], v[188:191], v[100:103]
	v_mfma_f32_16x16x32_bf16 v[96:99], v[156:159], v[188:191], v[96:99]
	v_mfma_f32_16x16x32_bf16 v[84:87], v[148:151], v[206:209], v[84:87]
	v_mfma_f32_16x16x32_bf16 v[80:83], v[156:159], v[206:209], v[80:83]
	v_mfma_f32_16x16x32_bf16 v[68:71], v[148:151], v[214:217], v[68:71]
	v_mfma_f32_16x16x32_bf16 v[64:67], v[156:159], v[214:217], v[64:67]
	s_setprio 0
	s_barrier
	ds_read_b128 v[160:163], v204 offset:49152
	ds_read_b128 v[164:167], v204 offset:50176
	ds_read_b128 v[184:187], v204 offset:51200
	ds_read_b128 v[188:191], v204 offset:52224
	ds_read_b128 v[192:195], v204 offset:53248
	ds_read_b128 v[206:209], v204 offset:54272
	ds_read_b128 v[210:213], v204 offset:55296
	ds_read_b128 v[214:217], v204 offset:56320
	global_load_lds_dwordx4 v170, s[98:99]
	s_add_i32 m0, s48, 0x2000
	s_add_u32 s46, s46, 0x200080
	s_addc_u32 s47, s47, 0
	s_add_i32 s48, s70, s1
	global_load_lds_dwordx4 v174, s[98:99]
	s_mov_b32 m0, s48
	s_nop 0
	global_load_lds_dwordx4 v170, s[46:47]
	s_add_i32 m0, s48, 0x2000
	s_nop 0
	global_load_lds_dwordx4 v174, s[46:47]
	s_mov_b32 m0, s59
	s_nop 0
	global_load_lds_dwordx4 v168, s[100:101]
	s_mov_b32 m0, s60
	s_nop 0
	global_load_lds_dwordx4 v172, s[100:101]
	s_add_i32 s68, s68, 2
	s_add_u32 s42, s42, 0x100
	s_addc_u32 s43, s43, 0
	s_add_u32 s66, s66, 0x100
	s_addc_u32 s67, s67, 0
	s_cmpk_gt_u32 s68, 0x7d
	s_waitcnt vmcnt(8)
	s_waitcnt lgkmcnt(0)
	s_barrier
	s_setprio 1
	s_waitcnt lgkmcnt(0)
	v_mfma_f32_16x16x32_bf16 v[60:63], v[128:131], v[160:163], v[60:63]
	v_mfma_f32_16x16x32_bf16 v[56:59], v[136:139], v[160:163], v[56:59]
	v_mfma_f32_16x16x32_bf16 v[44:47], v[128:131], v[184:187], v[44:47]
	v_mfma_f32_16x16x32_bf16 v[40:43], v[136:139], v[184:187], v[40:43]
	v_mfma_f32_16x16x32_bf16 v[28:31], v[128:131], v[192:195], v[28:31]
	v_mfma_f32_16x16x32_bf16 v[24:27], v[136:139], v[192:195], v[24:27]
	v_mfma_f32_16x16x32_bf16 v[12:15], v[128:131], v[210:213], v[12:15]
	v_mfma_f32_16x16x32_bf16 v[8:11], v[136:139], v[210:213], v[8:11]
	v_mfma_f32_16x16x32_bf16 v[60:63], v[132:135], v[164:167], v[60:63]
	v_mfma_f32_16x16x32_bf16 v[56:59], v[140:143], v[164:167], v[56:59]
	v_mfma_f32_16x16x32_bf16 v[44:47], v[132:135], v[188:191], v[44:47]
	v_mfma_f32_16x16x32_bf16 v[40:43], v[140:143], v[188:191], v[40:43]
	v_mfma_f32_16x16x32_bf16 v[28:31], v[132:135], v[206:209], v[28:31]
	v_mfma_f32_16x16x32_bf16 v[24:27], v[140:143], v[206:209], v[24:27]
	v_mfma_f32_16x16x32_bf16 v[12:15], v[132:135], v[214:217], v[12:15]
	v_mfma_f32_16x16x32_bf16 v[8:11], v[140:143], v[214:217], v[8:11]
	s_setprio 0
	s_setprio 1
	v_mfma_f32_16x16x32_bf16 v[52:55], v[144:147], v[160:163], v[52:55]
	v_mfma_f32_16x16x32_bf16 v[48:51], v[152:155], v[160:163], v[48:51]
	v_mfma_f32_16x16x32_bf16 v[36:39], v[144:147], v[184:187], v[36:39]
	v_mfma_f32_16x16x32_bf16 v[32:35], v[152:155], v[184:187], v[32:35]
	v_mfma_f32_16x16x32_bf16 v[20:23], v[144:147], v[192:195], v[20:23]
	v_mfma_f32_16x16x32_bf16 v[16:19], v[152:155], v[192:195], v[16:19]
	v_mfma_f32_16x16x32_bf16 v[4:7], v[144:147], v[210:213], v[4:7]
	v_mfma_f32_16x16x32_bf16 v[0:3], v[152:155], v[210:213], v[0:3]
	v_mfma_f32_16x16x32_bf16 v[52:55], v[148:151], v[164:167], v[52:55]
	v_mfma_f32_16x16x32_bf16 v[48:51], v[156:159], v[164:167], v[48:51]
	v_mfma_f32_16x16x32_bf16 v[36:39], v[148:151], v[188:191], v[36:39]
	v_mfma_f32_16x16x32_bf16 v[32:35], v[156:159], v[188:191], v[32:35]
	v_mfma_f32_16x16x32_bf16 v[20:23], v[148:151], v[206:209], v[20:23]
	v_mfma_f32_16x16x32_bf16 v[16:19], v[156:159], v[206:209], v[16:19]
	v_mfma_f32_16x16x32_bf16 v[4:7], v[148:151], v[214:217], v[4:7]
	v_mfma_f32_16x16x32_bf16 v[0:3], v[156:159], v[214:217], v[0:3]
	s_setprio 0
	s_barrier
	s_cbranch_scc0 .LBB0_1412
	s_and_b64 vcc, exec, s[10:11]
	s_cbranch_vccz .LBB0_1415
	s_barrier
